# prep1 decay loop: dead per-step kdT address computation removed on the 56 steps that no longer store (168 VALU per thread)
# speedup vs baseline: 1.0099x; 1.0020x over previous
.Lp1e_skip:
	global_load_dword v4, v6, s[8:9]
	global_load_dword v5, v6, s[8:9] offset:2048
	s_nop 0
	global_load_dword v6, v[154:155], off offset:-4096
	global_load_dword v7, v[146:147], off offset:2048
	global_load_dword v228, v[154:155], off
	s_nop 0
	global_load_dword v154, v[154:155], off offset:2048
	v_add_co_u32_e32 v146, vcc, s0, v158
	s_movk_i32 s0, 0x5000
	s_nop 0
	v_addc_co_u32_e32 v147, vcc, 0, v159, vcc
	v_add_co_u32_e32 v160, vcc, s17, v158
	s_nop 1
	v_addc_co_u32_e32 v161, vcc, 0, v159, vcc
	global_load_dword v155, v[160:161], off offset:-4096
	global_load_dword v156, v[146:147], off offset:2048
	s_nop 0
	global_load_dword v146, v[160:161], off
	global_load_dword v252, v[160:161], off offset:2048
	v_add_co_u32_e32 v160, vcc, s0, v158
	s_movk_i32 s0, 0x7000
	s_nop 0
	v_addc_co_u32_e32 v161, vcc, 0, v159, vcc
	v_add_co_u32_e32 v174, vcc, s62, v158
	s_nop 1
	v_addc_co_u32_e32 v175, vcc, 0, v159, vcc
	v_add_co_u32_e32 v158, vcc, s0, v158
	global_load_dword v253, v[174:175], off offset:-4096
	global_load_dword v227, v[160:161], off offset:2048
	global_load_dword v145, v[174:175], off
	global_load_dword v147, v[174:175], off offset:2048
	v_addc_co_u32_e32 v159, vcc, 0, v159, vcc
	global_load_dword v230, v[158:159], off
	global_load_dword v231, v[158:159], off offset:2048
	global_load_dword v157, v141, s[10:11]
	ds_read_b128 v[174:177], v9
	ds_read_b128 v[178:181], v9 offset:16
	ds_read_b128 v[182:185], v9 offset:32
	ds_read_b128 v[186:189], v9 offset:48
	ds_read_b128 v[212:215], v9 offset:4480
	ds_read_b128 v[234:237], v9 offset:4992
	s_waitcnt vmcnt(15) lgkmcnt(5)
	v_mul_f32_e32 v141, v5, v175
	v_fmac_f32_e32 v141, v4, v174
	s_waitcnt vmcnt(11) lgkmcnt(4)
	v_mul_f32_e32 v158, v154, v179
	v_fmac_f32_e32 v141, v6, v176
	v_fmac_f32_e32 v158, v228, v178
	v_fmac_f32_e32 v141, v7, v177
	ds_read_b128 v[174:177], v9 offset:128
	s_waitcnt vmcnt(10)
	v_fmac_f32_e32 v158, v155, v180
	s_waitcnt vmcnt(9)
	v_fmac_f32_e32 v158, v156, v181
	s_waitcnt vmcnt(0)
	v_add_f32_e32 v141, v157, v141
	v_add_f32_e32 v141, v141, v158
	s_waitcnt lgkmcnt(4)
	v_mul_f32_e32 v158, v252, v183
	v_fmac_f32_e32 v158, v146, v182
	v_fmac_f32_e32 v158, v253, v184
	v_fmac_f32_e32 v158, v227, v185
	v_add_f32_e32 v141, v141, v158
	s_waitcnt lgkmcnt(3)
	v_mul_f32_e32 v158, v147, v187
	v_fmac_f32_e32 v158, v145, v186
	v_fmac_f32_e32 v158, v230, v188
	v_fmac_f32_e32 v158, v231, v189
	v_add_f32_e32 v141, v141, v158
	v_min_f32_e32 v158, 0, v141
	v_mul_f32_e64 v141, |v141|, s18
	v_exp_f32_e32 v141, v141
	s_nop 0
	v_add_f32_e32 v141, 1.0, v141
	v_cmp_gt_f32_e32 vcc, s71, v141
	s_nop 1
	v_cndmask_b32_e64 v159, 0, 32, vcc
	v_ldexp_f32 v141, v141, v159
	v_log_f32_e32 v141, v141
	s_nop 0
	v_mul_f32_e32 v159, 0x3f317217, v141
	v_fma_f32 v159, v141, s48, -v159
	v_fmac_f32_e32 v159, 0x3377d1cf, v141
	v_fmac_f32_e32 v159, 0x3f317217, v141
	v_cmp_lt_f32_e64 s[0:1], |v141|, s49
	s_nop 1
	v_cndmask_b32_e64 v141, v141, v159, s[0:1]
	v_cndmask_b32_e32 v159, 0, v233, vcc
	v_sub_f32_e32 v141, v141, v159
	v_sub_f32_e32 v141, v158, v141
	s_waitcnt lgkmcnt(0)
	v_mul_f32_e32 v158, v5, v175
	v_fmac_f32_e32 v158, v4, v174
	v_fmac_f32_e32 v158, v6, v176
	v_fmac_f32_e32 v158, v7, v177
	ds_read_b128 v[174:177], v9 offset:144
	v_add_f32_e32 v158, v157, v158
	s_mov_b32 s0, 0x3d800000
	v_mul_f32_e32 v173, 0x3d800000, v141
	v_fma_f32 v141, v141, s0, 0
	s_waitcnt lgkmcnt(0)
	v_mul_f32_e32 v159, v154, v175
	v_fmac_f32_e32 v159, v228, v174
	v_fmac_f32_e32 v159, v155, v176
	v_fmac_f32_e32 v159, v156, v177
	ds_read_b128 v[174:177], v9 offset:160
	v_add_f32_e32 v158, v158, v159
	s_waitcnt lgkmcnt(0)
	v_mul_f32_e32 v159, v252, v175
	v_fmac_f32_e32 v159, v146, v174
	v_fmac_f32_e32 v159, v253, v176
	v_fmac_f32_e32 v159, v227, v177
	ds_read_b128 v[174:177], v9 offset:176
	v_add_f32_e32 v158, v158, v159
	s_waitcnt lgkmcnt(0)
	v_mul_f32_e32 v159, v147, v175
	v_fmac_f32_e32 v159, v145, v174
	v_fmac_f32_e32 v159, v230, v176
	v_fmac_f32_e32 v159, v231, v177
	v_add_f32_e32 v158, v158, v159
	v_min_f32_e32 v159, 0, v158
	v_mul_f32_e64 v158, |v158|, s18
	v_exp_f32_e32 v158, v158
	ds_read_b128 v[176:179], v9 offset:256
	v_add_f32_e32 v158, 1.0, v158
	v_cmp_gt_f32_e32 vcc, s71, v158
	s_nop 1
	v_cndmask_b32_e64 v160, 0, 32, vcc
	v_ldexp_f32 v158, v158, v160
	v_log_f32_e32 v158, v158
	s_nop 0
	v_mul_f32_e32 v160, 0x3f317217, v158
	v_fma_f32 v160, v158, s48, -v160
	v_fmac_f32_e32 v160, 0x3377d1cf, v158
	v_fmac_f32_e32 v160, 0x3f317217, v158
	v_cmp_lt_f32_e64 s[0:1], |v158|, s49
	s_nop 1
	v_cndmask_b32_e64 v158, v158, v160, s[0:1]
	v_cndmask_b32_e32 v160, 0, v233, vcc
	v_sub_f32_e32 v158, v158, v160
	v_sub_f32_e32 v158, v159, v158
	v_mul_f32_e32 v174, 0x3d800000, v158
	v_fmac_f32_e32 v141, 0x3d800000, v158
	s_waitcnt lgkmcnt(0)
	v_mul_f32_e32 v158, v5, v177
	v_fmac_f32_e32 v158, v4, v176
	v_fmac_f32_e32 v158, v6, v178
	v_fmac_f32_e32 v158, v7, v179
	ds_read_b128 v[176:179], v9 offset:272
	v_add_f32_e32 v158, v157, v158
	s_waitcnt lgkmcnt(0)
	v_mul_f32_e32 v159, v154, v177
	v_fmac_f32_e32 v159, v228, v176
	v_fmac_f32_e32 v159, v155, v178
	v_fmac_f32_e32 v159, v156, v179
	ds_read_b128 v[176:179], v9 offset:288
	v_add_f32_e32 v158, v158, v159
	s_waitcnt lgkmcnt(0)
	v_mul_f32_e32 v159, v252, v177
	v_fmac_f32_e32 v159, v146, v176
	v_fmac_f32_e32 v159, v253, v178
	v_fmac_f32_e32 v159, v227, v179
	ds_read_b128 v[176:179], v9 offset:304
	v_add_f32_e32 v158, v158, v159
	s_waitcnt lgkmcnt(0)
	v_mul_f32_e32 v159, v147, v177
	v_fmac_f32_e32 v159, v145, v176
	v_fmac_f32_e32 v159, v230, v178
	v_fmac_f32_e32 v159, v231, v179
	v_add_f32_e32 v158, v158, v159
	v_min_f32_e32 v159, 0, v158
	v_mul_f32_e64 v158, |v158|, s18
	v_exp_f32_e32 v158, v158
	ds_read_b128 v[176:179], v9 offset:384
	v_add_f32_e32 v158, 1.0, v158
	v_cmp_gt_f32_e32 vcc, s71, v158
	s_nop 1
	v_cndmask_b32_e64 v160, 0, 32, vcc
	v_ldexp_f32 v158, v158, v160
	v_log_f32_e32 v158, v158
	s_nop 0
	v_mul_f32_e32 v160, 0x3f317217, v158
	v_fma_f32 v160, v158, s48, -v160
	v_fmac_f32_e32 v160, 0x3377d1cf, v158
	v_fmac_f32_e32 v160, 0x3f317217, v158
	v_cmp_lt_f32_e64 s[0:1], |v158|, s49
	s_nop 1
	v_cndmask_b32_e64 v158, v158, v160, s[0:1]
	v_cndmask_b32_e32 v160, 0, v233, vcc
	v_sub_f32_e32 v158, v158, v160
	v_sub_f32_e32 v158, v159, v158
	v_mul_f32_e32 v175, 0x3d800000, v158
	v_fmac_f32_e32 v141, 0x3d800000, v158
	s_waitcnt lgkmcnt(0)
	v_mul_f32_e32 v158, v5, v177
	v_fmac_f32_e32 v158, v4, v176
	v_fmac_f32_e32 v158, v6, v178
	v_fmac_f32_e32 v158, v7, v179
	ds_read_b128 v[176:179], v9 offset:400
	v_add_f32_e32 v158, v157, v158
	s_waitcnt lgkmcnt(0)
	v_mul_f32_e32 v159, v154, v177
	v_fmac_f32_e32 v159, v228, v176
	v_fmac_f32_e32 v159, v155, v178
	v_fmac_f32_e32 v159, v156, v179
	ds_read_b128 v[176:179], v9 offset:416
	v_add_f32_e32 v158, v158, v159
	s_waitcnt lgkmcnt(0)
	v_mul_f32_e32 v159, v252, v177
	v_fmac_f32_e32 v159, v146, v176
	v_fmac_f32_e32 v159, v253, v178
	v_fmac_f32_e32 v159, v227, v179
	ds_read_b128 v[176:179], v9 offset:432
	v_add_f32_e32 v158, v158, v159
	s_waitcnt lgkmcnt(0)
	v_mul_f32_e32 v159, v147, v177
	v_fmac_f32_e32 v159, v145, v176
	v_fmac_f32_e32 v159, v230, v178
	v_fmac_f32_e32 v159, v231, v179
	v_add_f32_e32 v158, v158, v159
	v_min_f32_e32 v159, 0, v158
	v_mul_f32_e64 v158, |v158|, s18
	v_exp_f32_e32 v158, v158
	ds_read_b128 v[178:181], v9 offset:512
	v_add_f32_e32 v158, 1.0, v158
	v_cmp_gt_f32_e32 vcc, s71, v158
	s_nop 1
	v_cndmask_b32_e64 v160, 0, 32, vcc
	v_ldexp_f32 v158, v158, v160
	v_log_f32_e32 v158, v158
	s_nop 0
	v_mul_f32_e32 v160, 0x3f317217, v158
	v_fma_f32 v160, v158, s48, -v160
	v_fmac_f32_e32 v160, 0x3377d1cf, v158
	v_fmac_f32_e32 v160, 0x3f317217, v158
	v_cmp_lt_f32_e64 s[0:1], |v158|, s49
	s_nop 1
	v_cndmask_b32_e64 v158, v158, v160, s[0:1]
	v_cndmask_b32_e32 v160, 0, v233, vcc
	v_sub_f32_e32 v158, v158, v160
	v_sub_f32_e32 v158, v159, v158
	v_mul_f32_e32 v176, 0x3d800000, v158
	v_fmac_f32_e32 v141, 0x3d800000, v158
	s_waitcnt lgkmcnt(0)
	v_mul_f32_e32 v158, v5, v179
	v_fmac_f32_e32 v158, v4, v178
	v_fmac_f32_e32 v158, v6, v180
	v_fmac_f32_e32 v158, v7, v181
	ds_read_b128 v[178:181], v9 offset:528
	v_add_f32_e32 v158, v157, v158
	s_waitcnt lgkmcnt(0)
	v_mul_f32_e32 v159, v154, v179
	v_fmac_f32_e32 v159, v228, v178
	v_fmac_f32_e32 v159, v155, v180
	v_fmac_f32_e32 v159, v156, v181
	ds_read_b128 v[178:181], v9 offset:544
	v_add_f32_e32 v158, v158, v159
	s_waitcnt lgkmcnt(0)
	v_mul_f32_e32 v159, v252, v179
	v_fmac_f32_e32 v159, v146, v178
	v_fmac_f32_e32 v159, v253, v180
	v_fmac_f32_e32 v159, v227, v181
	ds_read_b128 v[178:181], v9 offset:560
	v_add_f32_e32 v158, v158, v159
	s_waitcnt lgkmcnt(0)
	v_mul_f32_e32 v159, v147, v179
	v_fmac_f32_e32 v159, v145, v178
	v_fmac_f32_e32 v159, v230, v180
	v_fmac_f32_e32 v159, v231, v181
	v_add_f32_e32 v158, v158, v159
	v_min_f32_e32 v159, 0, v158
	v_mul_f32_e64 v158, |v158|, s18
	v_exp_f32_e32 v158, v158
	ds_read_b128 v[178:181], v9 offset:640
	v_add_f32_e32 v158, 1.0, v158
	v_cmp_gt_f32_e32 vcc, s71, v158
	s_nop 1
	v_cndmask_b32_e64 v160, 0, 32, vcc
	v_ldexp_f32 v158, v158, v160
	v_log_f32_e32 v158, v158
	s_nop 0
	v_mul_f32_e32 v160, 0x3f317217, v158
	v_fma_f32 v160, v158, s48, -v160
	v_fmac_f32_e32 v160, 0x3377d1cf, v158
	v_fmac_f32_e32 v160, 0x3f317217, v158
	v_cmp_lt_f32_e64 s[0:1], |v158|, s49
	s_nop 1
	v_cndmask_b32_e64 v158, v158, v160, s[0:1]
	v_cndmask_b32_e32 v160, 0, v233, vcc
	v_sub_f32_e32 v158, v158, v160
	v_sub_f32_e32 v158, v159, v158
	v_mul_f32_e32 v177, 0x3d800000, v158
	v_fmac_f32_e32 v141, 0x3d800000, v158
	s_waitcnt lgkmcnt(0)
	v_mul_f32_e32 v158, v5, v179
	v_fmac_f32_e32 v158, v4, v178
	v_fmac_f32_e32 v158, v6, v180
	v_fmac_f32_e32 v158, v7, v181
	ds_read_b128 v[178:181], v9 offset:656
	v_add_f32_e32 v158, v157, v158
	s_waitcnt lgkmcnt(0)
	v_mul_f32_e32 v159, v154, v179
	v_fmac_f32_e32 v159, v228, v178
	v_fmac_f32_e32 v159, v155, v180
	v_fmac_f32_e32 v159, v156, v181
	ds_read_b128 v[178:181], v9 offset:672
	v_add_f32_e32 v158, v158, v159
	s_waitcnt lgkmcnt(0)
	v_mul_f32_e32 v159, v252, v179
	v_fmac_f32_e32 v159, v146, v178
	v_fmac_f32_e32 v159, v253, v180
	v_fmac_f32_e32 v159, v227, v181
	ds_read_b128 v[178:181], v9 offset:688
	v_add_f32_e32 v158, v158, v159
	s_waitcnt lgkmcnt(0)
	v_mul_f32_e32 v159, v147, v179
	v_fmac_f32_e32 v159, v145, v178
	v_fmac_f32_e32 v159, v230, v180
	v_fmac_f32_e32 v159, v231, v181
	v_add_f32_e32 v158, v158, v159
	v_min_f32_e32 v159, 0, v158
	v_mul_f32_e64 v158, |v158|, s18
	v_exp_f32_e32 v158, v158
	ds_read_b128 v[180:183], v9 offset:768
	v_add_f32_e32 v158, 1.0, v158
	v_cmp_gt_f32_e32 vcc, s71, v158
	s_nop 1
	v_cndmask_b32_e64 v160, 0, 32, vcc
	v_ldexp_f32 v158, v158, v160
	v_log_f32_e32 v158, v158
	s_nop 0
	v_mul_f32_e32 v160, 0x3f317217, v158
	v_fma_f32 v160, v158, s48, -v160
	v_fmac_f32_e32 v160, 0x3377d1cf, v158
	v_fmac_f32_e32 v160, 0x3f317217, v158
	v_cmp_lt_f32_e64 s[0:1], |v158|, s49
	s_nop 1
	v_cndmask_b32_e64 v158, v158, v160, s[0:1]
	v_cndmask_b32_e32 v160, 0, v233, vcc
	v_sub_f32_e32 v158, v158, v160
	v_sub_f32_e32 v158, v159, v158
	v_mul_f32_e32 v178, 0x3d800000, v158
	v_fmac_f32_e32 v141, 0x3d800000, v158
	s_waitcnt lgkmcnt(0)
	v_mul_f32_e32 v158, v5, v181
	v_fmac_f32_e32 v158, v4, v180
	v_fmac_f32_e32 v158, v6, v182
	v_fmac_f32_e32 v158, v7, v183
	ds_read_b128 v[180:183], v9 offset:784
	v_add_f32_e32 v158, v157, v158
	s_waitcnt lgkmcnt(0)
	v_mul_f32_e32 v159, v154, v181
	v_fmac_f32_e32 v159, v228, v180
	v_fmac_f32_e32 v159, v155, v182
	v_fmac_f32_e32 v159, v156, v183
	ds_read_b128 v[180:183], v9 offset:800
	v_add_f32_e32 v158, v158, v159
	s_waitcnt lgkmcnt(0)
	v_mul_f32_e32 v159, v252, v181
	v_fmac_f32_e32 v159, v146, v180
	v_fmac_f32_e32 v159, v253, v182
	v_fmac_f32_e32 v159, v227, v183
	ds_read_b128 v[180:183], v9 offset:816
	v_add_f32_e32 v158, v158, v159
	s_waitcnt lgkmcnt(0)
	v_mul_f32_e32 v159, v147, v181
	v_fmac_f32_e32 v159, v145, v180
	v_fmac_f32_e32 v159, v230, v182
	v_fmac_f32_e32 v159, v231, v183
	v_add_f32_e32 v158, v158, v159
	v_min_f32_e32 v159, 0, v158
	v_mul_f32_e64 v158, |v158|, s18
	v_exp_f32_e32 v158, v158
	ds_read_b128 v[180:183], v9 offset:896
	v_add_f32_e32 v158, 1.0, v158
	v_cmp_gt_f32_e32 vcc, s71, v158
	s_nop 1
	v_cndmask_b32_e64 v160, 0, 32, vcc
	v_ldexp_f32 v158, v158, v160
	v_log_f32_e32 v158, v158
	s_nop 0
	v_mul_f32_e32 v160, 0x3f317217, v158
	v_fma_f32 v160, v158, s48, -v160
	v_fmac_f32_e32 v160, 0x3377d1cf, v158
	v_fmac_f32_e32 v160, 0x3f317217, v158
	v_cmp_lt_f32_e64 s[0:1], |v158|, s49
	s_nop 1
	v_cndmask_b32_e64 v158, v158, v160, s[0:1]
	v_cndmask_b32_e32 v160, 0, v233, vcc
	v_sub_f32_e32 v158, v158, v160
	v_sub_f32_e32 v158, v159, v158
	v_mul_f32_e32 v179, 0x3d800000, v158
	v_fmac_f32_e32 v141, 0x3d800000, v158
	s_waitcnt lgkmcnt(0)
	v_mul_f32_e32 v158, v5, v181
	v_fmac_f32_e32 v158, v4, v180
	v_fmac_f32_e32 v158, v6, v182
	v_fmac_f32_e32 v158, v7, v183
	ds_read_b128 v[180:183], v9 offset:912
	v_add_f32_e32 v158, v157, v158
	s_waitcnt lgkmcnt(0)
	v_mul_f32_e32 v159, v154, v181
	v_fmac_f32_e32 v159, v228, v180
	v_fmac_f32_e32 v159, v155, v182
	v_fmac_f32_e32 v159, v156, v183
	ds_read_b128 v[180:183], v9 offset:928
	v_add_f32_e32 v158, v158, v159
	s_waitcnt lgkmcnt(0)
	v_mul_f32_e32 v159, v252, v181
	v_fmac_f32_e32 v159, v146, v180
	v_fmac_f32_e32 v159, v253, v182
	v_fmac_f32_e32 v159, v227, v183
	ds_read_b128 v[180:183], v9 offset:944
	v_add_f32_e32 v158, v158, v159
	s_waitcnt lgkmcnt(0)
	v_mul_f32_e32 v159, v147, v181
	v_fmac_f32_e32 v159, v145, v180
	v_fmac_f32_e32 v159, v230, v182
	v_fmac_f32_e32 v159, v231, v183
	v_add_f32_e32 v158, v158, v159
	v_min_f32_e32 v159, 0, v158
	v_mul_f32_e64 v158, |v158|, s18
	v_exp_f32_e32 v158, v158
	ds_read_b128 v[182:185], v9 offset:1024
	v_add_f32_e32 v158, 1.0, v158
	v_cmp_gt_f32_e32 vcc, s71, v158
	s_nop 1
	v_cndmask_b32_e64 v160, 0, 32, vcc
	v_ldexp_f32 v158, v158, v160
	v_log_f32_e32 v158, v158
	s_nop 0
	v_mul_f32_e32 v160, 0x3f317217, v158
	v_fma_f32 v160, v158, s48, -v160
	v_fmac_f32_e32 v160, 0x3377d1cf, v158
	v_fmac_f32_e32 v160, 0x3f317217, v158
	v_cmp_lt_f32_e64 s[0:1], |v158|, s49
	s_nop 1
	v_cndmask_b32_e64 v158, v158, v160, s[0:1]
	v_cndmask_b32_e32 v160, 0, v233, vcc
	v_sub_f32_e32 v158, v158, v160
	v_sub_f32_e32 v158, v159, v158
	v_mul_f32_e32 v180, 0x3d800000, v158
	v_fmac_f32_e32 v141, 0x3d800000, v158
	s_waitcnt lgkmcnt(0)
	v_mul_f32_e32 v158, v5, v183
	v_fmac_f32_e32 v158, v4, v182
	v_fmac_f32_e32 v158, v6, v184
	v_fmac_f32_e32 v158, v7, v185
	ds_read_b128 v[182:185], v9 offset:1040
	v_add_f32_e32 v158, v157, v158
	s_waitcnt lgkmcnt(0)
	v_mul_f32_e32 v159, v154, v183
	v_fmac_f32_e32 v159, v228, v182
	v_fmac_f32_e32 v159, v155, v184
	v_fmac_f32_e32 v159, v156, v185
	ds_read_b128 v[182:185], v9 offset:1056
	v_add_f32_e32 v158, v158, v159
	s_waitcnt lgkmcnt(0)
	v_mul_f32_e32 v159, v252, v183
	v_fmac_f32_e32 v159, v146, v182
	v_fmac_f32_e32 v159, v253, v184
	v_fmac_f32_e32 v159, v227, v185
	ds_read_b128 v[182:185], v9 offset:1072
	v_add_f32_e32 v158, v158, v159
	s_waitcnt lgkmcnt(0)
	v_mul_f32_e32 v159, v147, v183
	v_fmac_f32_e32 v159, v145, v182
	v_fmac_f32_e32 v159, v230, v184
	v_fmac_f32_e32 v159, v231, v185
	v_add_f32_e32 v158, v158, v159
	v_min_f32_e32 v159, 0, v158
	v_mul_f32_e64 v158, |v158|, s18
	v_exp_f32_e32 v158, v158
	ds_read_b128 v[182:185], v9 offset:1152
	v_add_f32_e32 v158, 1.0, v158
	v_cmp_gt_f32_e32 vcc, s71, v158
	s_nop 1
	v_cndmask_b32_e64 v160, 0, 32, vcc
	v_ldexp_f32 v158, v158, v160
	v_log_f32_e32 v158, v158
	s_nop 0
	v_mul_f32_e32 v160, 0x3f317217, v158
	v_fma_f32 v160, v158, s48, -v160
	v_fmac_f32_e32 v160, 0x3377d1cf, v158
	v_fmac_f32_e32 v160, 0x3f317217, v158
	v_cmp_lt_f32_e64 s[0:1], |v158|, s49
	s_nop 1
	v_cndmask_b32_e64 v158, v158, v160, s[0:1]
	v_cndmask_b32_e32 v160, 0, v233, vcc
	v_sub_f32_e32 v158, v158, v160
	v_sub_f32_e32 v158, v159, v158
	v_mul_f32_e32 v181, 0x3d800000, v158
	v_fmac_f32_e32 v141, 0x3d800000, v158
	s_waitcnt lgkmcnt(0)
	v_mul_f32_e32 v158, v5, v183
	v_fmac_f32_e32 v158, v4, v182
	v_fmac_f32_e32 v158, v6, v184
	v_fmac_f32_e32 v158, v7, v185
	ds_read_b128 v[182:185], v9 offset:1168
	v_add_f32_e32 v158, v157, v158
	s_waitcnt lgkmcnt(0)
	v_mul_f32_e32 v159, v154, v183
	v_fmac_f32_e32 v159, v228, v182
	v_fmac_f32_e32 v159, v155, v184
	v_fmac_f32_e32 v159, v156, v185
	ds_read_b128 v[182:185], v9 offset:1184
	v_add_f32_e32 v158, v158, v159
	s_waitcnt lgkmcnt(0)
	v_mul_f32_e32 v159, v252, v183
	v_fmac_f32_e32 v159, v146, v182
	v_fmac_f32_e32 v159, v253, v184
	v_fmac_f32_e32 v159, v227, v185
	ds_read_b128 v[182:185], v9 offset:1200
	v_add_f32_e32 v158, v158, v159
	s_waitcnt lgkmcnt(0)
	v_mul_f32_e32 v159, v147, v183
	v_fmac_f32_e32 v159, v145, v182
	v_fmac_f32_e32 v159, v230, v184
	v_fmac_f32_e32 v159, v231, v185
	v_add_f32_e32 v158, v158, v159
	v_min_f32_e32 v159, 0, v158
	v_mul_f32_e64 v158, |v158|, s18
	v_exp_f32_e32 v158, v158
	ds_read_b128 v[184:187], v9 offset:1280
	v_add_f32_e32 v158, 1.0, v158
	v_cmp_gt_f32_e32 vcc, s71, v158
	s_nop 1
	v_cndmask_b32_e64 v160, 0, 32, vcc
	v_ldexp_f32 v158, v158, v160
	v_log_f32_e32 v158, v158
	s_nop 0
	v_mul_f32_e32 v160, 0x3f317217, v158
	v_fma_f32 v160, v158, s48, -v160
	v_fmac_f32_e32 v160, 0x3377d1cf, v158
	v_fmac_f32_e32 v160, 0x3f317217, v158
	v_cmp_lt_f32_e64 s[0:1], |v158|, s49
	s_nop 1
	v_cndmask_b32_e64 v158, v158, v160, s[0:1]
	v_cndmask_b32_e32 v160, 0, v233, vcc
	v_sub_f32_e32 v158, v158, v160
	v_sub_f32_e32 v158, v159, v158
	v_mul_f32_e32 v182, 0x3d800000, v158
	v_fmac_f32_e32 v141, 0x3d800000, v158
	s_waitcnt lgkmcnt(0)
	v_mul_f32_e32 v158, v5, v185
	v_fmac_f32_e32 v158, v4, v184
	v_fmac_f32_e32 v158, v6, v186
	v_fmac_f32_e32 v158, v7, v187
	ds_read_b128 v[184:187], v9 offset:1296
	v_add_f32_e32 v158, v157, v158
	s_waitcnt lgkmcnt(0)
	v_mul_f32_e32 v159, v154, v185
	v_fmac_f32_e32 v159, v228, v184
	v_fmac_f32_e32 v159, v155, v186
	v_fmac_f32_e32 v159, v156, v187
	ds_read_b128 v[184:187], v9 offset:1312
	v_add_f32_e32 v158, v158, v159
	s_waitcnt lgkmcnt(0)
	v_mul_f32_e32 v159, v252, v185
	v_fmac_f32_e32 v159, v146, v184
	v_fmac_f32_e32 v159, v253, v186
	v_fmac_f32_e32 v159, v227, v187
	ds_read_b128 v[184:187], v9 offset:1328
	v_add_f32_e32 v158, v158, v159
	s_waitcnt lgkmcnt(0)
	v_mul_f32_e32 v159, v147, v185
	v_fmac_f32_e32 v159, v145, v184
	v_fmac_f32_e32 v159, v230, v186
	v_fmac_f32_e32 v159, v231, v187
	v_add_f32_e32 v158, v158, v159
	v_min_f32_e32 v159, 0, v158
	v_mul_f32_e64 v158, |v158|, s18
	v_exp_f32_e32 v158, v158
	ds_read_b128 v[184:187], v9 offset:1408
	v_add_f32_e32 v158, 1.0, v158
	v_cmp_gt_f32_e32 vcc, s71, v158
	s_nop 1
	v_cndmask_b32_e64 v160, 0, 32, vcc
	v_ldexp_f32 v158, v158, v160
	v_log_f32_e32 v158, v158
	s_nop 0
	v_mul_f32_e32 v160, 0x3f317217, v158
	v_fma_f32 v160, v158, s48, -v160
	v_fmac_f32_e32 v160, 0x3377d1cf, v158
	v_fmac_f32_e32 v160, 0x3f317217, v158
	v_cmp_lt_f32_e64 s[0:1], |v158|, s49
	s_nop 1
	v_cndmask_b32_e64 v158, v158, v160, s[0:1]
	v_cndmask_b32_e32 v160, 0, v233, vcc
	v_sub_f32_e32 v158, v158, v160
	v_sub_f32_e32 v158, v159, v158
	v_mul_f32_e32 v183, 0x3d800000, v158
	v_fmac_f32_e32 v141, 0x3d800000, v158
	s_waitcnt lgkmcnt(0)
	v_mul_f32_e32 v158, v5, v185
	v_fmac_f32_e32 v158, v4, v184
	v_fmac_f32_e32 v158, v6, v186
	v_fmac_f32_e32 v158, v7, v187
	ds_read_b128 v[184:187], v9 offset:1424
	v_add_f32_e32 v158, v157, v158
	s_waitcnt lgkmcnt(0)
	v_mul_f32_e32 v159, v154, v185
	v_fmac_f32_e32 v159, v228, v184
	v_fmac_f32_e32 v159, v155, v186
	v_fmac_f32_e32 v159, v156, v187
	ds_read_b128 v[184:187], v9 offset:1440
	v_add_f32_e32 v158, v158, v159
	s_waitcnt lgkmcnt(0)
	v_mul_f32_e32 v159, v252, v185
	v_fmac_f32_e32 v159, v146, v184
	v_fmac_f32_e32 v159, v253, v186
	v_fmac_f32_e32 v159, v227, v187
	ds_read_b128 v[184:187], v9 offset:1456
	v_add_f32_e32 v158, v158, v159
	s_waitcnt lgkmcnt(0)
	v_mul_f32_e32 v159, v147, v185
	v_fmac_f32_e32 v159, v145, v184
	v_fmac_f32_e32 v159, v230, v186
	v_fmac_f32_e32 v159, v231, v187
	v_add_f32_e32 v158, v158, v159
	v_min_f32_e32 v159, 0, v158
	v_mul_f32_e64 v158, |v158|, s18
	v_exp_f32_e32 v158, v158
	ds_read_b128 v[186:189], v9 offset:1536
	v_add_f32_e32 v158, 1.0, v158
	v_cmp_gt_f32_e32 vcc, s71, v158
	s_nop 1
	v_cndmask_b32_e64 v160, 0, 32, vcc
	v_ldexp_f32 v158, v158, v160
	v_log_f32_e32 v158, v158
	s_nop 0
	v_mul_f32_e32 v160, 0x3f317217, v158
	v_fma_f32 v160, v158, s48, -v160
	v_fmac_f32_e32 v160, 0x3377d1cf, v158
	v_fmac_f32_e32 v160, 0x3f317217, v158
	v_cmp_lt_f32_e64 s[0:1], |v158|, s49
	s_nop 1
	v_cndmask_b32_e64 v158, v158, v160, s[0:1]
	v_cndmask_b32_e32 v160, 0, v233, vcc
	v_sub_f32_e32 v158, v158, v160
	v_sub_f32_e32 v158, v159, v158
	v_mul_f32_e32 v184, 0x3d800000, v158
	v_fmac_f32_e32 v141, 0x3d800000, v158
	s_waitcnt lgkmcnt(0)
	v_mul_f32_e32 v158, v5, v187
	v_fmac_f32_e32 v158, v4, v186
	v_fmac_f32_e32 v158, v6, v188
	v_fmac_f32_e32 v158, v7, v189
	ds_read_b128 v[186:189], v9 offset:1552
	v_add_f32_e32 v158, v157, v158
	s_waitcnt lgkmcnt(0)
	v_mul_f32_e32 v159, v154, v187
	v_fmac_f32_e32 v159, v228, v186
	v_fmac_f32_e32 v159, v155, v188
	v_fmac_f32_e32 v159, v156, v189
	ds_read_b128 v[186:189], v9 offset:1568
	v_add_f32_e32 v158, v158, v159
	s_waitcnt lgkmcnt(0)
	v_mul_f32_e32 v159, v252, v187
	v_fmac_f32_e32 v159, v146, v186
	v_fmac_f32_e32 v159, v253, v188
	v_fmac_f32_e32 v159, v227, v189
	ds_read_b128 v[186:189], v9 offset:1584
	v_add_f32_e32 v158, v158, v159
	s_waitcnt lgkmcnt(0)
	v_mul_f32_e32 v159, v147, v187
	v_fmac_f32_e32 v159, v145, v186
	v_fmac_f32_e32 v159, v230, v188
	v_fmac_f32_e32 v159, v231, v189
	v_add_f32_e32 v158, v158, v159
	v_min_f32_e32 v159, 0, v158
	v_mul_f32_e64 v158, |v158|, s18
	v_exp_f32_e32 v158, v158
	ds_read_b128 v[186:189], v9 offset:1664
	v_add_f32_e32 v158, 1.0, v158
	v_cmp_gt_f32_e32 vcc, s71, v158
	s_nop 1
	v_cndmask_b32_e64 v160, 0, 32, vcc
	v_ldexp_f32 v158, v158, v160
	v_log_f32_e32 v158, v158
	s_nop 0
	v_mul_f32_e32 v160, 0x3f317217, v158
	v_fma_f32 v160, v158, s48, -v160
	v_fmac_f32_e32 v160, 0x3377d1cf, v158
	v_fmac_f32_e32 v160, 0x3f317217, v158
	v_cmp_lt_f32_e64 s[0:1], |v158|, s49
	s_nop 1
	v_cndmask_b32_e64 v158, v158, v160, s[0:1]
	v_cndmask_b32_e32 v160, 0, v233, vcc
	v_sub_f32_e32 v158, v158, v160
	v_sub_f32_e32 v158, v159, v158
	v_mul_f32_e32 v185, 0x3d800000, v158
	v_fmac_f32_e32 v141, 0x3d800000, v158
	s_waitcnt lgkmcnt(0)
	v_mul_f32_e32 v158, v5, v187
	v_fmac_f32_e32 v158, v4, v186
	v_fmac_f32_e32 v158, v6, v188
	v_fmac_f32_e32 v158, v7, v189
	ds_read_b128 v[186:189], v9 offset:1680
	v_add_f32_e32 v158, v157, v158
	s_waitcnt lgkmcnt(0)
	v_mul_f32_e32 v159, v154, v187
	v_fmac_f32_e32 v159, v228, v186
	v_fmac_f32_e32 v159, v155, v188
	v_fmac_f32_e32 v159, v156, v189
	ds_read_b128 v[186:189], v9 offset:1696
	v_add_f32_e32 v158, v158, v159
	s_waitcnt lgkmcnt(0)
	v_mul_f32_e32 v159, v252, v187
	v_fmac_f32_e32 v159, v146, v186
	v_fmac_f32_e32 v159, v253, v188
	v_fmac_f32_e32 v159, v227, v189
	ds_read_b128 v[186:189], v9 offset:1712
	v_add_f32_e32 v158, v158, v159
	s_waitcnt lgkmcnt(0)
	v_mul_f32_e32 v159, v147, v187
	v_fmac_f32_e32 v159, v145, v186
	v_fmac_f32_e32 v159, v230, v188
	v_fmac_f32_e32 v159, v231, v189
	v_add_f32_e32 v158, v158, v159
	v_min_f32_e32 v159, 0, v158
	v_mul_f32_e64 v158, |v158|, s18
	v_exp_f32_e32 v158, v158
	ds_read_b128 v[188:191], v9 offset:1792
	v_add_f32_e32 v158, 1.0, v158
	v_cmp_gt_f32_e32 vcc, s71, v158
	s_nop 1
	v_cndmask_b32_e64 v160, 0, 32, vcc
	v_ldexp_f32 v158, v158, v160
	v_log_f32_e32 v158, v158
	s_nop 0
	v_mul_f32_e32 v160, 0x3f317217, v158
	v_fma_f32 v160, v158, s48, -v160
	v_fmac_f32_e32 v160, 0x3377d1cf, v158
	v_fmac_f32_e32 v160, 0x3f317217, v158
	v_cmp_lt_f32_e64 s[0:1], |v158|, s49
	s_nop 1
	v_cndmask_b32_e64 v158, v158, v160, s[0:1]
	v_cndmask_b32_e32 v160, 0, v233, vcc
	v_sub_f32_e32 v158, v158, v160
	v_sub_f32_e32 v158, v159, v158
	v_mul_f32_e32 v186, 0x3d800000, v158
	v_fmac_f32_e32 v141, 0x3d800000, v158
	s_waitcnt lgkmcnt(0)
	v_mul_f32_e32 v158, v5, v189
	v_fmac_f32_e32 v158, v4, v188
	v_fmac_f32_e32 v158, v6, v190
	v_fmac_f32_e32 v158, v7, v191
	ds_read_b128 v[188:191], v9 offset:1808
	v_add_f32_e32 v158, v157, v158
	s_waitcnt lgkmcnt(0)
	v_mul_f32_e32 v159, v154, v189
	v_fmac_f32_e32 v159, v228, v188
	v_fmac_f32_e32 v159, v155, v190
	v_fmac_f32_e32 v159, v156, v191
	ds_read_b128 v[188:191], v9 offset:1824
	v_add_f32_e32 v158, v158, v159
	s_waitcnt lgkmcnt(0)
	v_mul_f32_e32 v159, v252, v189
	v_fmac_f32_e32 v159, v146, v188
	v_fmac_f32_e32 v159, v253, v190
	v_fmac_f32_e32 v159, v227, v191
	ds_read_b128 v[188:191], v9 offset:1840
	v_add_f32_e32 v158, v158, v159
	s_waitcnt lgkmcnt(0)
	v_mul_f32_e32 v159, v147, v189
	v_fmac_f32_e32 v159, v145, v188
	v_fmac_f32_e32 v159, v230, v190
	v_fmac_f32_e32 v159, v231, v191
	v_add_f32_e32 v158, v158, v159
	v_min_f32_e32 v159, 0, v158
	v_mul_f32_e64 v158, |v158|, s18
	v_exp_f32_e32 v158, v158
	ds_read_b128 v[188:191], v9 offset:1920
	v_add_f32_e32 v158, 1.0, v158
	v_cmp_gt_f32_e32 vcc, s71, v158
	s_nop 1
	v_cndmask_b32_e64 v160, 0, 32, vcc
	v_ldexp_f32 v158, v158, v160
	v_log_f32_e32 v158, v158
	s_nop 0
	v_mul_f32_e32 v160, 0x3f317217, v158
	v_fma_f32 v160, v158, s48, -v160
	v_fmac_f32_e32 v160, 0x3377d1cf, v158
	v_fmac_f32_e32 v160, 0x3f317217, v158
	v_cmp_lt_f32_e64 s[0:1], |v158|, s49
	s_nop 1
	v_cndmask_b32_e64 v158, v158, v160, s[0:1]
	v_cndmask_b32_e32 v160, 0, v233, vcc
	v_sub_f32_e32 v158, v158, v160
	v_sub_f32_e32 v158, v159, v158
	v_mul_f32_e32 v187, 0x3d800000, v158
	v_fmac_f32_e32 v141, 0x3d800000, v158
	s_waitcnt lgkmcnt(0)
	v_mul_f32_e32 v158, v5, v189
	v_fmac_f32_e32 v158, v4, v188
	v_fmac_f32_e32 v158, v6, v190
	v_fmac_f32_e32 v158, v7, v191
	ds_read_b128 v[188:191], v9 offset:1936
	v_add_f32_e32 v158, v157, v158
	s_waitcnt lgkmcnt(0)
	v_mul_f32_e32 v159, v154, v189
	v_fmac_f32_e32 v159, v228, v188
	v_fmac_f32_e32 v159, v155, v190
	v_fmac_f32_e32 v159, v156, v191
	ds_read_b128 v[188:191], v9 offset:1952
	v_add_f32_e32 v158, v158, v159
	s_waitcnt lgkmcnt(0)
	v_mul_f32_e32 v159, v252, v189
	v_fmac_f32_e32 v159, v146, v188
	v_fmac_f32_e32 v159, v253, v190
	v_fmac_f32_e32 v159, v227, v191
	ds_read_b128 v[188:191], v9 offset:1968
	v_add_f32_e32 v158, v158, v159
	s_waitcnt lgkmcnt(0)
	v_mul_f32_e32 v159, v147, v189
	v_fmac_f32_e32 v159, v145, v188
	v_fmac_f32_e32 v159, v230, v190
	v_fmac_f32_e32 v159, v231, v191
	v_add_f32_e32 v158, v158, v159
	v_min_f32_e32 v159, 0, v158
	v_mul_f32_e64 v158, |v158|, s18
	v_exp_f32_e32 v158, v158
	ds_read_b128 v[190:193], v9 offset:2048
	v_add_f32_e32 v158, 1.0, v158
	v_cmp_gt_f32_e32 vcc, s71, v158
	s_nop 1
	v_cndmask_b32_e64 v160, 0, 32, vcc
	v_ldexp_f32 v158, v158, v160
	v_log_f32_e32 v158, v158
	s_nop 0
	v_mul_f32_e32 v160, 0x3f317217, v158
	v_fma_f32 v160, v158, s48, -v160
	v_fmac_f32_e32 v160, 0x3377d1cf, v158
	v_fmac_f32_e32 v160, 0x3f317217, v158
	v_cmp_lt_f32_e64 s[0:1], |v158|, s49
	s_nop 1
	v_cndmask_b32_e64 v158, v158, v160, s[0:1]
	v_cndmask_b32_e32 v160, 0, v233, vcc
	v_sub_f32_e32 v158, v158, v160
	v_sub_f32_e32 v158, v159, v158
	v_mul_f32_e32 v188, 0x3d800000, v158
	v_fmac_f32_e32 v141, 0x3d800000, v158
	s_waitcnt lgkmcnt(0)
	v_mul_f32_e32 v158, v5, v191
	v_fmac_f32_e32 v158, v4, v190
	v_fmac_f32_e32 v158, v6, v192
	v_fmac_f32_e32 v158, v7, v193
	ds_read_b128 v[190:193], v9 offset:2064
	v_add_f32_e32 v158, v157, v158
	s_waitcnt lgkmcnt(0)
	v_mul_f32_e32 v159, v154, v191
	v_fmac_f32_e32 v159, v228, v190
	v_fmac_f32_e32 v159, v155, v192
	v_fmac_f32_e32 v159, v156, v193
	ds_read_b128 v[190:193], v9 offset:2080
	v_add_f32_e32 v158, v158, v159
	s_waitcnt lgkmcnt(0)
	v_mul_f32_e32 v159, v252, v191
	v_fmac_f32_e32 v159, v146, v190
	v_fmac_f32_e32 v159, v253, v192
	v_fmac_f32_e32 v159, v227, v193
	ds_read_b128 v[190:193], v9 offset:2096
	v_add_f32_e32 v158, v158, v159
	s_waitcnt lgkmcnt(0)
	v_mul_f32_e32 v159, v147, v191
	v_fmac_f32_e32 v159, v145, v190
	v_fmac_f32_e32 v159, v230, v192
	v_fmac_f32_e32 v159, v231, v193
	v_add_f32_e32 v158, v158, v159
	v_min_f32_e32 v159, 0, v158
	v_mul_f32_e64 v158, |v158|, s18
	v_exp_f32_e32 v158, v158
	ds_read_b128 v[190:193], v9 offset:2176
	v_add_f32_e32 v158, 1.0, v158
	v_cmp_gt_f32_e32 vcc, s71, v158
	s_nop 1
	v_cndmask_b32_e64 v160, 0, 32, vcc
	v_ldexp_f32 v158, v158, v160
	v_log_f32_e32 v158, v158
	s_nop 0
	v_mul_f32_e32 v160, 0x3f317217, v158
	v_fma_f32 v160, v158, s48, -v160
	v_fmac_f32_e32 v160, 0x3377d1cf, v158
	v_fmac_f32_e32 v160, 0x3f317217, v158
	v_cmp_lt_f32_e64 s[0:1], |v158|, s49
	s_nop 1
	v_cndmask_b32_e64 v158, v158, v160, s[0:1]
	v_cndmask_b32_e32 v160, 0, v233, vcc
	v_sub_f32_e32 v158, v158, v160
	v_sub_f32_e32 v158, v159, v158
	v_mul_f32_e32 v189, 0x3d800000, v158
	v_fmac_f32_e32 v141, 0x3d800000, v158
	s_waitcnt lgkmcnt(0)
	v_mul_f32_e32 v158, v5, v191
	v_fmac_f32_e32 v158, v4, v190
	v_fmac_f32_e32 v158, v6, v192
	v_fmac_f32_e32 v158, v7, v193
	ds_read_b128 v[190:193], v9 offset:2192
	v_add_f32_e32 v158, v157, v158
	s_waitcnt lgkmcnt(0)
	v_mul_f32_e32 v159, v154, v191
	v_fmac_f32_e32 v159, v228, v190
	v_fmac_f32_e32 v159, v155, v192
	v_fmac_f32_e32 v159, v156, v193
	ds_read_b128 v[190:193], v9 offset:2208
	v_add_f32_e32 v158, v158, v159
	s_waitcnt lgkmcnt(0)
	v_mul_f32_e32 v159, v252, v191
	v_fmac_f32_e32 v159, v146, v190
	v_fmac_f32_e32 v159, v253, v192
	v_fmac_f32_e32 v159, v227, v193
	ds_read_b128 v[190:193], v9 offset:2224
	v_add_f32_e32 v158, v158, v159
	s_waitcnt lgkmcnt(0)
	v_mul_f32_e32 v159, v147, v191
	v_fmac_f32_e32 v159, v145, v190
	v_fmac_f32_e32 v159, v230, v192
	v_fmac_f32_e32 v159, v231, v193
	v_add_f32_e32 v158, v158, v159
	v_min_f32_e32 v159, 0, v158
	v_mul_f32_e64 v158, |v158|, s18
	v_exp_f32_e32 v158, v158
	ds_read_b128 v[192:195], v9 offset:2304
	v_add_f32_e32 v158, 1.0, v158
	v_cmp_gt_f32_e32 vcc, s71, v158
	s_nop 1
	v_cndmask_b32_e64 v160, 0, 32, vcc
	v_ldexp_f32 v158, v158, v160
	v_log_f32_e32 v158, v158
	s_nop 0
	v_mul_f32_e32 v160, 0x3f317217, v158
	v_fma_f32 v160, v158, s48, -v160
	v_fmac_f32_e32 v160, 0x3377d1cf, v158
	v_fmac_f32_e32 v160, 0x3f317217, v158
	v_cmp_lt_f32_e64 s[0:1], |v158|, s49
	s_nop 1
	v_cndmask_b32_e64 v158, v158, v160, s[0:1]
	v_cndmask_b32_e32 v160, 0, v233, vcc
	v_sub_f32_e32 v158, v158, v160
	v_sub_f32_e32 v158, v159, v158
	v_mul_f32_e32 v190, 0x3d800000, v158
	v_fmac_f32_e32 v141, 0x3d800000, v158
	s_waitcnt lgkmcnt(0)
	v_mul_f32_e32 v158, v5, v193
	v_fmac_f32_e32 v158, v4, v192
	v_fmac_f32_e32 v158, v6, v194
	v_fmac_f32_e32 v158, v7, v195
	ds_read_b128 v[192:195], v9 offset:2320
	v_add_f32_e32 v158, v157, v158
	s_waitcnt lgkmcnt(0)
	v_mul_f32_e32 v159, v154, v193
	v_fmac_f32_e32 v159, v228, v192
	v_fmac_f32_e32 v159, v155, v194
	v_fmac_f32_e32 v159, v156, v195
	ds_read_b128 v[192:195], v9 offset:2336
	v_add_f32_e32 v158, v158, v159
	s_waitcnt lgkmcnt(0)
	v_mul_f32_e32 v159, v252, v193
	v_fmac_f32_e32 v159, v146, v192
	v_fmac_f32_e32 v159, v253, v194
	v_fmac_f32_e32 v159, v227, v195
	ds_read_b128 v[192:195], v9 offset:2352
	v_add_f32_e32 v158, v158, v159
	s_waitcnt lgkmcnt(0)
	v_mul_f32_e32 v159, v147, v193
	v_fmac_f32_e32 v159, v145, v192
	v_fmac_f32_e32 v159, v230, v194
	v_fmac_f32_e32 v159, v231, v195
	v_add_f32_e32 v158, v158, v159
	v_min_f32_e32 v159, 0, v158
	v_mul_f32_e64 v158, |v158|, s18
	v_exp_f32_e32 v158, v158
	ds_read_b128 v[192:195], v9 offset:2432
	v_add_f32_e32 v158, 1.0, v158
	v_cmp_gt_f32_e32 vcc, s71, v158
	s_nop 1
	v_cndmask_b32_e64 v160, 0, 32, vcc
	v_ldexp_f32 v158, v158, v160
	v_log_f32_e32 v158, v158
	s_nop 0
	v_mul_f32_e32 v160, 0x3f317217, v158
	v_fma_f32 v160, v158, s48, -v160
	v_fmac_f32_e32 v160, 0x3377d1cf, v158
	v_fmac_f32_e32 v160, 0x3f317217, v158
	v_cmp_lt_f32_e64 s[0:1], |v158|, s49
	s_nop 1
	v_cndmask_b32_e64 v158, v158, v160, s[0:1]
	v_cndmask_b32_e32 v160, 0, v233, vcc
	v_sub_f32_e32 v158, v158, v160
	v_sub_f32_e32 v158, v159, v158
	v_mul_f32_e32 v191, 0x3d800000, v158
	v_fmac_f32_e32 v141, 0x3d800000, v158
	s_waitcnt lgkmcnt(0)
	v_mul_f32_e32 v158, v5, v193
	v_fmac_f32_e32 v158, v4, v192
	v_fmac_f32_e32 v158, v6, v194
	v_fmac_f32_e32 v158, v7, v195
	ds_read_b128 v[192:195], v9 offset:2448
	v_add_f32_e32 v158, v157, v158
	s_waitcnt lgkmcnt(0)
	v_mul_f32_e32 v159, v154, v193
	v_fmac_f32_e32 v159, v228, v192
	v_fmac_f32_e32 v159, v155, v194
	v_fmac_f32_e32 v159, v156, v195
	ds_read_b128 v[192:195], v9 offset:2464
	v_add_f32_e32 v158, v158, v159
	s_waitcnt lgkmcnt(0)
	v_mul_f32_e32 v159, v252, v193
	v_fmac_f32_e32 v159, v146, v192
	v_fmac_f32_e32 v159, v253, v194
	v_fmac_f32_e32 v159, v227, v195
	ds_read_b128 v[192:195], v9 offset:2480
	v_add_f32_e32 v158, v158, v159
	s_waitcnt lgkmcnt(0)
	v_mul_f32_e32 v159, v147, v193
	v_fmac_f32_e32 v159, v145, v192
	v_fmac_f32_e32 v159, v230, v194
	v_fmac_f32_e32 v159, v231, v195
	v_add_f32_e32 v158, v158, v159
	v_min_f32_e32 v159, 0, v158
	v_mul_f32_e64 v158, |v158|, s18
	v_exp_f32_e32 v158, v158
	ds_read_b128 v[194:197], v9 offset:2560
	v_add_f32_e32 v158, 1.0, v158
	v_cmp_gt_f32_e32 vcc, s71, v158
	s_nop 1
	v_cndmask_b32_e64 v160, 0, 32, vcc
	v_ldexp_f32 v158, v158, v160
	v_log_f32_e32 v158, v158
	s_nop 0
	v_mul_f32_e32 v160, 0x3f317217, v158
	v_fma_f32 v160, v158, s48, -v160
	v_fmac_f32_e32 v160, 0x3377d1cf, v158
	v_fmac_f32_e32 v160, 0x3f317217, v158
	v_cmp_lt_f32_e64 s[0:1], |v158|, s49
	s_nop 1
	v_cndmask_b32_e64 v158, v158, v160, s[0:1]
	v_cndmask_b32_e32 v160, 0, v233, vcc
	v_sub_f32_e32 v158, v158, v160
	v_sub_f32_e32 v158, v159, v158
	v_mul_f32_e32 v192, 0x3d800000, v158
	v_fmac_f32_e32 v141, 0x3d800000, v158
	s_waitcnt lgkmcnt(0)
	v_mul_f32_e32 v158, v5, v195
	v_fmac_f32_e32 v158, v4, v194
	v_fmac_f32_e32 v158, v6, v196
	v_fmac_f32_e32 v158, v7, v197
	ds_read_b128 v[194:197], v9 offset:2576
	v_add_f32_e32 v158, v157, v158
	s_waitcnt lgkmcnt(0)
	v_mul_f32_e32 v159, v154, v195
	v_fmac_f32_e32 v159, v228, v194
	v_fmac_f32_e32 v159, v155, v196
	v_fmac_f32_e32 v159, v156, v197
	ds_read_b128 v[194:197], v9 offset:2592
	v_add_f32_e32 v158, v158, v159
	s_waitcnt lgkmcnt(0)
	v_mul_f32_e32 v159, v252, v195
	v_fmac_f32_e32 v159, v146, v194
	v_fmac_f32_e32 v159, v253, v196
	v_fmac_f32_e32 v159, v227, v197
	ds_read_b128 v[194:197], v9 offset:2608
	v_add_f32_e32 v158, v158, v159
	s_waitcnt lgkmcnt(0)
	v_mul_f32_e32 v159, v147, v195
	v_fmac_f32_e32 v159, v145, v194
	v_fmac_f32_e32 v159, v230, v196
	v_fmac_f32_e32 v159, v231, v197
	v_add_f32_e32 v158, v158, v159
	v_min_f32_e32 v159, 0, v158
	v_mul_f32_e64 v158, |v158|, s18
	v_exp_f32_e32 v158, v158
	ds_read_b128 v[194:197], v9 offset:2688
	v_add_f32_e32 v158, 1.0, v158
	v_cmp_gt_f32_e32 vcc, s71, v158
	s_nop 1
	v_cndmask_b32_e64 v160, 0, 32, vcc
	v_ldexp_f32 v158, v158, v160
	v_log_f32_e32 v158, v158
	s_nop 0
	v_mul_f32_e32 v160, 0x3f317217, v158
	v_fma_f32 v160, v158, s48, -v160
	v_fmac_f32_e32 v160, 0x3377d1cf, v158
	v_fmac_f32_e32 v160, 0x3f317217, v158
	v_cmp_lt_f32_e64 s[0:1], |v158|, s49
	s_nop 1
	v_cndmask_b32_e64 v158, v158, v160, s[0:1]
	v_cndmask_b32_e32 v160, 0, v233, vcc
	v_sub_f32_e32 v158, v158, v160
	v_sub_f32_e32 v158, v159, v158
	v_mul_f32_e32 v193, 0x3d800000, v158
	v_fmac_f32_e32 v141, 0x3d800000, v158
	s_waitcnt lgkmcnt(0)
	v_mul_f32_e32 v158, v5, v195
	v_fmac_f32_e32 v158, v4, v194
	v_fmac_f32_e32 v158, v6, v196
	v_fmac_f32_e32 v158, v7, v197
	ds_read_b128 v[194:197], v9 offset:2704
	v_add_f32_e32 v158, v157, v158
	s_waitcnt lgkmcnt(0)
	v_mul_f32_e32 v159, v154, v195
	v_fmac_f32_e32 v159, v228, v194
	v_fmac_f32_e32 v159, v155, v196
	v_fmac_f32_e32 v159, v156, v197
	ds_read_b128 v[194:197], v9 offset:2720
	v_add_f32_e32 v158, v158, v159
	s_waitcnt lgkmcnt(0)
	v_mul_f32_e32 v159, v252, v195
	v_fmac_f32_e32 v159, v146, v194
	v_fmac_f32_e32 v159, v253, v196
	v_fmac_f32_e32 v159, v227, v197
	ds_read_b128 v[194:197], v9 offset:2736
	v_add_f32_e32 v158, v158, v159
	s_waitcnt lgkmcnt(0)
	v_mul_f32_e32 v159, v147, v195
	v_fmac_f32_e32 v159, v145, v194
	v_fmac_f32_e32 v159, v230, v196
	v_fmac_f32_e32 v159, v231, v197
	v_add_f32_e32 v158, v158, v159
	v_min_f32_e32 v159, 0, v158
	v_mul_f32_e64 v158, |v158|, s18
	v_exp_f32_e32 v158, v158
	ds_read_b128 v[196:199], v9 offset:2816
	v_add_f32_e32 v158, 1.0, v158
	v_cmp_gt_f32_e32 vcc, s71, v158
	s_nop 1
	v_cndmask_b32_e64 v160, 0, 32, vcc
	v_ldexp_f32 v158, v158, v160
	v_log_f32_e32 v158, v158
	s_nop 0
	v_mul_f32_e32 v160, 0x3f317217, v158
	v_fma_f32 v160, v158, s48, -v160
	v_fmac_f32_e32 v160, 0x3377d1cf, v158
	v_fmac_f32_e32 v160, 0x3f317217, v158
	v_cmp_lt_f32_e64 s[0:1], |v158|, s49
	s_nop 1
	v_cndmask_b32_e64 v158, v158, v160, s[0:1]
	v_cndmask_b32_e32 v160, 0, v233, vcc
	v_sub_f32_e32 v158, v158, v160
	v_sub_f32_e32 v158, v159, v158
	v_mul_f32_e32 v194, 0x3d800000, v158
	v_fmac_f32_e32 v141, 0x3d800000, v158
	s_waitcnt lgkmcnt(0)
	v_mul_f32_e32 v158, v5, v197
	v_fmac_f32_e32 v158, v4, v196
	v_fmac_f32_e32 v158, v6, v198
	v_fmac_f32_e32 v158, v7, v199
	ds_read_b128 v[196:199], v9 offset:2832
	v_add_f32_e32 v158, v157, v158
	s_waitcnt lgkmcnt(0)
	v_mul_f32_e32 v159, v154, v197
	v_fmac_f32_e32 v159, v228, v196
	v_fmac_f32_e32 v159, v155, v198
	v_fmac_f32_e32 v159, v156, v199
	ds_read_b128 v[196:199], v9 offset:2848
	v_add_f32_e32 v158, v158, v159
	s_waitcnt lgkmcnt(0)
	v_mul_f32_e32 v159, v252, v197
	v_fmac_f32_e32 v159, v146, v196
	v_fmac_f32_e32 v159, v253, v198
	v_fmac_f32_e32 v159, v227, v199
	ds_read_b128 v[196:199], v9 offset:2864
	v_add_f32_e32 v158, v158, v159
	s_waitcnt lgkmcnt(0)
	v_mul_f32_e32 v159, v147, v197
	v_fmac_f32_e32 v159, v145, v196
	v_fmac_f32_e32 v159, v230, v198
	v_fmac_f32_e32 v159, v231, v199
	v_add_f32_e32 v158, v158, v159
	v_min_f32_e32 v159, 0, v158
	v_mul_f32_e64 v158, |v158|, s18
	v_exp_f32_e32 v158, v158
	ds_read_b128 v[196:199], v9 offset:2944
	v_add_f32_e32 v158, 1.0, v158
	v_cmp_gt_f32_e32 vcc, s71, v158
	s_nop 1
	v_cndmask_b32_e64 v160, 0, 32, vcc
	v_ldexp_f32 v158, v158, v160
	v_log_f32_e32 v158, v158
	s_nop 0
	v_mul_f32_e32 v160, 0x3f317217, v158
	v_fma_f32 v160, v158, s48, -v160
	v_fmac_f32_e32 v160, 0x3377d1cf, v158
	v_fmac_f32_e32 v160, 0x3f317217, v158
	v_cmp_lt_f32_e64 s[0:1], |v158|, s49
	s_nop 1
	v_cndmask_b32_e64 v158, v158, v160, s[0:1]
	v_cndmask_b32_e32 v160, 0, v233, vcc
	v_sub_f32_e32 v158, v158, v160
	v_sub_f32_e32 v158, v159, v158
	v_mul_f32_e32 v195, 0x3d800000, v158
	v_fmac_f32_e32 v141, 0x3d800000, v158
	s_waitcnt lgkmcnt(0)
	v_mul_f32_e32 v158, v5, v197
	v_fmac_f32_e32 v158, v4, v196
	v_fmac_f32_e32 v158, v6, v198
	v_fmac_f32_e32 v158, v7, v199
	ds_read_b128 v[196:199], v9 offset:2960
	v_add_f32_e32 v158, v157, v158
	s_waitcnt lgkmcnt(0)
	v_mul_f32_e32 v159, v154, v197
	v_fmac_f32_e32 v159, v228, v196
	v_fmac_f32_e32 v159, v155, v198
	v_fmac_f32_e32 v159, v156, v199
	ds_read_b128 v[196:199], v9 offset:2976
	v_add_f32_e32 v158, v158, v159
	s_waitcnt lgkmcnt(0)
	v_mul_f32_e32 v159, v252, v197
	v_fmac_f32_e32 v159, v146, v196
	v_fmac_f32_e32 v159, v253, v198
	v_fmac_f32_e32 v159, v227, v199
	ds_read_b128 v[196:199], v9 offset:2992
	v_add_f32_e32 v158, v158, v159
	s_waitcnt lgkmcnt(0)
	v_mul_f32_e32 v159, v147, v197
	v_fmac_f32_e32 v159, v145, v196
	v_fmac_f32_e32 v159, v230, v198
	v_fmac_f32_e32 v159, v231, v199
	v_add_f32_e32 v158, v158, v159
	v_min_f32_e32 v159, 0, v158
	v_mul_f32_e64 v158, |v158|, s18
	v_exp_f32_e32 v158, v158
	ds_read_b128 v[198:201], v9 offset:3072
	v_add_f32_e32 v158, 1.0, v158
	v_cmp_gt_f32_e32 vcc, s71, v158
	s_nop 1
	v_cndmask_b32_e64 v160, 0, 32, vcc
	v_ldexp_f32 v158, v158, v160
	v_log_f32_e32 v158, v158
	s_nop 0
	v_mul_f32_e32 v160, 0x3f317217, v158
	v_fma_f32 v160, v158, s48, -v160
	v_fmac_f32_e32 v160, 0x3377d1cf, v158
	v_fmac_f32_e32 v160, 0x3f317217, v158
	v_cmp_lt_f32_e64 s[0:1], |v158|, s49
	s_nop 1
	v_cndmask_b32_e64 v158, v158, v160, s[0:1]
	v_cndmask_b32_e32 v160, 0, v233, vcc
	v_sub_f32_e32 v158, v158, v160
	v_sub_f32_e32 v158, v159, v158
	v_mul_f32_e32 v196, 0x3d800000, v158
	v_fmac_f32_e32 v141, 0x3d800000, v158
	s_waitcnt lgkmcnt(0)
	v_mul_f32_e32 v158, v5, v199
	v_fmac_f32_e32 v158, v4, v198
	v_fmac_f32_e32 v158, v6, v200
	v_fmac_f32_e32 v158, v7, v201
	ds_read_b128 v[198:201], v9 offset:3088
	v_add_f32_e32 v158, v157, v158
	s_waitcnt lgkmcnt(0)
	v_mul_f32_e32 v159, v154, v199
	v_fmac_f32_e32 v159, v228, v198
	v_fmac_f32_e32 v159, v155, v200
	v_fmac_f32_e32 v159, v156, v201
	ds_read_b128 v[198:201], v9 offset:3104
	v_add_f32_e32 v158, v158, v159
	s_waitcnt lgkmcnt(0)
	v_mul_f32_e32 v159, v252, v199
	v_fmac_f32_e32 v159, v146, v198
	v_fmac_f32_e32 v159, v253, v200
	v_fmac_f32_e32 v159, v227, v201
	ds_read_b128 v[198:201], v9 offset:3120
	v_add_f32_e32 v158, v158, v159
	s_waitcnt lgkmcnt(0)
	v_mul_f32_e32 v159, v147, v199
	v_fmac_f32_e32 v159, v145, v198
	v_fmac_f32_e32 v159, v230, v200
	v_fmac_f32_e32 v159, v231, v201
	v_add_f32_e32 v158, v158, v159
	v_min_f32_e32 v159, 0, v158
	v_mul_f32_e64 v158, |v158|, s18
	v_exp_f32_e32 v158, v158
	ds_read_b128 v[198:201], v9 offset:3200
	v_add_f32_e32 v158, 1.0, v158
	v_cmp_gt_f32_e32 vcc, s71, v158
	s_nop 1
	v_cndmask_b32_e64 v160, 0, 32, vcc
	v_ldexp_f32 v158, v158, v160
	v_log_f32_e32 v158, v158
	s_nop 0
	v_mul_f32_e32 v160, 0x3f317217, v158
	v_fma_f32 v160, v158, s48, -v160
	v_fmac_f32_e32 v160, 0x3377d1cf, v158
	v_fmac_f32_e32 v160, 0x3f317217, v158
	v_cmp_lt_f32_e64 s[0:1], |v158|, s49
	s_nop 1
	v_cndmask_b32_e64 v158, v158, v160, s[0:1]
	v_cndmask_b32_e32 v160, 0, v233, vcc
	v_sub_f32_e32 v158, v158, v160
	v_sub_f32_e32 v158, v159, v158
	v_mul_f32_e32 v197, 0x3d800000, v158
	v_fmac_f32_e32 v141, 0x3d800000, v158
	s_waitcnt lgkmcnt(0)
	v_mul_f32_e32 v158, v5, v199
	v_fmac_f32_e32 v158, v4, v198
	v_fmac_f32_e32 v158, v6, v200
	v_fmac_f32_e32 v158, v7, v201
	ds_read_b128 v[198:201], v9 offset:3216
	v_add_f32_e32 v158, v157, v158
	s_waitcnt lgkmcnt(0)
	v_mul_f32_e32 v159, v154, v199
	v_fmac_f32_e32 v159, v228, v198
	v_fmac_f32_e32 v159, v155, v200
	v_fmac_f32_e32 v159, v156, v201
	ds_read_b128 v[198:201], v9 offset:3232
	v_add_f32_e32 v158, v158, v159
	s_waitcnt lgkmcnt(0)
	v_mul_f32_e32 v159, v252, v199
	v_fmac_f32_e32 v159, v146, v198
	v_fmac_f32_e32 v159, v253, v200
	v_fmac_f32_e32 v159, v227, v201
	ds_read_b128 v[198:201], v9 offset:3248
	v_add_f32_e32 v158, v158, v159
	s_waitcnt lgkmcnt(0)
	v_mul_f32_e32 v159, v147, v199
	v_fmac_f32_e32 v159, v145, v198
	v_fmac_f32_e32 v159, v230, v200
	v_fmac_f32_e32 v159, v231, v201
	v_add_f32_e32 v158, v158, v159
	v_min_f32_e32 v159, 0, v158
	v_mul_f32_e64 v158, |v158|, s18
	v_exp_f32_e32 v158, v158
	ds_read_b128 v[200:203], v9 offset:3328
	v_add_f32_e32 v158, 1.0, v158
	v_cmp_gt_f32_e32 vcc, s71, v158
	s_nop 1
	v_cndmask_b32_e64 v160, 0, 32, vcc
	v_ldexp_f32 v158, v158, v160
	v_log_f32_e32 v158, v158
	s_nop 0
	v_mul_f32_e32 v160, 0x3f317217, v158
	v_fma_f32 v160, v158, s48, -v160
	v_fmac_f32_e32 v160, 0x3377d1cf, v158
	v_fmac_f32_e32 v160, 0x3f317217, v158
	v_cmp_lt_f32_e64 s[0:1], |v158|, s49
	s_nop 1
	v_cndmask_b32_e64 v158, v158, v160, s[0:1]
	v_cndmask_b32_e32 v160, 0, v233, vcc
	v_sub_f32_e32 v158, v158, v160
	v_sub_f32_e32 v158, v159, v158
	v_mul_f32_e32 v198, 0x3d800000, v158
	v_fmac_f32_e32 v141, 0x3d800000, v158
	s_waitcnt lgkmcnt(0)
	v_mul_f32_e32 v158, v5, v201
	v_fmac_f32_e32 v158, v4, v200
	v_fmac_f32_e32 v158, v6, v202
	v_fmac_f32_e32 v158, v7, v203
	ds_read_b128 v[200:203], v9 offset:3344
	v_add_f32_e32 v158, v157, v158
	s_waitcnt lgkmcnt(0)
	v_mul_f32_e32 v159, v154, v201
	v_fmac_f32_e32 v159, v228, v200
	v_fmac_f32_e32 v159, v155, v202
	v_fmac_f32_e32 v159, v156, v203
	ds_read_b128 v[200:203], v9 offset:3360
	v_add_f32_e32 v158, v158, v159
	s_waitcnt lgkmcnt(0)
	v_mul_f32_e32 v159, v252, v201
	v_fmac_f32_e32 v159, v146, v200
	v_fmac_f32_e32 v159, v253, v202
	v_fmac_f32_e32 v159, v227, v203
	ds_read_b128 v[200:203], v9 offset:3376
	v_add_f32_e32 v158, v158, v159
	s_waitcnt lgkmcnt(0)
	v_mul_f32_e32 v159, v147, v201
	v_fmac_f32_e32 v159, v145, v200
	v_fmac_f32_e32 v159, v230, v202
	v_fmac_f32_e32 v159, v231, v203
	v_add_f32_e32 v158, v158, v159
	v_min_f32_e32 v159, 0, v158
	v_mul_f32_e64 v158, |v158|, s18
	v_exp_f32_e32 v158, v158
	ds_read_b128 v[200:203], v9 offset:3456
	v_add_f32_e32 v158, 1.0, v158
	v_cmp_gt_f32_e32 vcc, s71, v158
	s_nop 1
	v_cndmask_b32_e64 v160, 0, 32, vcc
	v_ldexp_f32 v158, v158, v160
	v_log_f32_e32 v158, v158
	s_nop 0
	v_mul_f32_e32 v160, 0x3f317217, v158
	v_fma_f32 v160, v158, s48, -v160
	v_fmac_f32_e32 v160, 0x3377d1cf, v158
	v_fmac_f32_e32 v160, 0x3f317217, v158
	v_cmp_lt_f32_e64 s[0:1], |v158|, s49
	s_nop 1
	v_cndmask_b32_e64 v158, v158, v160, s[0:1]
	v_cndmask_b32_e32 v160, 0, v233, vcc
	v_sub_f32_e32 v158, v158, v160
	v_sub_f32_e32 v158, v159, v158
	v_mul_f32_e32 v199, 0x3d800000, v158
	v_fmac_f32_e32 v141, 0x3d800000, v158
	s_waitcnt lgkmcnt(0)
	v_mul_f32_e32 v158, v5, v201
	v_fmac_f32_e32 v158, v4, v200
	v_fmac_f32_e32 v158, v6, v202
	v_fmac_f32_e32 v158, v7, v203
	ds_read_b128 v[200:203], v9 offset:3472
	v_add_f32_e32 v158, v157, v158
	s_waitcnt lgkmcnt(0)
	v_mul_f32_e32 v159, v154, v201
	v_fmac_f32_e32 v159, v228, v200
	v_fmac_f32_e32 v159, v155, v202
	v_fmac_f32_e32 v159, v156, v203
	ds_read_b128 v[200:203], v9 offset:3488
	v_add_f32_e32 v158, v158, v159
	s_waitcnt lgkmcnt(0)
	v_mul_f32_e32 v159, v252, v201
	v_fmac_f32_e32 v159, v146, v200
	v_fmac_f32_e32 v159, v253, v202
	v_fmac_f32_e32 v159, v227, v203
	ds_read_b128 v[200:203], v9 offset:3504
	v_add_f32_e32 v158, v158, v159
	s_waitcnt lgkmcnt(0)
	v_mul_f32_e32 v159, v147, v201
	v_fmac_f32_e32 v159, v145, v200
	v_fmac_f32_e32 v159, v230, v202
	v_fmac_f32_e32 v159, v231, v203
	v_add_f32_e32 v158, v158, v159
	v_min_f32_e32 v159, 0, v158
	v_mul_f32_e64 v158, |v158|, s18
	v_exp_f32_e32 v158, v158
	ds_read_b128 v[202:205], v9 offset:3584
	v_add_f32_e32 v158, 1.0, v158
	v_cmp_gt_f32_e32 vcc, s71, v158
	s_nop 1
	v_cndmask_b32_e64 v160, 0, 32, vcc
	v_ldexp_f32 v158, v158, v160
	v_log_f32_e32 v158, v158
	s_nop 0
	v_mul_f32_e32 v160, 0x3f317217, v158
	v_fma_f32 v160, v158, s48, -v160
	v_fmac_f32_e32 v160, 0x3377d1cf, v158
	v_fmac_f32_e32 v160, 0x3f317217, v158
	v_cmp_lt_f32_e64 s[0:1], |v158|, s49
	s_nop 1
	v_cndmask_b32_e64 v158, v158, v160, s[0:1]
	v_cndmask_b32_e32 v160, 0, v233, vcc
	v_sub_f32_e32 v158, v158, v160
	v_sub_f32_e32 v158, v159, v158
	v_mul_f32_e32 v200, 0x3d800000, v158
	v_fmac_f32_e32 v141, 0x3d800000, v158
	s_waitcnt lgkmcnt(0)
	v_mul_f32_e32 v158, v5, v203
	v_fmac_f32_e32 v158, v4, v202
	v_fmac_f32_e32 v158, v6, v204
	v_fmac_f32_e32 v158, v7, v205
	ds_read_b128 v[202:205], v9 offset:3600
	v_add_f32_e32 v158, v157, v158
	s_waitcnt lgkmcnt(0)
	v_mul_f32_e32 v159, v154, v203
	v_fmac_f32_e32 v159, v228, v202
	v_fmac_f32_e32 v159, v155, v204
	v_fmac_f32_e32 v159, v156, v205
	ds_read_b128 v[202:205], v9 offset:3616
	v_add_f32_e32 v158, v158, v159
	s_waitcnt lgkmcnt(0)
	v_mul_f32_e32 v159, v252, v203
	v_fmac_f32_e32 v159, v146, v202
	v_fmac_f32_e32 v159, v253, v204
	v_fmac_f32_e32 v159, v227, v205
	ds_read_b128 v[202:205], v9 offset:3632
	v_add_f32_e32 v158, v158, v159
	s_waitcnt lgkmcnt(0)
	v_mul_f32_e32 v159, v147, v203
	v_fmac_f32_e32 v159, v145, v202
	v_fmac_f32_e32 v159, v230, v204
	v_fmac_f32_e32 v159, v231, v205
	v_add_f32_e32 v158, v158, v159
	v_min_f32_e32 v159, 0, v158
	v_mul_f32_e64 v158, |v158|, s18
	v_exp_f32_e32 v158, v158
	ds_read_b128 v[202:205], v9 offset:3712
	v_add_f32_e32 v158, 1.0, v158
	v_cmp_gt_f32_e32 vcc, s71, v158
	s_nop 1
	v_cndmask_b32_e64 v160, 0, 32, vcc
	v_ldexp_f32 v158, v158, v160
	v_log_f32_e32 v158, v158
	s_nop 0
	v_mul_f32_e32 v160, 0x3f317217, v158
	v_fma_f32 v160, v158, s48, -v160
	v_fmac_f32_e32 v160, 0x3377d1cf, v158
	v_fmac_f32_e32 v160, 0x3f317217, v158
	v_cmp_lt_f32_e64 s[0:1], |v158|, s49
	s_nop 1
	v_cndmask_b32_e64 v158, v158, v160, s[0:1]
	v_cndmask_b32_e32 v160, 0, v233, vcc
	v_sub_f32_e32 v158, v158, v160
	v_sub_f32_e32 v158, v159, v158
	v_mul_f32_e32 v201, 0x3d800000, v158
	v_fmac_f32_e32 v141, 0x3d800000, v158
	s_waitcnt lgkmcnt(0)
	v_mul_f32_e32 v158, v5, v203
	v_fmac_f32_e32 v158, v4, v202
	v_fmac_f32_e32 v158, v6, v204
	v_fmac_f32_e32 v158, v7, v205
	ds_read_b128 v[202:205], v9 offset:3728
	v_add_f32_e32 v158, v157, v158
	s_waitcnt lgkmcnt(0)
	v_mul_f32_e32 v159, v154, v203
	v_fmac_f32_e32 v159, v228, v202
	v_fmac_f32_e32 v159, v155, v204
	v_fmac_f32_e32 v159, v156, v205
	ds_read_b128 v[202:205], v9 offset:3744
	v_add_f32_e32 v158, v158, v159
	s_waitcnt lgkmcnt(0)
	v_mul_f32_e32 v159, v252, v203
	v_fmac_f32_e32 v159, v146, v202
	v_fmac_f32_e32 v159, v253, v204
	v_fmac_f32_e32 v159, v227, v205
	ds_read_b128 v[202:205], v9 offset:3760
	v_add_f32_e32 v158, v158, v159
	s_waitcnt lgkmcnt(0)
	v_mul_f32_e32 v159, v147, v203
	v_fmac_f32_e32 v159, v145, v202
	v_fmac_f32_e32 v159, v230, v204
	v_fmac_f32_e32 v159, v231, v205
	v_add_f32_e32 v158, v158, v159
	v_min_f32_e32 v159, 0, v158
	v_mul_f32_e64 v158, |v158|, s18
	v_exp_f32_e32 v158, v158
	ds_read_b128 v[204:207], v9 offset:3840
	v_add_f32_e32 v158, 1.0, v158
	v_cmp_gt_f32_e32 vcc, s71, v158
	s_nop 1
	v_cndmask_b32_e64 v160, 0, 32, vcc
	v_ldexp_f32 v158, v158, v160
	v_log_f32_e32 v158, v158
	s_nop 0
	v_mul_f32_e32 v160, 0x3f317217, v158
	v_fma_f32 v160, v158, s48, -v160
	v_fmac_f32_e32 v160, 0x3377d1cf, v158
	v_fmac_f32_e32 v160, 0x3f317217, v158
	v_cmp_lt_f32_e64 s[0:1], |v158|, s49
	s_nop 1
	v_cndmask_b32_e64 v158, v158, v160, s[0:1]
	v_cndmask_b32_e32 v160, 0, v233, vcc
	v_sub_f32_e32 v158, v158, v160
	v_sub_f32_e32 v158, v159, v158
	v_mul_f32_e32 v202, 0x3d800000, v158
	v_fmac_f32_e32 v141, 0x3d800000, v158
	s_waitcnt lgkmcnt(0)
	v_mul_f32_e32 v158, v5, v205
	v_fmac_f32_e32 v158, v4, v204
	v_fmac_f32_e32 v158, v6, v206
	v_fmac_f32_e32 v158, v7, v207
	ds_read_b128 v[204:207], v9 offset:3856
	v_add_f32_e32 v158, v157, v158
	s_waitcnt lgkmcnt(0)
	v_mul_f32_e32 v159, v154, v205
	v_fmac_f32_e32 v159, v228, v204
	v_fmac_f32_e32 v159, v155, v206
	v_fmac_f32_e32 v159, v156, v207
	ds_read_b128 v[204:207], v9 offset:3872
	v_add_f32_e32 v158, v158, v159
	s_waitcnt lgkmcnt(0)
	v_mul_f32_e32 v159, v252, v205
	v_fmac_f32_e32 v159, v146, v204
	v_fmac_f32_e32 v159, v253, v206
	v_fmac_f32_e32 v159, v227, v207
	ds_read_b128 v[204:207], v9 offset:3888
	v_add_f32_e32 v158, v158, v159
	s_waitcnt lgkmcnt(0)
	v_mul_f32_e32 v159, v147, v205
	v_fmac_f32_e32 v159, v145, v204
	v_fmac_f32_e32 v159, v230, v206
	v_fmac_f32_e32 v159, v231, v207
	v_add_f32_e32 v158, v158, v159
	v_min_f32_e32 v159, 0, v158
	v_mul_f32_e64 v158, |v158|, s18
	v_exp_f32_e32 v158, v158
	ds_read_b128 v[204:207], v9 offset:3968
	v_add_f32_e32 v158, 1.0, v158
	v_cmp_gt_f32_e32 vcc, s71, v158
	s_nop 1
	v_cndmask_b32_e64 v160, 0, 32, vcc
	v_ldexp_f32 v158, v158, v160
	v_log_f32_e32 v158, v158
	s_nop 0
	v_mul_f32_e32 v160, 0x3f317217, v158
	v_fma_f32 v160, v158, s48, -v160
	v_fmac_f32_e32 v160, 0x3377d1cf, v158
	v_fmac_f32_e32 v160, 0x3f317217, v158
	v_cmp_lt_f32_e64 s[0:1], |v158|, s49
	s_nop 1
	v_cndmask_b32_e64 v158, v158, v160, s[0:1]
	v_cndmask_b32_e32 v160, 0, v233, vcc
	v_sub_f32_e32 v158, v158, v160
	v_sub_f32_e32 v158, v159, v158
	v_mul_f32_e32 v203, 0x3d800000, v158
	v_fmac_f32_e32 v141, 0x3d800000, v158
	s_waitcnt lgkmcnt(0)
	v_mul_f32_e32 v158, v5, v205
	v_fmac_f32_e32 v158, v4, v204
	v_fmac_f32_e32 v158, v6, v206
	v_fmac_f32_e32 v158, v7, v207
	ds_read_b128 v[204:207], v9 offset:3984
	v_add_f32_e32 v158, v157, v158
	s_waitcnt lgkmcnt(0)
	v_mul_f32_e32 v159, v154, v205
	v_fmac_f32_e32 v159, v228, v204
	v_fmac_f32_e32 v159, v155, v206
	v_fmac_f32_e32 v159, v156, v207
	ds_read_b128 v[204:207], v9 offset:4000
	v_add_f32_e32 v158, v158, v159
	s_waitcnt lgkmcnt(0)
	v_mul_f32_e32 v159, v252, v205
	v_fmac_f32_e32 v159, v146, v204
	v_fmac_f32_e32 v159, v253, v206
	v_fmac_f32_e32 v159, v227, v207
	ds_read_b128 v[204:207], v9 offset:4016
	v_add_f32_e32 v158, v158, v159
	s_waitcnt lgkmcnt(0)
	v_mul_f32_e32 v159, v147, v205
	v_fmac_f32_e32 v159, v145, v204
	v_fmac_f32_e32 v159, v230, v206
	v_fmac_f32_e32 v159, v231, v207
	v_add_f32_e32 v158, v158, v159
	v_min_f32_e32 v159, 0, v158
	v_mul_f32_e64 v158, |v158|, s18
	v_exp_f32_e32 v158, v158
	ds_read_b128 v[206:209], v9 offset:4096
	v_add_f32_e32 v158, 1.0, v158
	v_cmp_gt_f32_e32 vcc, s71, v158
	s_nop 1
	v_cndmask_b32_e64 v160, 0, 32, vcc
	v_ldexp_f32 v158, v158, v160
	v_log_f32_e32 v158, v158
	s_nop 0
	v_mul_f32_e32 v160, 0x3f317217, v158
	v_fma_f32 v160, v158, s48, -v160
	v_fmac_f32_e32 v160, 0x3377d1cf, v158
	v_fmac_f32_e32 v160, 0x3f317217, v158
	v_cmp_lt_f32_e64 s[0:1], |v158|, s49
	s_nop 1
	v_cndmask_b32_e64 v158, v158, v160, s[0:1]
	v_cndmask_b32_e32 v160, 0, v233, vcc
	v_sub_f32_e32 v158, v158, v160
	v_sub_f32_e32 v158, v159, v158
	v_mul_f32_e32 v204, 0x3d800000, v158
	v_fmac_f32_e32 v141, 0x3d800000, v158
	s_waitcnt lgkmcnt(0)
	v_mul_f32_e32 v158, v5, v207
	v_fmac_f32_e32 v158, v4, v206
	v_fmac_f32_e32 v158, v6, v208
	v_fmac_f32_e32 v158, v7, v209
	ds_read_b128 v[206:209], v9 offset:4112
	v_add_f32_e32 v158, v157, v158
	s_waitcnt lgkmcnt(0)
	v_mul_f32_e32 v159, v154, v207
	v_fmac_f32_e32 v159, v228, v206
	v_fmac_f32_e32 v159, v155, v208
	v_fmac_f32_e32 v159, v156, v209
	ds_read_b128 v[206:209], v9 offset:4128
	v_add_f32_e32 v158, v158, v159
	s_waitcnt lgkmcnt(0)
	v_mul_f32_e32 v159, v252, v207
	v_fmac_f32_e32 v159, v146, v206
	v_fmac_f32_e32 v159, v253, v208
	v_fmac_f32_e32 v159, v227, v209
	ds_read_b128 v[206:209], v9 offset:4144
	v_add_f32_e32 v158, v158, v159
	s_waitcnt lgkmcnt(0)
	v_mul_f32_e32 v159, v147, v207
	v_fmac_f32_e32 v159, v145, v206
	v_fmac_f32_e32 v159, v230, v208
	v_fmac_f32_e32 v159, v231, v209
	v_add_f32_e32 v158, v158, v159
	v_min_f32_e32 v159, 0, v158
	v_mul_f32_e64 v158, |v158|, s18
	v_exp_f32_e32 v158, v158
	ds_read_b128 v[206:209], v9 offset:4224
	v_add_f32_e32 v158, 1.0, v158
	v_cmp_gt_f32_e32 vcc, s71, v158
	s_nop 1
	v_cndmask_b32_e64 v160, 0, 32, vcc
	v_ldexp_f32 v158, v158, v160
	v_log_f32_e32 v158, v158
	s_nop 0
	v_mul_f32_e32 v160, 0x3f317217, v158
	v_fma_f32 v160, v158, s48, -v160
	v_fmac_f32_e32 v160, 0x3377d1cf, v158
	v_fmac_f32_e32 v160, 0x3f317217, v158
	v_cmp_lt_f32_e64 s[0:1], |v158|, s49
	s_nop 1
	v_cndmask_b32_e64 v158, v158, v160, s[0:1]
	v_cndmask_b32_e32 v160, 0, v233, vcc
	v_sub_f32_e32 v158, v158, v160
	v_sub_f32_e32 v158, v159, v158
	v_mul_f32_e32 v205, 0x3d800000, v158
	v_fmac_f32_e32 v141, 0x3d800000, v158
	s_waitcnt lgkmcnt(0)
	v_mul_f32_e32 v158, v5, v207
	v_fmac_f32_e32 v158, v4, v206
	v_fmac_f32_e32 v158, v6, v208
	v_fmac_f32_e32 v158, v7, v209
	ds_read_b128 v[206:209], v9 offset:4240
	v_add_f32_e32 v158, v157, v158
	s_waitcnt lgkmcnt(0)
	v_mul_f32_e32 v159, v154, v207
	v_fmac_f32_e32 v159, v228, v206
	v_fmac_f32_e32 v159, v155, v208
	v_fmac_f32_e32 v159, v156, v209
	ds_read_b128 v[206:209], v9 offset:4256
	v_add_f32_e32 v158, v158, v159
	s_waitcnt lgkmcnt(0)
	v_mul_f32_e32 v159, v252, v207
	v_fmac_f32_e32 v159, v146, v206
	v_fmac_f32_e32 v159, v253, v208
	v_fmac_f32_e32 v159, v227, v209
	ds_read_b128 v[206:209], v9 offset:4272
	v_add_f32_e32 v158, v158, v159
	s_waitcnt lgkmcnt(0)
	v_mul_f32_e32 v159, v147, v207
	v_fmac_f32_e32 v159, v145, v206
	v_fmac_f32_e32 v159, v230, v208
	v_fmac_f32_e32 v159, v231, v209
	v_add_f32_e32 v158, v158, v159
	v_min_f32_e32 v159, 0, v158
	v_mul_f32_e64 v158, |v158|, s18
	v_exp_f32_e32 v158, v158
	ds_read_b128 v[208:211], v9 offset:4352
	v_add_f32_e32 v158, 1.0, v158
	v_cmp_gt_f32_e32 vcc, s71, v158
	s_nop 1
	v_cndmask_b32_e64 v160, 0, 32, vcc
	v_ldexp_f32 v158, v158, v160
	v_log_f32_e32 v158, v158
	s_nop 0
	v_mul_f32_e32 v160, 0x3f317217, v158
	v_fma_f32 v160, v158, s48, -v160
	v_fmac_f32_e32 v160, 0x3377d1cf, v158
	v_fmac_f32_e32 v160, 0x3f317217, v158
	v_cmp_lt_f32_e64 s[0:1], |v158|, s49
	s_nop 1
	v_cndmask_b32_e64 v158, v158, v160, s[0:1]
	v_cndmask_b32_e32 v160, 0, v233, vcc
	v_sub_f32_e32 v158, v158, v160
	v_sub_f32_e32 v158, v159, v158
	v_mul_f32_e32 v207, 0x3d800000, v158
	v_fmac_f32_e32 v141, 0x3d800000, v158
	s_waitcnt lgkmcnt(0)
	v_mul_f32_e32 v158, v5, v209
	v_fmac_f32_e32 v158, v4, v208
	v_fmac_f32_e32 v158, v6, v210
	v_fmac_f32_e32 v158, v7, v211
	ds_read_b128 v[208:211], v9 offset:4368
	v_add_f32_e32 v158, v157, v158
	s_waitcnt lgkmcnt(0)
	v_mul_f32_e32 v159, v154, v209
	v_fmac_f32_e32 v159, v228, v208
	v_fmac_f32_e32 v159, v155, v210
	v_fmac_f32_e32 v159, v156, v211
	ds_read_b128 v[208:211], v9 offset:4384
	v_add_f32_e32 v158, v158, v159
	s_waitcnt lgkmcnt(0)
	v_mul_f32_e32 v159, v252, v209
	v_fmac_f32_e32 v159, v146, v208
	v_fmac_f32_e32 v159, v253, v210
	v_fmac_f32_e32 v159, v227, v211
	ds_read_b128 v[208:211], v9 offset:4400
	v_add_f32_e32 v158, v158, v159
	s_waitcnt lgkmcnt(0)
	v_mul_f32_e32 v159, v147, v209
	v_fmac_f32_e32 v159, v145, v208
	v_fmac_f32_e32 v159, v230, v210
	v_fmac_f32_e32 v159, v231, v211
	v_add_f32_e32 v158, v158, v159
	v_min_f32_e32 v159, 0, v158
	v_mul_f32_e64 v158, |v158|, s18
	v_exp_f32_e32 v158, v158
	s_nop 0
	v_add_f32_e32 v158, 1.0, v158
	v_cmp_gt_f32_e32 vcc, s71, v158
	s_nop 1
	v_cndmask_b32_e64 v160, 0, 32, vcc
	v_ldexp_f32 v158, v158, v160
	v_log_f32_e32 v158, v158
	s_nop 0
	v_mul_f32_e32 v160, 0x3f317217, v158
	v_fma_f32 v160, v158, s48, -v160
	v_fmac_f32_e32 v160, 0x3377d1cf, v158
	v_fmac_f32_e32 v160, 0x3f317217, v158
	v_cmp_lt_f32_e64 s[0:1], |v158|, s49
	s_nop 1
	v_cndmask_b32_e64 v158, v158, v160, s[0:1]
	v_cndmask_b32_e32 v160, 0, v233, vcc
	v_sub_f32_e32 v158, v158, v160
	v_sub_f32_e32 v158, v159, v158
	v_mul_f32_e32 v210, 0x3d800000, v158
	v_fmac_f32_e32 v141, 0x3d800000, v158
	v_mul_f32_e32 v158, v5, v213
	v_fmac_f32_e32 v158, v4, v212
	v_fmac_f32_e32 v158, v6, v214
	v_fmac_f32_e32 v158, v7, v215
	ds_read_b128 v[212:215], v9 offset:4496
	v_add_f32_e32 v158, v157, v158
	s_waitcnt lgkmcnt(0)
	v_mul_f32_e32 v159, v154, v213
	v_fmac_f32_e32 v159, v228, v212
	v_fmac_f32_e32 v159, v155, v214
	v_fmac_f32_e32 v159, v156, v215
	ds_read_b128 v[212:215], v9 offset:4512
	v_add_f32_e32 v158, v158, v159
	s_waitcnt lgkmcnt(0)
	v_mul_f32_e32 v159, v252, v213
	v_fmac_f32_e32 v159, v146, v212
	v_fmac_f32_e32 v159, v253, v214
	v_fmac_f32_e32 v159, v227, v215
	ds_read_b128 v[212:215], v9 offset:4528
	v_add_f32_e32 v158, v158, v159
	s_waitcnt lgkmcnt(0)
	v_mul_f32_e32 v159, v147, v213
	v_fmac_f32_e32 v159, v145, v212
	v_fmac_f32_e32 v159, v230, v214
	v_fmac_f32_e32 v159, v231, v215
	v_add_f32_e32 v158, v158, v159
	v_min_f32_e32 v159, 0, v158
	v_mul_f32_e64 v158, |v158|, s18
	v_exp_f32_e32 v158, v158
	ds_read_b128 v[214:217], v9 offset:4608
	v_add_f32_e32 v158, 1.0, v158
	v_cmp_gt_f32_e32 vcc, s71, v158
	s_nop 1
	v_cndmask_b32_e64 v160, 0, 32, vcc
	v_ldexp_f32 v158, v158, v160
	v_log_f32_e32 v158, v158
	s_nop 0
	v_mul_f32_e32 v160, 0x3f317217, v158
	v_fma_f32 v160, v158, s48, -v160
	v_fmac_f32_e32 v160, 0x3377d1cf, v158
	v_fmac_f32_e32 v160, 0x3f317217, v158
	v_cmp_lt_f32_e64 s[0:1], |v158|, s49
	s_nop 1
	v_cndmask_b32_e64 v158, v158, v160, s[0:1]
	v_cndmask_b32_e32 v160, 0, v233, vcc
	v_sub_f32_e32 v158, v158, v160
	v_sub_f32_e32 v158, v159, v158
	v_mul_f32_e32 v212, 0x3d800000, v158
	v_fmac_f32_e32 v141, 0x3d800000, v158
	s_waitcnt lgkmcnt(0)
	v_mul_f32_e32 v158, v5, v215
	v_fmac_f32_e32 v158, v4, v214
	v_fmac_f32_e32 v158, v6, v216
	v_fmac_f32_e32 v158, v7, v217
	ds_read_b128 v[214:217], v9 offset:4624
	v_add_f32_e32 v158, v157, v158
	s_waitcnt lgkmcnt(0)
	v_mul_f32_e32 v159, v154, v215
	v_fmac_f32_e32 v159, v228, v214
	v_fmac_f32_e32 v159, v155, v216
	v_fmac_f32_e32 v159, v156, v217
	ds_read_b128 v[214:217], v9 offset:4640
	v_add_f32_e32 v158, v158, v159
	s_waitcnt lgkmcnt(0)
	v_mul_f32_e32 v159, v252, v215
	v_fmac_f32_e32 v159, v146, v214
	v_fmac_f32_e32 v159, v253, v216
	v_fmac_f32_e32 v159, v227, v217
	ds_read_b128 v[214:217], v9 offset:4656
	v_add_f32_e32 v158, v158, v159
	s_waitcnt lgkmcnt(0)
	v_mul_f32_e32 v159, v147, v215
	v_fmac_f32_e32 v159, v145, v214
	v_fmac_f32_e32 v159, v230, v216
	v_fmac_f32_e32 v159, v231, v217
	v_add_f32_e32 v158, v158, v159
	v_min_f32_e32 v159, 0, v158
	v_mul_f32_e64 v158, |v158|, s18
	v_exp_f32_e32 v158, v158
	ds_read_b128 v[214:217], v9 offset:4736
	v_add_f32_e32 v158, 1.0, v158
	v_cmp_gt_f32_e32 vcc, s71, v158
	s_nop 1
	v_cndmask_b32_e64 v160, 0, 32, vcc
	v_ldexp_f32 v158, v158, v160
	v_log_f32_e32 v158, v158
	s_nop 0
	v_mul_f32_e32 v160, 0x3f317217, v158
	v_fma_f32 v160, v158, s48, -v160
	v_fmac_f32_e32 v160, 0x3377d1cf, v158
	v_fmac_f32_e32 v160, 0x3f317217, v158
	v_cmp_lt_f32_e64 s[0:1], |v158|, s49
	s_nop 1
	v_cndmask_b32_e64 v158, v158, v160, s[0:1]
	v_cndmask_b32_e32 v160, 0, v233, vcc
	v_sub_f32_e32 v158, v158, v160
	v_sub_f32_e32 v158, v159, v158
	v_mul_f32_e32 v206, 0x3d800000, v158
	v_fmac_f32_e32 v141, 0x3d800000, v158
	s_waitcnt lgkmcnt(0)
	v_mul_f32_e32 v158, v5, v215
	v_fmac_f32_e32 v158, v4, v214
	v_fmac_f32_e32 v158, v6, v216
	v_fmac_f32_e32 v158, v7, v217
	ds_read_b128 v[214:217], v9 offset:4752
	v_add_f32_e32 v158, v157, v158
	s_waitcnt lgkmcnt(0)
	v_mul_f32_e32 v159, v154, v215
	v_fmac_f32_e32 v159, v228, v214
	v_fmac_f32_e32 v159, v155, v216
	v_fmac_f32_e32 v159, v156, v217
	ds_read_b128 v[214:217], v9 offset:4768
	v_add_f32_e32 v158, v158, v159
	s_waitcnt lgkmcnt(0)
	v_mul_f32_e32 v159, v252, v215
	v_fmac_f32_e32 v159, v146, v214
	v_fmac_f32_e32 v159, v253, v216
	v_fmac_f32_e32 v159, v227, v217
	ds_read_b128 v[214:217], v9 offset:4784
	v_add_f32_e32 v158, v158, v159
	s_waitcnt lgkmcnt(0)
	v_mul_f32_e32 v159, v147, v215
	v_fmac_f32_e32 v159, v145, v214
	v_fmac_f32_e32 v159, v230, v216
	v_fmac_f32_e32 v159, v231, v217
	v_add_f32_e32 v158, v158, v159
	v_min_f32_e32 v159, 0, v158
	v_mul_f32_e64 v158, |v158|, s18
	v_exp_f32_e32 v158, v158
	ds_read_b128 v[214:217], v9 offset:4864
	v_add_f32_e32 v158, 1.0, v158
	v_cmp_gt_f32_e32 vcc, s71, v158
	s_nop 1
	v_cndmask_b32_e64 v160, 0, 32, vcc
	v_ldexp_f32 v158, v158, v160
	v_log_f32_e32 v158, v158
	s_nop 0
	v_mul_f32_e32 v160, 0x3f317217, v158
	v_fma_f32 v160, v158, s48, -v160
	v_fmac_f32_e32 v160, 0x3377d1cf, v158
	v_fmac_f32_e32 v160, 0x3f317217, v158
	v_cmp_lt_f32_e64 s[0:1], |v158|, s49
	s_nop 1
	v_cndmask_b32_e64 v158, v158, v160, s[0:1]
	v_cndmask_b32_e32 v160, 0, v233, vcc
	v_sub_f32_e32 v158, v158, v160
	v_sub_f32_e32 v158, v159, v158
	v_mul_f32_e32 v209, 0x3d800000, v158
	v_fmac_f32_e32 v141, 0x3d800000, v158
	s_waitcnt lgkmcnt(0)
	v_mul_f32_e32 v158, v5, v215
	v_fmac_f32_e32 v158, v4, v214
	v_fmac_f32_e32 v158, v6, v216
	v_fmac_f32_e32 v158, v7, v217
	ds_read_b128 v[214:217], v9 offset:4880
	v_add_f32_e32 v158, v157, v158
	s_waitcnt lgkmcnt(0)
	v_mul_f32_e32 v159, v154, v215
	v_fmac_f32_e32 v159, v228, v214
	v_fmac_f32_e32 v159, v155, v216
	v_fmac_f32_e32 v159, v156, v217
	ds_read_b128 v[214:217], v9 offset:4896
	v_add_f32_e32 v158, v158, v159
	s_waitcnt lgkmcnt(0)
	v_mul_f32_e32 v159, v252, v215
	v_fmac_f32_e32 v159, v146, v214
	v_fmac_f32_e32 v159, v253, v216
	v_fmac_f32_e32 v159, v227, v217
	ds_read_b128 v[214:217], v9 offset:4912
	v_add_f32_e32 v158, v158, v159
	s_waitcnt lgkmcnt(0)
	v_mul_f32_e32 v159, v147, v215
	v_fmac_f32_e32 v159, v145, v214
	v_fmac_f32_e32 v159, v230, v216
	v_fmac_f32_e32 v159, v231, v217
	v_add_f32_e32 v158, v158, v159
	v_min_f32_e32 v159, 0, v158
	v_mul_f32_e64 v158, |v158|, s18
	v_exp_f32_e32 v158, v158
	s_nop 0
	v_add_f32_e32 v158, 1.0, v158
	v_cmp_gt_f32_e32 vcc, s71, v158
	s_nop 1
	v_cndmask_b32_e64 v160, 0, 32, vcc
	v_ldexp_f32 v158, v158, v160
	v_log_f32_e32 v158, v158
	s_nop 0
	v_mul_f32_e32 v160, 0x3f317217, v158
	v_fma_f32 v160, v158, s48, -v160
	v_fmac_f32_e32 v160, 0x3377d1cf, v158
	v_fmac_f32_e32 v160, 0x3f317217, v158
	v_cmp_lt_f32_e64 s[0:1], |v158|, s49
	s_nop 1
	v_cndmask_b32_e64 v158, v158, v160, s[0:1]
	v_cndmask_b32_e32 v160, 0, v233, vcc
	v_sub_f32_e32 v158, v158, v160
	v_sub_f32_e32 v158, v159, v158
	v_mul_f32_e32 v214, 0x3d800000, v158
	v_fmac_f32_e32 v141, 0x3d800000, v158
	v_mul_f32_e32 v158, v5, v235
	v_fmac_f32_e32 v158, v4, v234
	v_fmac_f32_e32 v158, v6, v236
	v_fmac_f32_e32 v158, v7, v237
	ds_read_b128 v[234:237], v9 offset:5008
	v_add_f32_e32 v158, v157, v158
	s_waitcnt lgkmcnt(0)
	v_mul_f32_e32 v159, v154, v235
	v_fmac_f32_e32 v159, v228, v234
	v_fmac_f32_e32 v159, v155, v236
	v_fmac_f32_e32 v159, v156, v237
	ds_read_b128 v[234:237], v9 offset:5024
	v_add_f32_e32 v158, v158, v159
	s_waitcnt lgkmcnt(0)
	v_mul_f32_e32 v159, v252, v235
	v_fmac_f32_e32 v159, v146, v234
	v_fmac_f32_e32 v159, v253, v236
	v_fmac_f32_e32 v159, v227, v237
	ds_read_b128 v[234:237], v9 offset:5040
	v_add_f32_e32 v158, v158, v159
	s_waitcnt lgkmcnt(0)
	v_mul_f32_e32 v159, v147, v235
	v_fmac_f32_e32 v159, v145, v234
	v_fmac_f32_e32 v159, v230, v236
	v_fmac_f32_e32 v159, v231, v237
	v_add_f32_e32 v158, v158, v159
	v_min_f32_e32 v159, 0, v158
	v_mul_f32_e64 v158, |v158|, s18
	v_exp_f32_e32 v158, v158
	ds_read_b128 v[234:237], v9 offset:5120
	v_add_f32_e32 v158, 1.0, v158
	v_cmp_gt_f32_e32 vcc, s71, v158
	s_nop 1
	v_cndmask_b32_e64 v160, 0, 32, vcc
	v_ldexp_f32 v158, v158, v160
	v_log_f32_e32 v158, v158
	s_nop 0
	v_mul_f32_e32 v160, 0x3f317217, v158
	v_fma_f32 v160, v158, s48, -v160
	v_fmac_f32_e32 v160, 0x3377d1cf, v158
	v_fmac_f32_e32 v160, 0x3f317217, v158
	v_cmp_lt_f32_e64 s[0:1], |v158|, s49
	s_nop 1
	v_cndmask_b32_e64 v158, v158, v160, s[0:1]
	v_cndmask_b32_e32 v160, 0, v233, vcc
	v_sub_f32_e32 v158, v158, v160
	v_sub_f32_e32 v158, v159, v158
	v_mul_f32_e32 v216, 0x3d800000, v158
	v_fmac_f32_e32 v141, 0x3d800000, v158
	s_waitcnt lgkmcnt(0)
	v_mul_f32_e32 v158, v5, v235
	v_fmac_f32_e32 v158, v4, v234
	v_fmac_f32_e32 v158, v6, v236
	v_fmac_f32_e32 v158, v7, v237
	ds_read_b128 v[234:237], v9 offset:5136
	v_add_f32_e32 v158, v157, v158
	s_waitcnt lgkmcnt(0)
	v_mul_f32_e32 v159, v154, v235
	v_fmac_f32_e32 v159, v228, v234
	v_fmac_f32_e32 v159, v155, v236
	v_fmac_f32_e32 v159, v156, v237
	ds_read_b128 v[234:237], v9 offset:5152
	v_add_f32_e32 v158, v158, v159
	s_waitcnt lgkmcnt(0)
	v_mul_f32_e32 v159, v252, v235
	v_fmac_f32_e32 v159, v146, v234
	v_fmac_f32_e32 v159, v253, v236
	v_fmac_f32_e32 v159, v227, v237
	ds_read_b128 v[234:237], v9 offset:5168
	v_add_f32_e32 v158, v158, v159
	s_waitcnt lgkmcnt(0)
	v_mul_f32_e32 v159, v147, v235
	v_fmac_f32_e32 v159, v145, v234
	v_fmac_f32_e32 v159, v230, v236
	v_fmac_f32_e32 v159, v231, v237
	v_add_f32_e32 v158, v158, v159
	v_min_f32_e32 v159, 0, v158
	v_mul_f32_e64 v158, |v158|, s18
	v_exp_f32_e32 v158, v158
	ds_read_b128 v[234:237], v9 offset:5248
	v_add_f32_e32 v158, 1.0, v158
	v_cmp_gt_f32_e32 vcc, s71, v158
	s_nop 1
	v_cndmask_b32_e64 v160, 0, 32, vcc
	v_ldexp_f32 v158, v158, v160
	v_log_f32_e32 v158, v158
	s_nop 0
	v_mul_f32_e32 v160, 0x3f317217, v158
	v_fma_f32 v160, v158, s48, -v160
	v_fmac_f32_e32 v160, 0x3377d1cf, v158
	v_fmac_f32_e32 v160, 0x3f317217, v158
	v_cmp_lt_f32_e64 s[0:1], |v158|, s49
	s_nop 1
	v_cndmask_b32_e64 v158, v158, v160, s[0:1]
	v_cndmask_b32_e32 v160, 0, v233, vcc
	v_sub_f32_e32 v158, v158, v160
	v_sub_f32_e32 v158, v159, v158
	v_mul_f32_e32 v208, 0x3d800000, v158
	v_fmac_f32_e32 v141, 0x3d800000, v158
	s_waitcnt lgkmcnt(0)
	v_mul_f32_e32 v158, v5, v235
	v_fmac_f32_e32 v158, v4, v234
	v_fmac_f32_e32 v158, v6, v236
	v_fmac_f32_e32 v158, v7, v237
	ds_read_b128 v[234:237], v9 offset:5264
	v_add_f32_e32 v158, v157, v158
	s_waitcnt lgkmcnt(0)
	v_mul_f32_e32 v159, v154, v235
	v_fmac_f32_e32 v159, v228, v234
	v_fmac_f32_e32 v159, v155, v236
	v_fmac_f32_e32 v159, v156, v237
	ds_read_b128 v[234:237], v9 offset:5280
	v_add_f32_e32 v158, v158, v159
	s_waitcnt lgkmcnt(0)
	v_mul_f32_e32 v159, v252, v235
	v_fmac_f32_e32 v159, v146, v234
	v_fmac_f32_e32 v159, v253, v236
	v_fmac_f32_e32 v159, v227, v237
	ds_read_b128 v[234:237], v9 offset:5296
	v_add_f32_e32 v158, v158, v159
	s_waitcnt lgkmcnt(0)
	v_mul_f32_e32 v159, v147, v235
	v_fmac_f32_e32 v159, v145, v234
	v_fmac_f32_e32 v159, v230, v236
	v_fmac_f32_e32 v159, v231, v237
	v_add_f32_e32 v158, v158, v159
	v_min_f32_e32 v159, 0, v158
	v_mul_f32_e64 v158, |v158|, s18
	v_exp_f32_e32 v158, v158
	ds_read_b128 v[234:237], v9 offset:5376
	v_add_f32_e32 v158, 1.0, v158
	v_cmp_gt_f32_e32 vcc, s71, v158
	s_nop 1
	v_cndmask_b32_e64 v160, 0, 32, vcc
	v_ldexp_f32 v158, v158, v160
	v_log_f32_e32 v158, v158
	s_nop 0
	v_mul_f32_e32 v160, 0x3f317217, v158
	v_fma_f32 v160, v158, s48, -v160
	v_fmac_f32_e32 v160, 0x3377d1cf, v158
	v_fmac_f32_e32 v160, 0x3f317217, v158
	v_cmp_lt_f32_e64 s[0:1], |v158|, s49
	s_nop 1
	v_cndmask_b32_e64 v158, v158, v160, s[0:1]
	v_cndmask_b32_e32 v160, 0, v233, vcc
	v_sub_f32_e32 v158, v158, v160
	v_sub_f32_e32 v158, v159, v158
	v_mul_f32_e32 v213, 0x3d800000, v158
	v_fmac_f32_e32 v141, 0x3d800000, v158
	s_waitcnt lgkmcnt(0)
	v_mul_f32_e32 v158, v5, v235
	v_fmac_f32_e32 v158, v4, v234
	v_fmac_f32_e32 v158, v6, v236
	v_fmac_f32_e32 v158, v7, v237
	ds_read_b128 v[234:237], v9 offset:5392
	v_add_f32_e32 v158, v157, v158
	s_waitcnt lgkmcnt(0)
	v_mul_f32_e32 v159, v154, v235
	v_fmac_f32_e32 v159, v228, v234
	v_fmac_f32_e32 v159, v155, v236
	v_fmac_f32_e32 v159, v156, v237
	ds_read_b128 v[234:237], v9 offset:5408
	v_add_f32_e32 v158, v158, v159
	s_waitcnt lgkmcnt(0)
	v_mul_f32_e32 v159, v252, v235
	v_fmac_f32_e32 v159, v146, v234
	v_fmac_f32_e32 v159, v253, v236
	v_fmac_f32_e32 v159, v227, v237
	ds_read_b128 v[234:237], v9 offset:5424
	v_add_f32_e32 v158, v158, v159
	s_waitcnt lgkmcnt(0)
	v_mul_f32_e32 v159, v147, v235
	v_fmac_f32_e32 v159, v145, v234
	v_fmac_f32_e32 v159, v230, v236
	v_fmac_f32_e32 v159, v231, v237
	v_add_f32_e32 v158, v158, v159
	v_min_f32_e32 v159, 0, v158
	v_mul_f32_e64 v158, |v158|, s18
	v_exp_f32_e32 v158, v158
	ds_read_b128 v[236:239], v9 offset:5504
	v_add_f32_e32 v158, 1.0, v158
	v_cmp_gt_f32_e32 vcc, s71, v158
	s_nop 1
	v_cndmask_b32_e64 v160, 0, 32, vcc
	v_ldexp_f32 v158, v158, v160
	v_log_f32_e32 v158, v158
	s_nop 0
	v_mul_f32_e32 v160, 0x3f317217, v158
	v_fma_f32 v160, v158, s48, -v160
	v_fmac_f32_e32 v160, 0x3377d1cf, v158
	v_fmac_f32_e32 v160, 0x3f317217, v158
	v_cmp_lt_f32_e64 s[0:1], |v158|, s49
	s_nop 1
	v_cndmask_b32_e64 v158, v158, v160, s[0:1]
	v_cndmask_b32_e32 v160, 0, v233, vcc
	v_sub_f32_e32 v158, v158, v160
	v_sub_f32_e32 v158, v159, v158
	v_mul_f32_e32 v234, 0x3d800000, v158
	v_fmac_f32_e32 v141, 0x3d800000, v158
	s_waitcnt lgkmcnt(0)
	v_mul_f32_e32 v158, v5, v237
	v_fmac_f32_e32 v158, v4, v236
	v_fmac_f32_e32 v158, v6, v238
	v_fmac_f32_e32 v158, v7, v239
	ds_read_b128 v[236:239], v9 offset:5520
	v_add_f32_e32 v158, v157, v158
	s_waitcnt lgkmcnt(0)
	v_mul_f32_e32 v159, v154, v237
	v_fmac_f32_e32 v159, v228, v236
	v_fmac_f32_e32 v159, v155, v238
	v_fmac_f32_e32 v159, v156, v239
	ds_read_b128 v[236:239], v9 offset:5536
	v_add_f32_e32 v158, v158, v159
	s_waitcnt lgkmcnt(0)
	v_mul_f32_e32 v159, v252, v237
	v_fmac_f32_e32 v159, v146, v236
	v_fmac_f32_e32 v159, v253, v238
	v_fmac_f32_e32 v159, v227, v239
	ds_read_b128 v[236:239], v9 offset:5552
	v_add_f32_e32 v158, v158, v159
	s_waitcnt lgkmcnt(0)
	v_mul_f32_e32 v159, v147, v237
	v_fmac_f32_e32 v159, v145, v236
	v_fmac_f32_e32 v159, v230, v238
	v_fmac_f32_e32 v159, v231, v239
	v_add_f32_e32 v158, v158, v159
	v_min_f32_e32 v159, 0, v158
	v_mul_f32_e64 v158, |v158|, s18
	v_exp_f32_e32 v158, v158
	ds_read_b128 v[238:241], v9 offset:5632
	v_add_f32_e32 v158, 1.0, v158
	v_cmp_gt_f32_e32 vcc, s71, v158
	s_nop 1
	v_cndmask_b32_e64 v160, 0, 32, vcc
	v_ldexp_f32 v158, v158, v160
	v_log_f32_e32 v158, v158
	s_nop 0
	v_mul_f32_e32 v160, 0x3f317217, v158
	v_fma_f32 v160, v158, s48, -v160
	v_fmac_f32_e32 v160, 0x3377d1cf, v158
	v_fmac_f32_e32 v160, 0x3f317217, v158
	v_cmp_lt_f32_e64 s[0:1], |v158|, s49
	s_nop 1
	v_cndmask_b32_e64 v158, v158, v160, s[0:1]
	v_cndmask_b32_e32 v160, 0, v233, vcc
	v_sub_f32_e32 v158, v158, v160
	v_sub_f32_e32 v158, v159, v158
	v_mul_f32_e32 v236, 0x3d800000, v158
	v_fmac_f32_e32 v141, 0x3d800000, v158
	s_waitcnt lgkmcnt(0)
	v_mul_f32_e32 v158, v5, v239
	v_fmac_f32_e32 v158, v4, v238
	v_fmac_f32_e32 v158, v6, v240
	v_fmac_f32_e32 v158, v7, v241
	ds_read_b128 v[238:241], v9 offset:5648
	v_add_f32_e32 v158, v157, v158
	s_waitcnt lgkmcnt(0)
	v_mul_f32_e32 v159, v154, v239
	v_fmac_f32_e32 v159, v228, v238
	v_fmac_f32_e32 v159, v155, v240
	v_fmac_f32_e32 v159, v156, v241
	ds_read_b128 v[238:241], v9 offset:5664
	v_add_f32_e32 v158, v158, v159
	s_waitcnt lgkmcnt(0)
	v_mul_f32_e32 v159, v252, v239
	v_fmac_f32_e32 v159, v146, v238
	v_fmac_f32_e32 v159, v253, v240
	v_fmac_f32_e32 v159, v227, v241
	ds_read_b128 v[238:241], v9 offset:5680
	v_add_f32_e32 v158, v158, v159
	s_waitcnt lgkmcnt(0)
	v_mul_f32_e32 v159, v147, v239
	v_fmac_f32_e32 v159, v145, v238
	v_fmac_f32_e32 v159, v230, v240
	v_fmac_f32_e32 v159, v231, v241
	v_add_f32_e32 v158, v158, v159
	v_min_f32_e32 v159, 0, v158
	v_mul_f32_e64 v158, |v158|, s18
	v_exp_f32_e32 v158, v158
	ds_read_b128 v[238:241], v9 offset:5760
	v_add_f32_e32 v158, 1.0, v158
	v_cmp_gt_f32_e32 vcc, s71, v158
	s_nop 1
	v_cndmask_b32_e64 v160, 0, 32, vcc
	v_ldexp_f32 v158, v158, v160
	v_log_f32_e32 v158, v158
	s_nop 0
	v_mul_f32_e32 v160, 0x3f317217, v158
	v_fma_f32 v160, v158, s48, -v160
	v_fmac_f32_e32 v160, 0x3377d1cf, v158
	v_fmac_f32_e32 v160, 0x3f317217, v158
	v_cmp_lt_f32_e64 s[0:1], |v158|, s49
	s_nop 1
	v_cndmask_b32_e64 v158, v158, v160, s[0:1]
	v_cndmask_b32_e32 v160, 0, v233, vcc
	v_sub_f32_e32 v158, v158, v160
	v_sub_f32_e32 v158, v159, v158
	v_mul_f32_e32 v211, 0x3d800000, v158
	v_fmac_f32_e32 v141, 0x3d800000, v158
	s_waitcnt lgkmcnt(0)
	v_mul_f32_e32 v158, v5, v239
	v_fmac_f32_e32 v158, v4, v238
	v_fmac_f32_e32 v158, v6, v240
	v_fmac_f32_e32 v158, v7, v241
	ds_read_b128 v[238:241], v9 offset:5776
	v_add_f32_e32 v158, v157, v158
	s_waitcnt lgkmcnt(0)
	v_mul_f32_e32 v159, v154, v239
	v_fmac_f32_e32 v159, v228, v238
	v_fmac_f32_e32 v159, v155, v240
	v_fmac_f32_e32 v159, v156, v241
	ds_read_b128 v[238:241], v9 offset:5792
	v_add_f32_e32 v158, v158, v159
	s_waitcnt lgkmcnt(0)
	v_mul_f32_e32 v159, v252, v239
	v_fmac_f32_e32 v159, v146, v238
	v_fmac_f32_e32 v159, v253, v240
	v_fmac_f32_e32 v159, v227, v241
	ds_read_b128 v[238:241], v9 offset:5808
	v_add_f32_e32 v158, v158, v159
	s_waitcnt lgkmcnt(0)
	v_mul_f32_e32 v159, v147, v239
	v_fmac_f32_e32 v159, v145, v238
	v_fmac_f32_e32 v159, v230, v240
	v_fmac_f32_e32 v159, v231, v241
	v_add_f32_e32 v158, v158, v159
	v_min_f32_e32 v159, 0, v158
	v_mul_f32_e64 v158, |v158|, s18
	v_exp_f32_e32 v158, v158
	ds_read_b128 v[238:241], v9 offset:5888
	v_add_f32_e32 v158, 1.0, v158
	v_cmp_gt_f32_e32 vcc, s71, v158
	s_nop 1
	v_cndmask_b32_e64 v160, 0, 32, vcc
	v_ldexp_f32 v158, v158, v160
	v_log_f32_e32 v158, v158
	s_nop 0
	v_mul_f32_e32 v160, 0x3f317217, v158
	v_fma_f32 v160, v158, s48, -v160
	v_fmac_f32_e32 v160, 0x3377d1cf, v158
	v_fmac_f32_e32 v160, 0x3f317217, v158
	v_cmp_lt_f32_e64 s[0:1], |v158|, s49
	s_nop 1
	v_cndmask_b32_e64 v158, v158, v160, s[0:1]
	v_cndmask_b32_e32 v160, 0, v233, vcc
	v_sub_f32_e32 v158, v158, v160
	v_sub_f32_e32 v158, v159, v158
	v_mul_f32_e32 v217, 0x3d800000, v158
	v_fmac_f32_e32 v141, 0x3d800000, v158
	s_waitcnt lgkmcnt(0)
	v_mul_f32_e32 v158, v5, v239
	v_fmac_f32_e32 v158, v4, v238
	v_fmac_f32_e32 v158, v6, v240
	v_fmac_f32_e32 v158, v7, v241
	ds_read_b128 v[238:241], v9 offset:5904
	v_add_f32_e32 v158, v157, v158
	s_waitcnt lgkmcnt(0)
	v_mul_f32_e32 v159, v154, v239
	v_fmac_f32_e32 v159, v228, v238
	v_fmac_f32_e32 v159, v155, v240
	v_fmac_f32_e32 v159, v156, v241
	ds_read_b128 v[238:241], v9 offset:5920
	v_add_f32_e32 v158, v158, v159
	s_waitcnt lgkmcnt(0)
	v_mul_f32_e32 v159, v252, v239
	v_fmac_f32_e32 v159, v146, v238
	v_fmac_f32_e32 v159, v253, v240
	v_fmac_f32_e32 v159, v227, v241
	ds_read_b128 v[238:241], v9 offset:5936
	v_add_f32_e32 v158, v158, v159
	s_waitcnt lgkmcnt(0)
	v_mul_f32_e32 v159, v147, v239
	v_fmac_f32_e32 v159, v145, v238
	v_fmac_f32_e32 v159, v230, v240
	v_fmac_f32_e32 v159, v231, v241
	v_add_f32_e32 v158, v158, v159
	v_min_f32_e32 v159, 0, v158
	v_mul_f32_e64 v158, |v158|, s18
	v_exp_f32_e32 v158, v158
	ds_read_b128 v[240:243], v9 offset:6016
	v_add_f32_e32 v158, 1.0, v158
	v_cmp_gt_f32_e32 vcc, s71, v158
	s_nop 1
	v_cndmask_b32_e64 v160, 0, 32, vcc
	v_ldexp_f32 v158, v158, v160
	v_log_f32_e32 v158, v158
	s_nop 0
	v_mul_f32_e32 v160, 0x3f317217, v158
	v_fma_f32 v160, v158, s48, -v160
	v_fmac_f32_e32 v160, 0x3377d1cf, v158
	v_fmac_f32_e32 v160, 0x3f317217, v158
	v_cmp_lt_f32_e64 s[0:1], |v158|, s49
	s_nop 1
	v_cndmask_b32_e64 v158, v158, v160, s[0:1]
	v_cndmask_b32_e32 v160, 0, v233, vcc
	v_sub_f32_e32 v158, v158, v160
	v_sub_f32_e32 v158, v159, v158
	v_mul_f32_e32 v238, 0x3d800000, v158
	v_fmac_f32_e32 v141, 0x3d800000, v158
	s_waitcnt lgkmcnt(0)
	v_mul_f32_e32 v158, v5, v241
	v_fmac_f32_e32 v158, v4, v240
	v_fmac_f32_e32 v158, v6, v242
	v_fmac_f32_e32 v158, v7, v243
	ds_read_b128 v[240:243], v9 offset:6032
	v_add_f32_e32 v158, v157, v158
	s_waitcnt lgkmcnt(0)
	v_mul_f32_e32 v159, v154, v241
	v_fmac_f32_e32 v159, v228, v240
	v_fmac_f32_e32 v159, v155, v242
	v_fmac_f32_e32 v159, v156, v243
	ds_read_b128 v[240:243], v9 offset:6048
	v_add_f32_e32 v158, v158, v159
	s_waitcnt lgkmcnt(0)
	v_mul_f32_e32 v159, v252, v241
	v_fmac_f32_e32 v159, v146, v240
	v_fmac_f32_e32 v159, v253, v242
	v_fmac_f32_e32 v159, v227, v243
	ds_read_b128 v[240:243], v9 offset:6064
	v_add_f32_e32 v158, v158, v159
	s_waitcnt lgkmcnt(0)
	v_mul_f32_e32 v159, v147, v241
	v_fmac_f32_e32 v159, v145, v240
	v_fmac_f32_e32 v159, v230, v242
	v_fmac_f32_e32 v159, v231, v243
	v_add_f32_e32 v158, v158, v159
	v_min_f32_e32 v159, 0, v158
	v_mul_f32_e64 v158, |v158|, s18
	v_exp_f32_e32 v158, v158
	ds_read_b128 v[242:245], v9 offset:6144
	v_add_f32_e32 v158, 1.0, v158
	v_cmp_gt_f32_e32 vcc, s71, v158
	s_nop 1
	v_cndmask_b32_e64 v160, 0, 32, vcc
	v_ldexp_f32 v158, v158, v160
	v_log_f32_e32 v158, v158
	s_nop 0
	v_mul_f32_e32 v160, 0x3f317217, v158
	v_fma_f32 v160, v158, s48, -v160
	v_fmac_f32_e32 v160, 0x3377d1cf, v158
	v_fmac_f32_e32 v160, 0x3f317217, v158
	v_cmp_lt_f32_e64 s[0:1], |v158|, s49
	s_nop 1
	v_cndmask_b32_e64 v158, v158, v160, s[0:1]
	v_cndmask_b32_e32 v160, 0, v233, vcc
	v_sub_f32_e32 v158, v158, v160
	v_sub_f32_e32 v158, v159, v158
	v_mul_f32_e32 v240, 0x3d800000, v158
	v_fmac_f32_e32 v141, 0x3d800000, v158
	s_waitcnt lgkmcnt(0)
	v_mul_f32_e32 v158, v5, v243
	v_fmac_f32_e32 v158, v4, v242
	v_fmac_f32_e32 v158, v6, v244
	v_fmac_f32_e32 v158, v7, v245
	ds_read_b128 v[242:245], v9 offset:6160
	v_add_f32_e32 v158, v157, v158
	s_waitcnt lgkmcnt(0)
	v_mul_f32_e32 v159, v154, v243
	v_fmac_f32_e32 v159, v228, v242
	v_fmac_f32_e32 v159, v155, v244
	v_fmac_f32_e32 v159, v156, v245
	ds_read_b128 v[242:245], v9 offset:6176
	v_add_f32_e32 v158, v158, v159
	s_waitcnt lgkmcnt(0)
	v_mul_f32_e32 v159, v252, v243
	v_fmac_f32_e32 v159, v146, v242
	v_fmac_f32_e32 v159, v253, v244
	v_fmac_f32_e32 v159, v227, v245
	ds_read_b128 v[242:245], v9 offset:6192
	v_add_f32_e32 v158, v158, v159
	s_waitcnt lgkmcnt(0)
	v_mul_f32_e32 v159, v147, v243
	v_fmac_f32_e32 v159, v145, v242
	v_fmac_f32_e32 v159, v230, v244
	v_fmac_f32_e32 v159, v231, v245
	v_add_f32_e32 v158, v158, v159
	v_min_f32_e32 v159, 0, v158
	v_mul_f32_e64 v158, |v158|, s18
	v_exp_f32_e32 v158, v158
	ds_read_b128 v[242:245], v9 offset:6272
	v_add_f32_e32 v158, 1.0, v158
	v_cmp_gt_f32_e32 vcc, s71, v158
	s_nop 1
	v_cndmask_b32_e64 v160, 0, 32, vcc
	v_ldexp_f32 v158, v158, v160
	v_log_f32_e32 v158, v158
	s_nop 0
	v_mul_f32_e32 v160, 0x3f317217, v158
	v_fma_f32 v160, v158, s48, -v160
	v_fmac_f32_e32 v160, 0x3377d1cf, v158
	v_fmac_f32_e32 v160, 0x3f317217, v158
	v_cmp_lt_f32_e64 s[0:1], |v158|, s49
	s_nop 1
	v_cndmask_b32_e64 v158, v158, v160, s[0:1]
	v_cndmask_b32_e32 v160, 0, v233, vcc
	v_sub_f32_e32 v158, v158, v160
	v_sub_f32_e32 v158, v159, v158
	v_mul_f32_e32 v215, 0x3d800000, v158
	v_fmac_f32_e32 v141, 0x3d800000, v158
	s_waitcnt lgkmcnt(0)
	v_mul_f32_e32 v158, v5, v243
	v_fmac_f32_e32 v158, v4, v242
	v_fmac_f32_e32 v158, v6, v244
	v_fmac_f32_e32 v158, v7, v245
	ds_read_b128 v[242:245], v9 offset:6288
	v_add_f32_e32 v158, v157, v158
	s_waitcnt lgkmcnt(0)
	v_mul_f32_e32 v159, v154, v243
	v_fmac_f32_e32 v159, v228, v242
	v_fmac_f32_e32 v159, v155, v244
	v_fmac_f32_e32 v159, v156, v245
	ds_read_b128 v[242:245], v9 offset:6304
	v_add_f32_e32 v158, v158, v159
	s_waitcnt lgkmcnt(0)
	v_mul_f32_e32 v159, v252, v243
	v_fmac_f32_e32 v159, v146, v242
	v_fmac_f32_e32 v159, v253, v244
	v_fmac_f32_e32 v159, v227, v245
	ds_read_b128 v[242:245], v9 offset:6320
	v_add_f32_e32 v158, v158, v159
	s_waitcnt lgkmcnt(0)
	v_mul_f32_e32 v159, v147, v243
	v_fmac_f32_e32 v159, v145, v242
	v_fmac_f32_e32 v159, v230, v244
	v_fmac_f32_e32 v159, v231, v245
	v_add_f32_e32 v158, v158, v159
	v_min_f32_e32 v159, 0, v158
	v_mul_f32_e64 v158, |v158|, s18
	v_exp_f32_e32 v158, v158
	ds_read_b128 v[242:245], v9 offset:6400
	v_add_f32_e32 v158, 1.0, v158
	v_cmp_gt_f32_e32 vcc, s71, v158
	s_nop 1
	v_cndmask_b32_e64 v160, 0, 32, vcc
	v_ldexp_f32 v158, v158, v160
	v_log_f32_e32 v158, v158
	s_nop 0
	v_mul_f32_e32 v160, 0x3f317217, v158
	v_fma_f32 v160, v158, s48, -v160
	v_fmac_f32_e32 v160, 0x3377d1cf, v158
	v_fmac_f32_e32 v160, 0x3f317217, v158
	v_cmp_lt_f32_e64 s[0:1], |v158|, s49
	s_nop 1
	v_cndmask_b32_e64 v158, v158, v160, s[0:1]
	v_cndmask_b32_e32 v160, 0, v233, vcc
	v_sub_f32_e32 v158, v158, v160
	v_sub_f32_e32 v158, v159, v158
	v_mul_f32_e32 v237, 0x3d800000, v158
	v_fmac_f32_e32 v141, 0x3d800000, v158
	s_waitcnt lgkmcnt(0)
	v_mul_f32_e32 v158, v5, v243
	v_fmac_f32_e32 v158, v4, v242
	v_fmac_f32_e32 v158, v6, v244
	v_fmac_f32_e32 v158, v7, v245
	ds_read_b128 v[242:245], v9 offset:6416
	v_add_f32_e32 v158, v157, v158
	s_waitcnt lgkmcnt(0)
	v_mul_f32_e32 v159, v154, v243
	v_fmac_f32_e32 v159, v228, v242
	v_fmac_f32_e32 v159, v155, v244
	v_fmac_f32_e32 v159, v156, v245
	ds_read_b128 v[242:245], v9 offset:6432
	v_add_f32_e32 v158, v158, v159
	s_waitcnt lgkmcnt(0)
	v_mul_f32_e32 v159, v252, v243
	v_fmac_f32_e32 v159, v146, v242
	v_fmac_f32_e32 v159, v253, v244
	v_fmac_f32_e32 v159, v227, v245
	ds_read_b128 v[242:245], v9 offset:6448
	v_add_f32_e32 v158, v158, v159
	s_waitcnt lgkmcnt(0)
	v_mul_f32_e32 v159, v147, v243
	v_fmac_f32_e32 v159, v145, v242
	v_fmac_f32_e32 v159, v230, v244
	v_fmac_f32_e32 v159, v231, v245
	v_add_f32_e32 v158, v158, v159
	v_min_f32_e32 v159, 0, v158
	v_mul_f32_e64 v158, |v158|, s18
	v_exp_f32_e32 v158, v158
	ds_read_b128 v[244:247], v9 offset:6528
	v_add_f32_e32 v158, 1.0, v158
	v_cmp_gt_f32_e32 vcc, s71, v158
	s_nop 1
	v_cndmask_b32_e64 v160, 0, 32, vcc
	v_ldexp_f32 v158, v158, v160
	v_log_f32_e32 v158, v158
	s_nop 0
	v_mul_f32_e32 v160, 0x3f317217, v158
	v_fma_f32 v160, v158, s48, -v160
	v_fmac_f32_e32 v160, 0x3377d1cf, v158
	v_fmac_f32_e32 v160, 0x3f317217, v158
	v_cmp_lt_f32_e64 s[0:1], |v158|, s49
	s_nop 1
	v_cndmask_b32_e64 v158, v158, v160, s[0:1]
	v_cndmask_b32_e32 v160, 0, v233, vcc
	v_sub_f32_e32 v158, v158, v160
	v_sub_f32_e32 v158, v159, v158
	v_mul_f32_e32 v242, 0x3d800000, v158
	v_fmac_f32_e32 v141, 0x3d800000, v158
	s_waitcnt lgkmcnt(0)
	v_mul_f32_e32 v158, v5, v245
	v_fmac_f32_e32 v158, v4, v244
	v_fmac_f32_e32 v158, v6, v246
	v_fmac_f32_e32 v158, v7, v247
	ds_read_b128 v[244:247], v9 offset:6544
	v_add_f32_e32 v158, v157, v158
	s_waitcnt lgkmcnt(0)
	v_mul_f32_e32 v159, v154, v245
	v_fmac_f32_e32 v159, v228, v244
	v_fmac_f32_e32 v159, v155, v246
	v_fmac_f32_e32 v159, v156, v247
	ds_read_b128 v[244:247], v9 offset:6560
	v_add_f32_e32 v158, v158, v159
	s_waitcnt lgkmcnt(0)
	v_mul_f32_e32 v159, v252, v245
	v_fmac_f32_e32 v159, v146, v244
	v_fmac_f32_e32 v159, v253, v246
	v_fmac_f32_e32 v159, v227, v247
	ds_read_b128 v[244:247], v9 offset:6576
	v_add_f32_e32 v158, v158, v159
	s_waitcnt lgkmcnt(0)
	v_mul_f32_e32 v159, v147, v245
	v_fmac_f32_e32 v159, v145, v244
	v_fmac_f32_e32 v159, v230, v246
	v_fmac_f32_e32 v159, v231, v247
	v_add_f32_e32 v158, v158, v159
	v_min_f32_e32 v159, 0, v158
	v_mul_f32_e64 v158, |v158|, s18
	v_exp_f32_e32 v158, v158
	ds_read_b128 v[246:249], v9 offset:6656
	v_add_f32_e32 v158, 1.0, v158
	v_cmp_gt_f32_e32 vcc, s71, v158
	s_nop 1
	v_cndmask_b32_e64 v160, 0, 32, vcc
	v_ldexp_f32 v158, v158, v160
	v_log_f32_e32 v158, v158
	s_nop 0
	v_mul_f32_e32 v160, 0x3f317217, v158
	v_fma_f32 v160, v158, s48, -v160
	v_fmac_f32_e32 v160, 0x3377d1cf, v158
	v_fmac_f32_e32 v160, 0x3f317217, v158
	v_cmp_lt_f32_e64 s[0:1], |v158|, s49
	s_nop 1
	v_cndmask_b32_e64 v158, v158, v160, s[0:1]
	v_cndmask_b32_e32 v160, 0, v233, vcc
	v_sub_f32_e32 v158, v158, v160
	v_sub_f32_e32 v158, v159, v158
	v_mul_f32_e32 v244, 0x3d800000, v158
	v_fmac_f32_e32 v141, 0x3d800000, v158
	s_waitcnt lgkmcnt(0)
	v_mul_f32_e32 v158, v5, v247
	v_fmac_f32_e32 v158, v4, v246
	v_fmac_f32_e32 v158, v6, v248
	v_fmac_f32_e32 v158, v7, v249
	ds_read_b128 v[246:249], v9 offset:6672
	v_add_f32_e32 v158, v157, v158
	s_waitcnt lgkmcnt(0)
	v_mul_f32_e32 v159, v154, v247
	v_fmac_f32_e32 v159, v228, v246
	v_fmac_f32_e32 v159, v155, v248
	v_fmac_f32_e32 v159, v156, v249
	ds_read_b128 v[246:249], v9 offset:6688
	v_add_f32_e32 v158, v158, v159
	s_waitcnt lgkmcnt(0)
	v_mul_f32_e32 v159, v252, v247
	v_fmac_f32_e32 v159, v146, v246
	v_fmac_f32_e32 v159, v253, v248
	v_fmac_f32_e32 v159, v227, v249
	ds_read_b128 v[246:249], v9 offset:6704
	v_add_f32_e32 v158, v158, v159
	s_waitcnt lgkmcnt(0)
	v_mul_f32_e32 v159, v147, v247
	v_fmac_f32_e32 v159, v145, v246
	v_fmac_f32_e32 v159, v230, v248
	v_fmac_f32_e32 v159, v231, v249
	v_add_f32_e32 v158, v158, v159
	v_min_f32_e32 v159, 0, v158
	v_mul_f32_e64 v158, |v158|, s18
	v_exp_f32_e32 v158, v158
	ds_read_b128 v[246:249], v9 offset:6784
	v_add_f32_e32 v158, 1.0, v158
	v_cmp_gt_f32_e32 vcc, s71, v158
	s_nop 1
	v_cndmask_b32_e64 v160, 0, 32, vcc
	v_ldexp_f32 v158, v158, v160
	v_log_f32_e32 v158, v158
	s_nop 0
	v_mul_f32_e32 v160, 0x3f317217, v158
	v_fma_f32 v160, v158, s48, -v160
	v_fmac_f32_e32 v160, 0x3377d1cf, v158
	v_fmac_f32_e32 v160, 0x3f317217, v158
	v_cmp_lt_f32_e64 s[0:1], |v158|, s49
	s_nop 1
	v_cndmask_b32_e64 v158, v158, v160, s[0:1]
	v_cndmask_b32_e32 v160, 0, v233, vcc
	v_sub_f32_e32 v158, v158, v160
	v_sub_f32_e32 v158, v159, v158
	v_mul_f32_e32 v235, 0x3d800000, v158
	v_fmac_f32_e32 v141, 0x3d800000, v158
	s_waitcnt lgkmcnt(0)
	v_mul_f32_e32 v158, v5, v247
	v_fmac_f32_e32 v158, v4, v246
	v_fmac_f32_e32 v158, v6, v248
	v_fmac_f32_e32 v158, v7, v249
	ds_read_b128 v[246:249], v9 offset:6800
	v_add_f32_e32 v158, v157, v158
	s_waitcnt lgkmcnt(0)
	v_mul_f32_e32 v159, v154, v247
	v_fmac_f32_e32 v159, v228, v246
	v_fmac_f32_e32 v159, v155, v248
	v_fmac_f32_e32 v159, v156, v249
	ds_read_b128 v[246:249], v9 offset:6816
	v_add_f32_e32 v158, v158, v159
	s_waitcnt lgkmcnt(0)
	v_mul_f32_e32 v159, v252, v247
	v_fmac_f32_e32 v159, v146, v246
	v_fmac_f32_e32 v159, v253, v248
	v_fmac_f32_e32 v159, v227, v249
	ds_read_b128 v[246:249], v9 offset:6832
	v_add_f32_e32 v158, v158, v159
	s_waitcnt lgkmcnt(0)
	v_mul_f32_e32 v159, v147, v247
	v_fmac_f32_e32 v159, v145, v246
	v_fmac_f32_e32 v159, v230, v248
	v_fmac_f32_e32 v159, v231, v249
	v_add_f32_e32 v158, v158, v159
	v_min_f32_e32 v159, 0, v158
	v_mul_f32_e64 v158, |v158|, s18
	v_exp_f32_e32 v158, v158
	ds_read_b128 v[246:249], v9 offset:6912
	v_add_f32_e32 v158, 1.0, v158
	v_cmp_gt_f32_e32 vcc, s71, v158
	s_nop 1
	v_cndmask_b32_e64 v160, 0, 32, vcc
	v_ldexp_f32 v158, v158, v160
	v_log_f32_e32 v158, v158
	s_nop 0
	v_mul_f32_e32 v160, 0x3f317217, v158
	v_fma_f32 v160, v158, s48, -v160
	v_fmac_f32_e32 v160, 0x3377d1cf, v158
	v_fmac_f32_e32 v160, 0x3f317217, v158
	v_cmp_lt_f32_e64 s[0:1], |v158|, s49
	s_nop 1
	v_cndmask_b32_e64 v158, v158, v160, s[0:1]
	v_cndmask_b32_e32 v160, 0, v233, vcc
	v_sub_f32_e32 v158, v158, v160
	v_sub_f32_e32 v158, v159, v158
	v_mul_f32_e32 v241, 0x3d800000, v158
	v_fmac_f32_e32 v141, 0x3d800000, v158
	s_waitcnt lgkmcnt(0)
	v_mul_f32_e32 v158, v5, v247
	v_fmac_f32_e32 v158, v4, v246
	v_fmac_f32_e32 v158, v6, v248
	v_fmac_f32_e32 v158, v7, v249
	ds_read_b128 v[246:249], v9 offset:6928
	v_add_f32_e32 v158, v157, v158
	s_waitcnt lgkmcnt(0)
	v_mul_f32_e32 v159, v154, v247
	v_fmac_f32_e32 v159, v228, v246
	v_fmac_f32_e32 v159, v155, v248
	v_fmac_f32_e32 v159, v156, v249
	ds_read_b128 v[246:249], v9 offset:6944
	v_add_f32_e32 v158, v158, v159
	s_waitcnt lgkmcnt(0)
	v_mul_f32_e32 v159, v252, v247
	v_fmac_f32_e32 v159, v146, v246
	v_fmac_f32_e32 v159, v253, v248
	v_fmac_f32_e32 v159, v227, v249
	ds_read_b128 v[246:249], v9 offset:6960
	v_add_f32_e32 v158, v158, v159
	s_waitcnt lgkmcnt(0)
	v_mul_f32_e32 v159, v147, v247
	v_fmac_f32_e32 v159, v145, v246
	v_fmac_f32_e32 v159, v230, v248
	v_fmac_f32_e32 v159, v231, v249
	v_add_f32_e32 v158, v158, v159
	v_min_f32_e32 v159, 0, v158
	v_mul_f32_e64 v158, |v158|, s18
	v_exp_f32_e32 v158, v158
	ds_read_b128 v[248:251], v9 offset:7040
	v_add_f32_e32 v158, 1.0, v158
	v_cmp_gt_f32_e32 vcc, s71, v158
	s_nop 1
	v_cndmask_b32_e64 v160, 0, 32, vcc
	v_ldexp_f32 v158, v158, v160
	v_log_f32_e32 v158, v158
	s_nop 0
	v_mul_f32_e32 v160, 0x3f317217, v158
	v_fma_f32 v160, v158, s48, -v160
	v_fmac_f32_e32 v160, 0x3377d1cf, v158
	v_fmac_f32_e32 v160, 0x3f317217, v158
	v_cmp_lt_f32_e64 s[0:1], |v158|, s49
	s_nop 1
	v_cndmask_b32_e64 v158, v158, v160, s[0:1]
	v_cndmask_b32_e32 v160, 0, v233, vcc
	v_sub_f32_e32 v158, v158, v160
	v_sub_f32_e32 v158, v159, v158
	v_mul_f32_e32 v246, 0x3d800000, v158
	v_fmac_f32_e32 v141, 0x3d800000, v158
	s_waitcnt lgkmcnt(0)
	v_mul_f32_e32 v158, v5, v249
	v_fmac_f32_e32 v158, v4, v248
	v_fmac_f32_e32 v158, v6, v250
	v_fmac_f32_e32 v158, v7, v251
	ds_read_b128 v[248:251], v9 offset:7056
	v_add_f32_e32 v158, v157, v158
	s_waitcnt lgkmcnt(0)
	v_mul_f32_e32 v159, v154, v249
	v_fmac_f32_e32 v159, v228, v248
	v_fmac_f32_e32 v159, v155, v250
	v_fmac_f32_e32 v159, v156, v251
	ds_read_b128 v[248:251], v9 offset:7072
	v_add_f32_e32 v158, v158, v159
	s_waitcnt lgkmcnt(0)
	v_mul_f32_e32 v159, v252, v249
	v_fmac_f32_e32 v159, v146, v248
	v_fmac_f32_e32 v159, v253, v250
	v_fmac_f32_e32 v159, v227, v251
	ds_read_b128 v[248:251], v9 offset:7088
	v_add_f32_e32 v158, v158, v159
	s_waitcnt lgkmcnt(0)
	v_mul_f32_e32 v159, v147, v249
	v_fmac_f32_e32 v159, v145, v248
	v_fmac_f32_e32 v159, v230, v250
	v_fmac_f32_e32 v159, v231, v251
	v_add_f32_e32 v158, v158, v159
	v_min_f32_e32 v159, 0, v158
	v_mul_f32_e64 v158, |v158|, s18
	v_exp_f32_e32 v158, v158
	ds_read_b128 v[248:251], v9 offset:7168
	v_add_f32_e32 v158, 1.0, v158
	v_cmp_gt_f32_e32 vcc, s71, v158
	s_nop 1
	v_cndmask_b32_e64 v160, 0, 32, vcc
	v_ldexp_f32 v158, v158, v160
	v_log_f32_e32 v158, v158
	s_nop 0
	v_mul_f32_e32 v160, 0x3f317217, v158
	v_fma_f32 v160, v158, s48, -v160
	v_fmac_f32_e32 v160, 0x3377d1cf, v158
	v_fmac_f32_e32 v160, 0x3f317217, v158
	v_cmp_lt_f32_e64 s[0:1], |v158|, s49
	s_nop 1
	v_cndmask_b32_e64 v158, v158, v160, s[0:1]
	v_cndmask_b32_e32 v160, 0, v233, vcc
	v_sub_f32_e32 v158, v158, v160
	v_sub_f32_e32 v158, v159, v158
	v_mul_f32_e32 v247, 0x3d800000, v158
	v_fmac_f32_e32 v141, 0x3d800000, v158
	s_waitcnt lgkmcnt(0)
	v_mul_f32_e32 v158, v5, v249
	v_fmac_f32_e32 v158, v4, v248
	v_fmac_f32_e32 v158, v6, v250
	v_fmac_f32_e32 v158, v7, v251
	ds_read_b128 v[248:251], v9 offset:7184
	v_add_f32_e32 v158, v157, v158
	s_waitcnt lgkmcnt(0)
	v_mul_f32_e32 v159, v154, v249
	v_fmac_f32_e32 v159, v228, v248
	v_fmac_f32_e32 v159, v155, v250
	v_fmac_f32_e32 v159, v156, v251
	ds_read_b128 v[248:251], v9 offset:7200
	v_add_f32_e32 v158, v158, v159
	s_waitcnt lgkmcnt(0)
	v_mul_f32_e32 v159, v252, v249
	v_fmac_f32_e32 v159, v146, v248
	v_fmac_f32_e32 v159, v253, v250
	v_fmac_f32_e32 v159, v227, v251
	ds_read_b128 v[248:251], v9 offset:7216
	v_add_f32_e32 v158, v158, v159
	s_waitcnt lgkmcnt(0)
	v_mul_f32_e32 v159, v147, v249
	v_fmac_f32_e32 v159, v145, v248
	v_fmac_f32_e32 v159, v230, v250
	v_fmac_f32_e32 v159, v231, v251
	v_add_f32_e32 v158, v158, v159
	v_min_f32_e32 v159, 0, v158
	v_mul_f32_e64 v158, |v158|, s18
	v_exp_f32_e32 v158, v158
	ds_read_b128 v[248:251], v9 offset:7296
	v_add_f32_e32 v158, 1.0, v158
	v_cmp_gt_f32_e32 vcc, s71, v158
	s_nop 1
	v_cndmask_b32_e64 v160, 0, 32, vcc
	v_ldexp_f32 v158, v158, v160
	v_log_f32_e32 v158, v158
	s_nop 0
	v_mul_f32_e32 v160, 0x3f317217, v158
	v_fma_f32 v160, v158, s48, -v160
	v_fmac_f32_e32 v160, 0x3377d1cf, v158
	v_fmac_f32_e32 v160, 0x3f317217, v158
	v_cmp_lt_f32_e64 s[0:1], |v158|, s49
	s_nop 1
	v_cndmask_b32_e64 v158, v158, v160, s[0:1]
	v_cndmask_b32_e32 v160, 0, v233, vcc
	v_sub_f32_e32 v158, v158, v160
	v_sub_f32_e32 v158, v159, v158
	v_mul_f32_e32 v239, 0x3d800000, v158
	v_fmac_f32_e32 v141, 0x3d800000, v158
	s_waitcnt lgkmcnt(0)
	v_mul_f32_e32 v158, v5, v249
	v_fmac_f32_e32 v158, v4, v248
	v_fmac_f32_e32 v158, v6, v250
	v_fmac_f32_e32 v158, v7, v251
	ds_read_b128 v[248:251], v9 offset:7312
	v_add_f32_e32 v158, v157, v158
	s_waitcnt lgkmcnt(0)
	v_mul_f32_e32 v159, v154, v249
	v_fmac_f32_e32 v159, v228, v248
	v_fmac_f32_e32 v159, v155, v250
	v_fmac_f32_e32 v159, v156, v251
	ds_read_b128 v[248:251], v9 offset:7328
	v_add_f32_e32 v158, v158, v159
	s_waitcnt lgkmcnt(0)
	v_mul_f32_e32 v159, v252, v249
	v_fmac_f32_e32 v159, v146, v248
	v_fmac_f32_e32 v159, v253, v250
	v_fmac_f32_e32 v159, v227, v251
	ds_read_b128 v[248:251], v9 offset:7344
	v_add_f32_e32 v158, v158, v159
	s_waitcnt lgkmcnt(0)
	v_mul_f32_e32 v159, v147, v249
	v_fmac_f32_e32 v159, v145, v248
	v_fmac_f32_e32 v159, v230, v250
	v_fmac_f32_e32 v159, v231, v251
	v_add_f32_e32 v158, v158, v159
	v_min_f32_e32 v159, 0, v158
	v_mul_f32_e64 v158, |v158|, s18
	v_exp_f32_e32 v158, v158
	ds_read_b128 v[248:251], v9 offset:7424
	v_add_f32_e32 v158, 1.0, v158
	v_cmp_gt_f32_e32 vcc, s71, v158
	s_nop 1
	v_cndmask_b32_e64 v160, 0, 32, vcc
	v_ldexp_f32 v158, v158, v160
	v_log_f32_e32 v158, v158
	s_nop 0
	v_mul_f32_e32 v160, 0x3f317217, v158
	v_fma_f32 v160, v158, s48, -v160
	v_fmac_f32_e32 v160, 0x3377d1cf, v158
	v_fmac_f32_e32 v160, 0x3f317217, v158
	v_cmp_lt_f32_e64 s[0:1], |v158|, s49
	s_nop 1
	v_cndmask_b32_e64 v158, v158, v160, s[0:1]
	v_cndmask_b32_e32 v160, 0, v233, vcc
	v_sub_f32_e32 v158, v158, v160
	v_sub_f32_e32 v158, v159, v158
	v_mul_f32_e32 v245, 0x3d800000, v158
	v_fmac_f32_e32 v141, 0x3d800000, v158
	s_waitcnt lgkmcnt(0)
	v_mul_f32_e32 v158, v5, v249
	v_fmac_f32_e32 v158, v4, v248
	v_fmac_f32_e32 v158, v6, v250
	v_fmac_f32_e32 v158, v7, v251
	ds_read_b128 v[248:251], v9 offset:7440
	v_add_f32_e32 v158, v157, v158
	s_waitcnt lgkmcnt(0)
	v_mul_f32_e32 v159, v154, v249
	v_fmac_f32_e32 v159, v228, v248
	v_fmac_f32_e32 v159, v155, v250
	v_fmac_f32_e32 v159, v156, v251
	ds_read_b128 v[248:251], v9 offset:7456
	v_add_f32_e32 v158, v158, v159
	s_waitcnt lgkmcnt(0)
	v_mul_f32_e32 v159, v252, v249
	v_fmac_f32_e32 v159, v146, v248
	v_fmac_f32_e32 v159, v253, v250
	v_fmac_f32_e32 v159, v227, v251
	ds_read_b128 v[248:251], v9 offset:7472
	v_add_f32_e32 v158, v158, v159
	s_waitcnt lgkmcnt(0)
	v_mul_f32_e32 v159, v147, v249
	v_fmac_f32_e32 v159, v145, v248
	v_fmac_f32_e32 v159, v230, v250
	v_fmac_f32_e32 v159, v231, v251
	v_add_f32_e32 v158, v158, v159
	v_min_f32_e32 v159, 0, v158
	v_mul_f32_e64 v158, |v158|, s18
	v_exp_f32_e32 v158, v158
	s_nop 0
	v_add_f32_e32 v158, 1.0, v158
	v_cmp_gt_f32_e32 vcc, s71, v158
	s_nop 1
	v_cndmask_b32_e64 v160, 0, 32, vcc
	v_ldexp_f32 v158, v158, v160
	v_log_f32_e32 v158, v158
	s_nop 0
	v_mul_f32_e32 v160, 0x3f317217, v158
	v_fma_f32 v160, v158, s48, -v160
	v_fmac_f32_e32 v160, 0x3377d1cf, v158
	v_fmac_f32_e32 v160, 0x3f317217, v158
	v_cmp_lt_f32_e64 s[0:1], |v158|, s49
	s_nop 1
	v_cndmask_b32_e64 v158, v158, v160, s[0:1]
	v_cndmask_b32_e32 v160, 0, v233, vcc
	v_sub_f32_e32 v158, v158, v160
	v_sub_f32_e32 v158, v159, v158
	v_mul_f32_e32 v249, 0x3d800000, v158
	v_fmac_f32_e32 v141, 0x3d800000, v158
	ds_read_b128 v[158:161], v9 offset:7552
	s_waitcnt lgkmcnt(0)
	v_mul_f32_e32 v159, v5, v159
	v_fmac_f32_e32 v159, v4, v158
	v_fmac_f32_e32 v159, v6, v160
	v_fmac_f32_e32 v159, v7, v161
	v_add_f32_e32 v243, v157, v159
	ds_read_b128 v[158:161], v9 offset:7568
	s_waitcnt lgkmcnt(0)
	v_mul_f32_e32 v159, v154, v159
	v_fmac_f32_e32 v159, v228, v158
	v_fmac_f32_e32 v159, v155, v160
	v_fmac_f32_e32 v159, v156, v161
	v_add_f32_e32 v243, v243, v159
	ds_read_b128 v[158:161], v9 offset:7584
	s_waitcnt lgkmcnt(0)
	v_mul_f32_e32 v159, v252, v159
	v_fmac_f32_e32 v159, v146, v158
	v_fmac_f32_e32 v159, v253, v160
	v_fmac_f32_e32 v159, v227, v161
	v_add_f32_e32 v243, v243, v159
	ds_read_b128 v[158:161], v9 offset:7600
	s_waitcnt lgkmcnt(0)
	v_mul_f32_e32 v159, v147, v159
	v_fmac_f32_e32 v159, v145, v158
	v_fmac_f32_e32 v159, v230, v160
	v_fmac_f32_e32 v159, v231, v161
	v_add_f32_e32 v158, v243, v159
	v_min_f32_e32 v159, 0, v158
	v_mul_f32_e64 v158, |v158|, s18
	v_exp_f32_e32 v158, v158
	s_nop 0
	v_add_f32_e32 v158, 1.0, v158
	v_cmp_gt_f32_e32 vcc, s71, v158
	s_nop 1
	v_cndmask_b32_e64 v160, 0, 32, vcc
	v_ldexp_f32 v158, v158, v160
	v_log_f32_e32 v158, v158
	s_nop 0
	v_mul_f32_e32 v160, 0x3f317217, v158
	v_fma_f32 v160, v158, s48, -v160
	v_fmac_f32_e32 v160, 0x3377d1cf, v158
	v_fmac_f32_e32 v160, 0x3f317217, v158
	v_cmp_lt_f32_e64 s[0:1], |v158|, s49
	s_nop 1
	v_cndmask_b32_e64 v158, v158, v160, s[0:1]
	v_cndmask_b32_e32 v160, 0, v233, vcc
	v_sub_f32_e32 v158, v158, v160
	v_sub_f32_e32 v158, v159, v158
	v_mul_f32_e32 v250, 0x3d800000, v158
	v_fmac_f32_e32 v141, 0x3d800000, v158
	ds_read_b128 v[158:161], v9 offset:7680
	s_waitcnt lgkmcnt(0)
	v_mul_f32_e32 v159, v5, v159
	v_fmac_f32_e32 v159, v4, v158
	v_fmac_f32_e32 v159, v6, v160
	v_fmac_f32_e32 v159, v7, v161
	v_add_f32_e32 v243, v157, v159
	ds_read_b128 v[158:161], v9 offset:7696
	s_waitcnt lgkmcnt(0)
	v_mul_f32_e32 v159, v154, v159
	v_fmac_f32_e32 v159, v228, v158
	v_fmac_f32_e32 v159, v155, v160
	v_fmac_f32_e32 v159, v156, v161
	v_add_f32_e32 v243, v243, v159
	ds_read_b128 v[158:161], v9 offset:7712
	s_waitcnt lgkmcnt(0)
	v_mul_f32_e32 v159, v252, v159
	v_fmac_f32_e32 v159, v146, v158
	v_fmac_f32_e32 v159, v253, v160
	v_fmac_f32_e32 v159, v227, v161
	v_add_f32_e32 v243, v243, v159
	ds_read_b128 v[158:161], v9 offset:7728
	s_waitcnt lgkmcnt(0)
	v_mul_f32_e32 v159, v147, v159
	v_fmac_f32_e32 v159, v145, v158
	v_fmac_f32_e32 v159, v230, v160
	v_fmac_f32_e32 v159, v231, v161
	v_add_f32_e32 v158, v243, v159
	v_min_f32_e32 v159, 0, v158
	v_mul_f32_e64 v158, |v158|, s18
	v_exp_f32_e32 v158, v158
	s_nop 0
	v_add_f32_e32 v158, 1.0, v158
	v_cmp_gt_f32_e32 vcc, s71, v158
	s_nop 1
	v_cndmask_b32_e64 v160, 0, 32, vcc
	v_ldexp_f32 v158, v158, v160
	v_log_f32_e32 v158, v158
	s_nop 0
	v_mul_f32_e32 v160, 0x3f317217, v158
	v_fma_f32 v160, v158, s48, -v160
	v_fmac_f32_e32 v160, 0x3377d1cf, v158
	v_fmac_f32_e32 v160, 0x3f317217, v158
	v_cmp_lt_f32_e64 s[0:1], |v158|, s49
	s_nop 1
	v_cndmask_b32_e64 v158, v158, v160, s[0:1]
	v_cndmask_b32_e32 v160, 0, v233, vcc
	v_sub_f32_e32 v158, v158, v160
	v_sub_f32_e32 v158, v159, v158
	v_mul_f32_e32 v243, 0x3d800000, v158
	v_fmac_f32_e32 v141, 0x3d800000, v158
	ds_read_b128 v[158:161], v9 offset:7808
	s_waitcnt lgkmcnt(0)
	v_mul_f32_e32 v159, v5, v159
	v_fmac_f32_e32 v159, v4, v158
	v_fmac_f32_e32 v159, v6, v160
	v_fmac_f32_e32 v159, v7, v161
	v_add_f32_e32 v248, v157, v159
	ds_read_b128 v[158:161], v9 offset:7824
	s_waitcnt lgkmcnt(0)
	v_mul_f32_e32 v159, v154, v159
	v_fmac_f32_e32 v159, v228, v158
	v_fmac_f32_e32 v159, v155, v160
	v_fmac_f32_e32 v159, v156, v161
	v_add_f32_e32 v248, v248, v159
	ds_read_b128 v[158:161], v9 offset:7840
	s_waitcnt lgkmcnt(0)
	v_mul_f32_e32 v159, v252, v159
	v_fmac_f32_e32 v159, v146, v158
	v_fmac_f32_e32 v159, v253, v160
	v_fmac_f32_e32 v159, v227, v161
	v_add_f32_e32 v248, v248, v159
	ds_read_b128 v[158:161], v9 offset:7856
	s_waitcnt lgkmcnt(0)
	v_mul_f32_e32 v159, v147, v159
	v_fmac_f32_e32 v159, v145, v158
	v_fmac_f32_e32 v159, v230, v160
	v_fmac_f32_e32 v159, v231, v161
	v_add_f32_e32 v158, v248, v159
	v_min_f32_e32 v159, 0, v158
	v_mul_f32_e64 v158, |v158|, s18
	v_exp_f32_e32 v158, v158
	s_nop 0
	v_add_f32_e32 v158, 1.0, v158
	v_cmp_gt_f32_e32 vcc, s71, v158
	s_nop 1
	v_cndmask_b32_e64 v160, 0, 32, vcc
	v_ldexp_f32 v158, v158, v160
	v_log_f32_e32 v158, v158
	s_nop 0
	v_mul_f32_e32 v160, 0x3f317217, v158
	v_fma_f32 v160, v158, s48, -v160
	v_fmac_f32_e32 v160, 0x3377d1cf, v158
	v_fmac_f32_e32 v160, 0x3f317217, v158
	v_cmp_lt_f32_e64 s[0:1], |v158|, s49
	s_nop 1
	v_cndmask_b32_e64 v158, v158, v160, s[0:1]
	v_cndmask_b32_e32 v160, 0, v233, vcc
	v_sub_f32_e32 v158, v158, v160
	v_sub_f32_e32 v158, v159, v158
	v_mul_f32_e32 v248, 0x3d800000, v158
	v_fmac_f32_e32 v141, 0x3d800000, v158
	ds_read_b128 v[158:161], v9 offset:7936
	s_waitcnt lgkmcnt(0)
	v_mul_f32_e32 v159, v5, v159
	v_fmac_f32_e32 v159, v4, v158
	v_fmac_f32_e32 v159, v6, v160
	v_fmac_f32_e32 v159, v7, v161
	v_add_f32_e32 v251, v157, v159
	ds_read_b128 v[158:161], v9 offset:7952
	s_waitcnt lgkmcnt(0)
	v_mul_f32_e32 v159, v154, v159
	v_fmac_f32_e32 v159, v228, v158
	v_fmac_f32_e32 v159, v155, v160
	v_fmac_f32_e32 v159, v156, v161
	v_add_f32_e32 v251, v251, v159
	ds_read_b128 v[158:161], v9 offset:7968
	s_waitcnt lgkmcnt(0)
	v_mul_f32_e32 v159, v252, v159
	v_fmac_f32_e32 v159, v146, v158
	v_fmac_f32_e32 v159, v253, v160
	v_fmac_f32_e32 v159, v227, v161
	v_add_f32_e32 v251, v251, v159
	ds_read_b128 v[158:161], v9 offset:7984
	s_waitcnt lgkmcnt(0)
	v_mul_f32_e32 v159, v147, v159
	v_fmac_f32_e32 v159, v145, v158
	v_fmac_f32_e32 v159, v230, v160
	v_fmac_f32_e32 v159, v231, v161
	v_add_f32_e32 v158, v251, v159
	v_min_f32_e32 v159, 0, v158
	v_mul_f32_e64 v158, |v158|, s18
	v_exp_f32_e32 v158, v158
	s_nop 0
	v_add_f32_e32 v158, 1.0, v158
	v_cmp_gt_f32_e32 vcc, s71, v158
	s_nop 1
	v_cndmask_b32_e64 v160, 0, 32, vcc
	v_ldexp_f32 v158, v158, v160
	v_log_f32_e32 v158, v158
	s_nop 0
	v_mul_f32_e32 v160, 0x3f317217, v158
	v_fma_f32 v160, v158, s48, -v160
	v_fmac_f32_e32 v160, 0x3377d1cf, v158
	v_fmac_f32_e32 v160, 0x3f317217, v158
	v_cmp_lt_f32_e64 s[0:1], |v158|, s49
	s_nop 1
	v_cndmask_b32_e64 v158, v158, v160, s[0:1]
	v_cndmask_b32_e32 v160, 0, v233, vcc
	v_sub_f32_e32 v158, v158, v160
	v_sub_f32_e32 v158, v159, v158
	v_mul_f32_e32 v251, 0x3d800000, v158
	v_fmac_f32_e32 v141, 0x3d800000, v158
	ds_read_b128 v[158:161], v9 offset:8064
	s_waitcnt lgkmcnt(0)
	v_mul_f32_e32 v5, v5, v159
	v_fmac_f32_e32 v5, v4, v158
	v_fmac_f32_e32 v5, v6, v160
	v_fmac_f32_e32 v5, v7, v161
	v_add_f32_e32 v157, v157, v5
	ds_read_b128 v[4:7], v9 offset:8080
	s_waitcnt lgkmcnt(0)
	v_mul_f32_e32 v5, v154, v5
	v_fmac_f32_e32 v5, v228, v4
	v_fmac_f32_e32 v5, v155, v6
	v_fmac_f32_e32 v5, v156, v7
	v_add_f32_e32 v4, v157, v5
	ds_read_b128 v[154:157], v9 offset:8096
	s_waitcnt lgkmcnt(0)
	v_mul_f32_e32 v5, v252, v155
	v_fmac_f32_e32 v5, v146, v154
	v_fmac_f32_e32 v5, v253, v156
	v_fmac_f32_e32 v5, v227, v157
	v_add_f32_e32 v146, v4, v5
	ds_read_b128 v[4:7], v9 offset:8112
	s_waitcnt lgkmcnt(0)
	v_mul_f32_e32 v5, v147, v5
	v_fmac_f32_e32 v5, v145, v4
	v_fmac_f32_e32 v5, v230, v6
	v_fmac_f32_e32 v5, v231, v7
	v_add_f32_e32 v4, v146, v5
	v_min_f32_e32 v5, 0, v4
	v_mul_f32_e64 v4, |v4|, s18
	v_exp_f32_e32 v4, v4
	v_ashrrev_i32_e32 v145, 31, v144
	v_mov_b32_e32 v147, v3
	v_add_f32_e32 v4, 1.0, v4
	v_cmp_gt_f32_e32 vcc, s71, v4
	s_nop 1
	v_cndmask_b32_e64 v6, 0, 32, vcc
	v_ldexp_f32 v4, v4, v6
	v_log_f32_e32 v4, v4
	s_nop 0
	v_mul_f32_e32 v6, 0x3f317217, v4
	v_fma_f32 v6, v4, s48, -v6
	v_fmac_f32_e32 v6, 0x3377d1cf, v4
	v_fmac_f32_e32 v6, 0x3f317217, v4
	v_cmp_lt_f32_e64 s[0:1], |v4|, s49
	s_nop 1
	v_cndmask_b32_e64 v4, v4, v6, s[0:1]
	v_cndmask_b32_e32 v6, 0, v233, vcc
	v_sub_f32_e32 v4, v4, v6
	v_sub_f32_e32 v4, v5, v4
	v_lshlrev_b64 v[6:7], 7, v[144:145]
	ds_read_u16 v145, v41 offset:24576
	v_mul_f32_e32 v252, 0x3d800000, v4
	v_cndmask_b32_e64 v144, v252, v173, s[4:5]
	v_add_f32_e32 v156, 0, v144
	ds_read_u16 v144, v41 offset:8192
	s_waitcnt lgkmcnt(1)
	v_lshlrev_b32_e32 v157, 16, v145
	v_mul_f32_e32 v145, 0x3fb8aa3b, v156
	v_exp_f32_e32 v145, v145
	v_fmac_f32_e32 v141, 0x3d800000, v4
	s_waitcnt lgkmcnt(0)
	v_lshlrev_b32_e32 v144, 16, v144
	v_or_b32_e32 v4, v143, v11
	v_mul_f32_e32 v144, 0x3db504f3, v144
	v_lshlrev_b32_e32 v146, 13, v4
	v_ashrrev_i32_e32 v143, 31, v142
	v_mul_f32_e32 v144, v144, v145
	v_lshl_add_u64 v[142:143], v[146:147], 0, v[142:143]
	v_cvt_pk_bf16_f32 v158, v144, v144
	v_or_b32_e32 v144, v142, v10
	v_mov_b32_e32 v145, v143
	v_lshlrev_b64 v[146:147], 8, v[144:145]
	v_mul_f32_e32 v145, 0xbfb8aa3b, v156
	v_exp_f32_e32 v145, v145
	v_lshlrev_b32_e32 v144, 1, v8
	v_or_b32_e32 v146, v146, v144
	v_lshl_add_u64 v[154:155], s[36:37], 0, v[146:147]
	v_mul_f32_e32 v145, v145, v157
	v_and_b32_e32 v227, 0xff, v0
	v_lshrrev_b32_e32 v228, 8, v0
	v_lshlrev_b32_e32 v227, 2, v227
	v_lshl_add_u32 v227, v228, 16, v227
	ds_write_b32 v227, v218 offset:40960
	ds_write_b32 v227, v219 offset:41984
	ds_write_b32 v227, v220 offset:43008
	ds_write_b32 v227, v221 offset:44032
	ds_write_b32 v227, v222 offset:45056
	ds_write_b32 v227, v223 offset:46080
	ds_write_b32 v227, v224 offset:47104
	ds_write_b32 v227, v225 offset:48128
	ds_write_b32 v227, v226 offset:49152
	v_cndmask_b32_e64 v224, 0, -14, s[4:5]
	v_cndmask_b32_e64 v225, 0, -1, s[4:5]
	s_mov_b32 s98, 0xffff0000
	global_store_short_d16_hi v[154:155], v158, off
	v_cvt_pk_bf16_f32 v145, v145, v145
	v_lshl_add_u64 v[146:147], s[38:39], 0, v[146:147]
	global_store_short_d16_hi v[146:147], v145, off
	v_sub_f32_e32 v145, v141, v156
	v_mul_f32_e32 v145, 0x3fb8aa3b, v145
	v_exp_f32_e32 v145, v145
	v_lshlrev_b32_e32 v4, 14, v4
	v_mov_b32_e32 v5, v3
	v_lshl_add_u64 v[4:5], v[4:5], 0, v[6:7]
	v_or_b32_e32 v4, v4, v8
	v_mul_f32_e32 v145, v145, v157
	v_lshlrev_b64 v[6:7], 7, v[4:5]
	v_lshl_add_u64 v[6:7], s[54:55], 0, v[6:7]
	v_cvt_pk_bf16_f32 v145, v145, v145
	v_lshrrev_b32_e32 v220, 16, v145
	ds_read_u16 v146, v43 offset:8192
	ds_read_u16 v147, v43 offset:24576
	v_cndmask_b32_e64 v145, v251, v174, s[4:5]
	v_add_f32_e32 v145, v145, v156
	s_movk_i32 s0, 0x1ff
	s_waitcnt lgkmcnt(1)
	v_lshlrev_b32_e32 v146, 16, v146
	s_waitcnt lgkmcnt(0)
	v_lshlrev_b32_e32 v156, 16, v147
	v_mul_f32_e32 v147, 0x3fb8aa3b, v145
	v_exp_f32_e32 v147, v147
	v_mul_f32_e32 v146, 0x3db504f3, v146
	v_cmp_lt_i32_e32 vcc, s0, v1
	v_lshl_add_u64 v[4:5], v[4:5], 2, s[50:51]
	v_mul_f32_e32 v146, v146, v147
	v_cvt_pk_bf16_f32 v157, v146, v146
	v_or_b32_e32 v146, v142, v12
	v_mov_b32_e32 v147, v143
	v_lshlrev_b64 v[146:147], 8, v[146:147]
	v_or_b32_e32 v146, v146, v144
	v_lshl_add_u64 v[154:155], s[36:37], 0, v[146:147]
	global_store_short_d16_hi v[154:155], v157, off
	v_mul_f32_e32 v154, 0xbfb8aa3b, v145
	v_exp_f32_e32 v154, v154
	v_lshl_add_u64 v[146:147], s[38:39], 0, v[146:147]
	s_or_b64 s[12:13], vcc, s[12:13]
	v_mul_f32_e32 v154, v154, v156
	v_cvt_pk_bf16_f32 v154, v154, v154
	global_store_short_d16_hi v[146:147], v154, off
	v_sub_f32_e32 v146, v141, v145
	v_mul_f32_e32 v146, 0x3fb8aa3b, v146
	v_exp_f32_e32 v146, v146
	s_nop 0
	v_mul_f32_e32 v146, v146, v156
	v_cvt_pk_bf16_f32 v154, v146, v146
	v_and_or_b32 v220, v154, s98, v220
	ds_read_u16 v147, v45 offset:24576
	v_cndmask_b32_e64 v146, v248, v175, s[4:5]
	v_add_f32_e32 v145, v146, v145
	ds_read_u16 v146, v45 offset:8192
	s_waitcnt lgkmcnt(1)
	v_lshlrev_b32_e32 v156, 16, v147
	v_mul_f32_e32 v147, 0x3fb8aa3b, v145
	v_exp_f32_e32 v147, v147
	s_waitcnt lgkmcnt(0)
	v_lshlrev_b32_e32 v146, 16, v146
	v_mul_f32_e32 v146, 0x3db504f3, v146
	v_mul_f32_e32 v146, v146, v147
	v_cvt_pk_bf16_f32 v157, v146, v146
	v_or_b32_e32 v146, v142, v14
	v_mov_b32_e32 v147, v143
	v_lshlrev_b64 v[146:147], 8, v[146:147]
	v_or_b32_e32 v146, v146, v144
	v_lshl_add_u64 v[154:155], s[36:37], 0, v[146:147]
	global_store_short_d16_hi v[154:155], v157, off
	v_mul_f32_e32 v154, 0xbfb8aa3b, v145
	v_exp_f32_e32 v154, v154
	v_lshl_add_u64 v[146:147], s[38:39], 0, v[146:147]
	v_mul_f32_e32 v154, v154, v156
	v_cvt_pk_bf16_f32 v154, v154, v154
	global_store_short_d16_hi v[146:147], v154, off
	v_sub_f32_e32 v146, v141, v145
	v_mul_f32_e32 v146, 0x3fb8aa3b, v146
	v_exp_f32_e32 v146, v146
	v_mov_b32_e32 v155, v143
	v_mul_f32_e32 v146, v146, v156
	v_cvt_pk_bf16_f32 v154, v146, v146
	v_lshrrev_b32_e32 v221, 16, v154
	v_cndmask_b32_e64 v146, v243, v176, s[4:5]
	v_add_f32_e32 v145, v146, v145
	ds_read_u16 v146, v47 offset:8192
	v_mul_f32_e32 v154, 0x3fb8aa3b, v145
	v_exp_f32_e32 v154, v154
	s_waitcnt lgkmcnt(0)
	v_lshlrev_b32_e32 v147, 16, v146
	v_mul_f32_e32 v147, 0x3db504f3, v147
	v_mul_f32_e32 v147, v154, v147
	v_cvt_pk_bf16_f32 v147, v147, v147
	v_or_b32_e32 v154, v142, v16
	v_lshlrev_b64 v[154:155], 8, v[154:155]
	v_or_b32_e32 v154, v154, v144
	ds_read_u16 v146, v47 offset:24576
	v_lshl_add_u64 v[156:157], s[36:37], 0, v[154:155]
	global_store_short_d16_hi v[156:157], v147, off
	v_mul_f32_e32 v147, 0xbfb8aa3b, v145
	v_exp_f32_e32 v147, v147
	s_waitcnt lgkmcnt(0)
	v_lshlrev_b32_e32 v146, 16, v146
	v_lshl_add_u64 v[154:155], s[38:39], 0, v[154:155]
	v_mul_f32_e32 v147, v147, v146
	v_cvt_pk_bf16_f32 v147, v147, v147
	global_store_short_d16_hi v[154:155], v147, off
	v_sub_f32_e32 v147, v141, v145
	v_mul_f32_e32 v147, 0x3fb8aa3b, v147
	v_exp_f32_e32 v147, v147
	s_nop 0
	v_mul_f32_e32 v146, v147, v146
	v_cvt_pk_bf16_f32 v154, v146, v146
	v_and_or_b32 v221, v154, s98, v221
	ds_read_u16 v147, v49 offset:24576
	v_cndmask_b32_e64 v146, v250, v177, s[4:5]
	v_add_f32_e32 v145, v146, v145
	ds_read_u16 v146, v49 offset:8192
	s_waitcnt lgkmcnt(1)
	v_lshlrev_b32_e32 v156, 16, v147
	v_mul_f32_e32 v147, 0x3fb8aa3b, v145
	v_exp_f32_e32 v147, v147
	s_waitcnt lgkmcnt(0)
	v_lshlrev_b32_e32 v146, 16, v146
	v_mul_f32_e32 v146, 0x3db504f3, v146
	v_mul_f32_e32 v146, v147, v146
	v_cvt_pk_bf16_f32 v157, v146, v146
	v_or_b32_e32 v146, v142, v18
	v_mov_b32_e32 v147, v143
	v_lshlrev_b64 v[146:147], 8, v[146:147]
	v_or_b32_e32 v146, v146, v144
	v_lshl_add_u64 v[154:155], s[36:37], 0, v[146:147]
	global_store_short_d16_hi v[154:155], v157, off
	v_mul_f32_e32 v154, 0xbfb8aa3b, v145
	v_exp_f32_e32 v154, v154
	v_lshl_add_u64 v[146:147], s[38:39], 0, v[146:147]
	v_mul_f32_e32 v154, v154, v156
	v_cvt_pk_bf16_f32 v154, v154, v154
	global_store_short_d16_hi v[146:147], v154, off
	v_sub_f32_e32 v146, v141, v145
	v_mul_f32_e32 v146, 0x3fb8aa3b, v146
	v_exp_f32_e32 v146, v146
	s_nop 0
	v_mul_f32_e32 v146, v146, v156
	v_cvt_pk_bf16_f32 v154, v146, v146
	v_lshrrev_b32_e32 v222, 16, v154
	ds_read_u16 v147, v51 offset:24576
	v_cndmask_b32_e64 v146, v249, v178, s[4:5]
	v_add_f32_e32 v145, v146, v145
	ds_read_u16 v146, v51 offset:8192
	s_waitcnt lgkmcnt(1)
	v_lshlrev_b32_e32 v156, 16, v147
	v_mul_f32_e32 v147, 0x3fb8aa3b, v145
	v_exp_f32_e32 v147, v147
	s_waitcnt lgkmcnt(0)
	v_lshlrev_b32_e32 v146, 16, v146
	v_mul_f32_e32 v146, 0x3db504f3, v146
	v_mul_f32_e32 v146, v147, v146
	v_cvt_pk_bf16_f32 v157, v146, v146
	v_or_b32_e32 v146, v142, v20
	v_mov_b32_e32 v147, v143
	v_lshlrev_b64 v[146:147], 8, v[146:147]
	v_or_b32_e32 v146, v146, v144
	v_lshl_add_u64 v[154:155], s[36:37], 0, v[146:147]
	global_store_short_d16_hi v[154:155], v157, off
	v_mul_f32_e32 v154, 0xbfb8aa3b, v145
	v_exp_f32_e32 v154, v154
	v_lshl_add_u64 v[146:147], s[38:39], 0, v[146:147]
	v_mul_f32_e32 v154, v154, v156
	v_cvt_pk_bf16_f32 v154, v154, v154
	global_store_short_d16_hi v[146:147], v154, off
	v_sub_f32_e32 v146, v141, v145
	v_mul_f32_e32 v146, 0x3fb8aa3b, v146
	v_exp_f32_e32 v146, v146
	s_nop 0
	v_mul_f32_e32 v146, v146, v156
	v_cvt_pk_bf16_f32 v154, v146, v146
	v_and_or_b32 v222, v154, s98, v222
	ds_read_u16 v147, v53 offset:24576
	v_cndmask_b32_e64 v146, v245, v179, s[4:5]
	v_add_f32_e32 v145, v146, v145
	ds_read_u16 v146, v53 offset:8192
	s_waitcnt lgkmcnt(1)
	v_lshlrev_b32_e32 v156, 16, v147
	v_mul_f32_e32 v147, 0x3fb8aa3b, v145
	v_exp_f32_e32 v147, v147
	s_waitcnt lgkmcnt(0)
	v_lshlrev_b32_e32 v146, 16, v146
	v_mul_f32_e32 v146, 0x3db504f3, v146
	v_mul_f32_e32 v146, v147, v146
	v_cvt_pk_bf16_f32 v157, v146, v146
	v_or_b32_e32 v146, v142, v22
	v_mov_b32_e32 v147, v143
	v_lshlrev_b64 v[146:147], 8, v[146:147]
	v_or_b32_e32 v146, v146, v144
	v_lshl_add_u64 v[154:155], s[36:37], 0, v[146:147]
	global_store_short_d16_hi v[154:155], v157, off
	v_mul_f32_e32 v154, 0xbfb8aa3b, v145
	v_exp_f32_e32 v154, v154
	v_lshl_add_u64 v[146:147], s[38:39], 0, v[146:147]
	v_mul_f32_e32 v154, v154, v156
	v_cvt_pk_bf16_f32 v154, v154, v154
	global_store_short_d16_hi v[146:147], v154, off
	v_sub_f32_e32 v146, v141, v145
	v_mul_f32_e32 v146, 0x3fb8aa3b, v146
	v_exp_f32_e32 v146, v146
	s_nop 0
	v_mul_f32_e32 v146, v146, v156
	v_cvt_pk_bf16_f32 v154, v146, v146
	v_lshrrev_b32_e32 v223, 16, v154
	ds_read_u16 v147, v55 offset:24576
	v_cndmask_b32_e64 v146, v239, v180, s[4:5]
	v_add_f32_e32 v145, v146, v145
	ds_read_u16 v146, v55 offset:8192
	s_waitcnt lgkmcnt(1)
	v_lshlrev_b32_e32 v156, 16, v147
	v_mul_f32_e32 v147, 0x3fb8aa3b, v145
	v_exp_f32_e32 v147, v147
	s_waitcnt lgkmcnt(0)
	v_lshlrev_b32_e32 v146, 16, v146
	v_mul_f32_e32 v146, 0x3db504f3, v146
	v_mul_f32_e32 v146, v147, v146
	v_cvt_pk_bf16_f32 v157, v146, v146
	v_or_b32_e32 v146, v142, v24
	v_mov_b32_e32 v147, v143
	v_lshlrev_b64 v[146:147], 8, v[146:147]
	v_or_b32_e32 v146, v146, v144
	v_lshl_add_u64 v[154:155], s[36:37], 0, v[146:147]
	global_store_short_d16_hi v[154:155], v157, off
	v_mul_f32_e32 v154, 0xbfb8aa3b, v145
	v_exp_f32_e32 v154, v154
	v_lshl_add_u64 v[146:147], s[38:39], 0, v[146:147]
	v_mul_f32_e32 v154, v154, v156
	v_cvt_pk_bf16_f32 v154, v154, v154
	global_store_short_d16_hi v[146:147], v154, off
	v_sub_f32_e32 v146, v141, v145
	v_mul_f32_e32 v146, 0x3fb8aa3b, v146
	v_exp_f32_e32 v146, v146
	s_nop 0
	v_mul_f32_e32 v146, v146, v156
	v_cvt_pk_bf16_f32 v154, v146, v146
	v_lshlrev_b32_e32 v146, 1, v24
	v_mov_b32_e32 v147, v3
	v_lshl_add_u64 v[146:147], v[6:7], 0, v[146:147]
	v_and_or_b32 v223, v154, s98, v223
	v_alignbit_b32 v226, v223, v223, 16
	v_alignbit_b32 v218, v220, v220, 16
	v_cndmask_b32_e64 v220, v226, v220, s[4:5]
	v_cndmask_b32_e64 v223, v218, v223, s[4:5]
	v_alignbit_b32 v226, v222, v222, 16
	v_alignbit_b32 v218, v221, v221, 16
	v_cndmask_b32_e64 v221, v226, v221, s[4:5]
	v_cndmask_b32_e64 v222, v218, v222, s[4:5]
	v_lshl_add_u64 v[218:219], v[146:147], 0, v[224:225]
	global_store_dwordx4 v[218:219], v[220:223], off
	s_nop 1
	ds_read_u16 v147, v57 offset:24576
	v_cndmask_b32_e64 v146, v247, v181, s[4:5]
	v_add_f32_e32 v145, v146, v145
	ds_read_u16 v146, v57 offset:8192
	s_waitcnt lgkmcnt(1)
	v_lshlrev_b32_e32 v156, 16, v147
	v_mul_f32_e32 v147, 0x3fb8aa3b, v145
	v_exp_f32_e32 v147, v147
	s_waitcnt lgkmcnt(0)
	v_lshlrev_b32_e32 v146, 16, v146
	v_mul_f32_e32 v146, 0x3db504f3, v146
	v_mul_f32_e32 v146, v147, v146
	v_cvt_pk_bf16_f32 v157, v146, v146
	v_or_b32_e32 v146, v142, v26
	v_mov_b32_e32 v147, v143
	v_lshlrev_b64 v[146:147], 8, v[146:147]
	v_or_b32_e32 v146, v146, v144
	v_lshl_add_u64 v[154:155], s[36:37], 0, v[146:147]
	global_store_short_d16_hi v[154:155], v157, off
	v_mul_f32_e32 v154, 0xbfb8aa3b, v145
	v_exp_f32_e32 v154, v154
	v_lshl_add_u64 v[146:147], s[38:39], 0, v[146:147]
	v_mul_f32_e32 v154, v154, v156
	v_cvt_pk_bf16_f32 v154, v154, v154
	global_store_short_d16_hi v[146:147], v154, off
	v_sub_f32_e32 v146, v141, v145
	v_mul_f32_e32 v146, 0x3fb8aa3b, v146
	v_exp_f32_e32 v146, v146
	s_nop 0
	v_mul_f32_e32 v146, v146, v156
	v_cvt_pk_bf16_f32 v154, v146, v146
	v_lshrrev_b32_e32 v220, 16, v154
	ds_read_u16 v147, v59 offset:24576
	v_cndmask_b32_e64 v146, v246, v182, s[4:5]
	v_add_f32_e32 v145, v146, v145
	ds_read_u16 v146, v59 offset:8192
	s_waitcnt lgkmcnt(1)
	v_lshlrev_b32_e32 v156, 16, v147
	v_mul_f32_e32 v147, 0x3fb8aa3b, v145
	v_exp_f32_e32 v147, v147
	s_waitcnt lgkmcnt(0)
	v_lshlrev_b32_e32 v146, 16, v146
	v_mul_f32_e32 v146, 0x3db504f3, v146
	v_mul_f32_e32 v146, v147, v146
	v_cvt_pk_bf16_f32 v157, v146, v146
	v_or_b32_e32 v146, v142, v28
	v_mov_b32_e32 v147, v143
	v_lshlrev_b64 v[146:147], 8, v[146:147]
	v_or_b32_e32 v146, v146, v144
	v_lshl_add_u64 v[154:155], s[36:37], 0, v[146:147]
	global_store_short_d16_hi v[154:155], v157, off
	v_mul_f32_e32 v154, 0xbfb8aa3b, v145
	v_exp_f32_e32 v154, v154
	v_lshl_add_u64 v[146:147], s[38:39], 0, v[146:147]
	v_mul_f32_e32 v154, v154, v156
	v_cvt_pk_bf16_f32 v154, v154, v154
	global_store_short_d16_hi v[146:147], v154, off
	v_sub_f32_e32 v146, v141, v145
	v_mul_f32_e32 v146, 0x3fb8aa3b, v146
	v_exp_f32_e32 v146, v146
	s_nop 0
	v_mul_f32_e32 v146, v146, v156
	v_cvt_pk_bf16_f32 v154, v146, v146
	v_and_or_b32 v220, v154, s98, v220
	ds_read_u16 v147, v61 offset:24576
	v_cndmask_b32_e64 v146, v241, v183, s[4:5]
	v_add_f32_e32 v145, v146, v145
	ds_read_u16 v146, v61 offset:8192
	s_waitcnt lgkmcnt(1)
	v_lshlrev_b32_e32 v156, 16, v147
	v_mul_f32_e32 v147, 0x3fb8aa3b, v145
	v_exp_f32_e32 v147, v147
	s_waitcnt lgkmcnt(0)
	v_lshlrev_b32_e32 v146, 16, v146
	v_mul_f32_e32 v146, 0x3db504f3, v146
	v_mul_f32_e32 v146, v147, v146
	v_cvt_pk_bf16_f32 v157, v146, v146
	v_or_b32_e32 v146, v142, v30
	v_mov_b32_e32 v147, v143
	v_lshlrev_b64 v[146:147], 8, v[146:147]
	v_or_b32_e32 v146, v146, v144
	v_lshl_add_u64 v[154:155], s[36:37], 0, v[146:147]
	global_store_short_d16_hi v[154:155], v157, off
	v_mul_f32_e32 v154, 0xbfb8aa3b, v145
	v_exp_f32_e32 v154, v154
	v_lshl_add_u64 v[146:147], s[38:39], 0, v[146:147]
	v_mul_f32_e32 v154, v154, v156
	v_cvt_pk_bf16_f32 v154, v154, v154
	global_store_short_d16_hi v[146:147], v154, off
	v_sub_f32_e32 v146, v141, v145
	v_mul_f32_e32 v146, 0x3fb8aa3b, v146
	v_exp_f32_e32 v146, v146
	s_nop 0
	v_mul_f32_e32 v146, v146, v156
	v_cvt_pk_bf16_f32 v154, v146, v146
	v_lshrrev_b32_e32 v221, 16, v154
	ds_read_u16 v147, v63 offset:24576
	v_cndmask_b32_e64 v146, v235, v184, s[4:5]
	v_add_f32_e32 v145, v146, v145
	ds_read_u16 v146, v63 offset:8192
	s_waitcnt lgkmcnt(1)
	v_lshlrev_b32_e32 v156, 16, v147
	v_mul_f32_e32 v147, 0x3fb8aa3b, v145
	v_exp_f32_e32 v147, v147
	s_waitcnt lgkmcnt(0)
	v_lshlrev_b32_e32 v146, 16, v146
	v_mul_f32_e32 v146, 0x3db504f3, v146
	v_mul_f32_e32 v146, v147, v146
	v_cvt_pk_bf16_f32 v157, v146, v146
	v_or_b32_e32 v146, v142, v32
	v_mov_b32_e32 v147, v143
	v_lshlrev_b64 v[146:147], 8, v[146:147]
	v_or_b32_e32 v146, v146, v144
	v_lshl_add_u64 v[154:155], s[36:37], 0, v[146:147]
	global_store_short_d16_hi v[154:155], v157, off
	v_mul_f32_e32 v154, 0xbfb8aa3b, v145
	v_exp_f32_e32 v154, v154
	v_lshl_add_u64 v[146:147], s[38:39], 0, v[146:147]
	v_mul_f32_e32 v154, v154, v156
	v_cvt_pk_bf16_f32 v154, v154, v154
	global_store_short_d16_hi v[146:147], v154, off
	v_sub_f32_e32 v146, v141, v145
	v_mul_f32_e32 v146, 0x3fb8aa3b, v146
	v_exp_f32_e32 v146, v146
	s_nop 0
	v_mul_f32_e32 v146, v146, v156
	v_cvt_pk_bf16_f32 v154, v146, v146
	v_and_or_b32 v221, v154, s98, v221
	ds_read_u16 v147, v65 offset:24576
	v_cndmask_b32_e64 v146, v244, v185, s[4:5]
	v_add_f32_e32 v145, v146, v145
	ds_read_u16 v146, v65 offset:8192
	s_waitcnt lgkmcnt(1)
	v_lshlrev_b32_e32 v156, 16, v147
	v_mul_f32_e32 v147, 0x3fb8aa3b, v145
	v_exp_f32_e32 v147, v147
	s_waitcnt lgkmcnt(0)
	v_lshlrev_b32_e32 v146, 16, v146
	v_mul_f32_e32 v146, 0x3db504f3, v146
	v_mul_f32_e32 v146, v147, v146
	v_cvt_pk_bf16_f32 v157, v146, v146
	v_or_b32_e32 v146, v142, v34
	v_mov_b32_e32 v147, v143
	v_lshlrev_b64 v[146:147], 8, v[146:147]
	v_or_b32_e32 v146, v146, v144
	v_lshl_add_u64 v[154:155], s[36:37], 0, v[146:147]
	global_store_short_d16_hi v[154:155], v157, off
	v_mul_f32_e32 v154, 0xbfb8aa3b, v145
	v_exp_f32_e32 v154, v154
	v_lshl_add_u64 v[146:147], s[38:39], 0, v[146:147]
	v_mul_f32_e32 v154, v154, v156
	v_cvt_pk_bf16_f32 v154, v154, v154
	global_store_short_d16_hi v[146:147], v154, off
	v_sub_f32_e32 v146, v141, v145
	v_mul_f32_e32 v146, 0x3fb8aa3b, v146
	v_exp_f32_e32 v146, v146
	s_nop 0
	v_mul_f32_e32 v146, v146, v156
	v_cvt_pk_bf16_f32 v154, v146, v146
	v_lshrrev_b32_e32 v222, 16, v154
	ds_read_u16 v147, v67 offset:24576
	v_cndmask_b32_e64 v146, v242, v186, s[4:5]
	v_add_f32_e32 v145, v146, v145
	ds_read_u16 v146, v67 offset:8192
	s_waitcnt lgkmcnt(1)
	v_lshlrev_b32_e32 v156, 16, v147
	v_mul_f32_e32 v147, 0x3fb8aa3b, v145
	v_exp_f32_e32 v147, v147
	s_waitcnt lgkmcnt(0)
	v_lshlrev_b32_e32 v146, 16, v146
	v_mul_f32_e32 v146, 0x3db504f3, v146
	v_mul_f32_e32 v146, v147, v146
	v_cvt_pk_bf16_f32 v157, v146, v146
	v_or_b32_e32 v146, v142, v38
	v_mov_b32_e32 v147, v143
	v_lshlrev_b64 v[146:147], 8, v[146:147]
	v_or_b32_e32 v146, v146, v144
	v_lshl_add_u64 v[154:155], s[36:37], 0, v[146:147]
	global_store_short_d16_hi v[154:155], v157, off
	v_mul_f32_e32 v154, 0xbfb8aa3b, v145
	v_exp_f32_e32 v154, v154
	v_lshl_add_u64 v[146:147], s[38:39], 0, v[146:147]
	v_mul_f32_e32 v154, v154, v156
	v_cvt_pk_bf16_f32 v154, v154, v154
	global_store_short_d16_hi v[146:147], v154, off
	v_sub_f32_e32 v146, v141, v145
	v_mul_f32_e32 v146, 0x3fb8aa3b, v146
	v_exp_f32_e32 v146, v146
	s_nop 0
	v_mul_f32_e32 v146, v146, v156
	v_cvt_pk_bf16_f32 v154, v146, v146
	v_and_or_b32 v222, v154, s98, v222
	ds_read_u16 v147, v69 offset:24576
	v_cndmask_b32_e64 v146, v237, v187, s[4:5]
	v_add_f32_e32 v145, v146, v145
	ds_read_u16 v146, v69 offset:8192
	s_waitcnt lgkmcnt(1)
	v_lshlrev_b32_e32 v156, 16, v147
	v_mul_f32_e32 v147, 0x3fb8aa3b, v145
	v_exp_f32_e32 v147, v147
	s_waitcnt lgkmcnt(0)
	v_lshlrev_b32_e32 v146, 16, v146
	v_mul_f32_e32 v146, 0x3db504f3, v146
	v_mul_f32_e32 v146, v147, v146
	v_cvt_pk_bf16_f32 v157, v146, v146
	v_or_b32_e32 v146, v142, v40
	v_mov_b32_e32 v147, v143
	v_lshlrev_b64 v[146:147], 8, v[146:147]
	v_or_b32_e32 v146, v146, v144
	v_lshl_add_u64 v[154:155], s[36:37], 0, v[146:147]
	global_store_short_d16_hi v[154:155], v157, off
	v_mul_f32_e32 v154, 0xbfb8aa3b, v145
	v_exp_f32_e32 v154, v154
	v_lshl_add_u64 v[146:147], s[38:39], 0, v[146:147]
	v_mul_f32_e32 v154, v154, v156
	v_cvt_pk_bf16_f32 v154, v154, v154
	global_store_short_d16_hi v[146:147], v154, off
	v_sub_f32_e32 v146, v141, v145
	v_mul_f32_e32 v146, 0x3fb8aa3b, v146
	v_exp_f32_e32 v146, v146
	s_nop 0
	v_mul_f32_e32 v146, v146, v156
	v_cvt_pk_bf16_f32 v154, v146, v146
	v_lshrrev_b32_e32 v223, 16, v154
	ds_read_u16 v147, v71 offset:24576
	v_cndmask_b32_e64 v146, v215, v188, s[4:5]
	v_add_f32_e32 v145, v146, v145
	ds_read_u16 v146, v71 offset:8192
	s_waitcnt lgkmcnt(1)
	v_lshlrev_b32_e32 v156, 16, v147
	v_mul_f32_e32 v147, 0x3fb8aa3b, v145
	v_exp_f32_e32 v147, v147
	s_waitcnt lgkmcnt(0)
	v_lshlrev_b32_e32 v146, 16, v146
	v_mul_f32_e32 v146, 0x3db504f3, v146
	v_mul_f32_e32 v146, v147, v146
	v_cvt_pk_bf16_f32 v157, v146, v146
	v_or_b32_e32 v146, v142, v42
	v_mov_b32_e32 v147, v143
	v_lshlrev_b64 v[146:147], 8, v[146:147]
	v_or_b32_e32 v146, v146, v144
	v_lshl_add_u64 v[154:155], s[36:37], 0, v[146:147]
	global_store_short_d16_hi v[154:155], v157, off
	v_mul_f32_e32 v154, 0xbfb8aa3b, v145
	v_exp_f32_e32 v154, v154
	v_lshl_add_u64 v[146:147], s[38:39], 0, v[146:147]
	v_mul_f32_e32 v154, v154, v156
	v_cvt_pk_bf16_f32 v154, v154, v154
	global_store_short_d16_hi v[146:147], v154, off
	v_sub_f32_e32 v146, v141, v145
	v_mul_f32_e32 v146, 0x3fb8aa3b, v146
	v_exp_f32_e32 v146, v146
	s_nop 0
	v_mul_f32_e32 v146, v146, v156
	v_cvt_pk_bf16_f32 v154, v146, v146
	v_lshlrev_b32_e32 v146, 1, v42
	v_mov_b32_e32 v147, v3
	v_lshl_add_u64 v[146:147], v[6:7], 0, v[146:147]
	v_and_or_b32 v223, v154, s98, v223
	v_alignbit_b32 v226, v223, v223, 16
	v_alignbit_b32 v218, v220, v220, 16
	v_cndmask_b32_e64 v220, v226, v220, s[4:5]
	v_cndmask_b32_e64 v223, v218, v223, s[4:5]
	v_alignbit_b32 v226, v222, v222, 16
	v_alignbit_b32 v218, v221, v221, 16
	v_cndmask_b32_e64 v221, v226, v221, s[4:5]
	v_cndmask_b32_e64 v222, v218, v222, s[4:5]
	v_lshl_add_u64 v[218:219], v[146:147], 0, v[224:225]
	global_store_dwordx4 v[218:219], v[220:223], off
	s_nop 1
	ds_read_u16 v147, v73 offset:24576
	v_cndmask_b32_e64 v146, v240, v189, s[4:5]
	v_add_f32_e32 v145, v146, v145
	ds_read_u16 v146, v73 offset:8192
	s_waitcnt lgkmcnt(1)
	v_lshlrev_b32_e32 v156, 16, v147
	v_mul_f32_e32 v147, 0x3fb8aa3b, v145
	v_exp_f32_e32 v147, v147
	s_waitcnt lgkmcnt(0)
	v_lshlrev_b32_e32 v146, 16, v146
	v_mul_f32_e32 v146, 0x3db504f3, v146
	v_mul_f32_e32 v146, v147, v146
	v_cvt_pk_bf16_f32 v157, v146, v146
	v_or_b32_e32 v146, v142, v44
	v_mov_b32_e32 v147, v143
	v_lshlrev_b64 v[146:147], 8, v[146:147]
	v_or_b32_e32 v146, v146, v144
	v_lshl_add_u64 v[154:155], s[36:37], 0, v[146:147]
	global_store_short_d16_hi v[154:155], v157, off
	v_mul_f32_e32 v154, 0xbfb8aa3b, v145
	v_exp_f32_e32 v154, v154
	v_lshl_add_u64 v[146:147], s[38:39], 0, v[146:147]
	v_mul_f32_e32 v154, v154, v156
	v_cvt_pk_bf16_f32 v154, v154, v154
	global_store_short_d16_hi v[146:147], v154, off
	v_sub_f32_e32 v146, v141, v145
	v_mul_f32_e32 v146, 0x3fb8aa3b, v146
	v_exp_f32_e32 v146, v146
	s_nop 0
	v_mul_f32_e32 v146, v146, v156
	v_cvt_pk_bf16_f32 v154, v146, v146
	v_lshrrev_b32_e32 v220, 16, v154
	ds_read_u16 v147, v75 offset:24576
	v_cndmask_b32_e64 v146, v238, v190, s[4:5]
	v_add_f32_e32 v145, v146, v145
	ds_read_u16 v146, v75 offset:8192
	s_waitcnt lgkmcnt(1)
	v_lshlrev_b32_e32 v156, 16, v147
	v_mul_f32_e32 v147, 0x3fb8aa3b, v145
	v_exp_f32_e32 v147, v147
	s_waitcnt lgkmcnt(0)
	v_lshlrev_b32_e32 v146, 16, v146
	v_mul_f32_e32 v146, 0x3db504f3, v146
	v_mul_f32_e32 v146, v147, v146
	v_cvt_pk_bf16_f32 v157, v146, v146
	v_or_b32_e32 v146, v142, v46
	v_mov_b32_e32 v147, v143
	v_lshlrev_b64 v[146:147], 8, v[146:147]
	v_or_b32_e32 v146, v146, v144
	v_lshl_add_u64 v[154:155], s[36:37], 0, v[146:147]
	global_store_short_d16_hi v[154:155], v157, off
	v_mul_f32_e32 v154, 0xbfb8aa3b, v145
	v_exp_f32_e32 v154, v154
	v_lshl_add_u64 v[146:147], s[38:39], 0, v[146:147]
	v_mul_f32_e32 v154, v154, v156
	v_cvt_pk_bf16_f32 v154, v154, v154
	global_store_short_d16_hi v[146:147], v154, off
	v_sub_f32_e32 v146, v141, v145
	v_mul_f32_e32 v146, 0x3fb8aa3b, v146
	v_exp_f32_e32 v146, v146
	s_nop 0
	v_mul_f32_e32 v146, v146, v156
	v_cvt_pk_bf16_f32 v154, v146, v146
	v_and_or_b32 v220, v154, s98, v220
	ds_read_u16 v147, v77 offset:24576
	v_cndmask_b32_e64 v146, v217, v191, s[4:5]
	v_add_f32_e32 v145, v146, v145
	ds_read_u16 v146, v77 offset:8192
	s_waitcnt lgkmcnt(1)
	v_lshlrev_b32_e32 v156, 16, v147
	v_mul_f32_e32 v147, 0x3fb8aa3b, v145
	v_exp_f32_e32 v147, v147
	s_waitcnt lgkmcnt(0)
	v_lshlrev_b32_e32 v146, 16, v146
	v_mul_f32_e32 v146, 0x3db504f3, v146
	v_mul_f32_e32 v146, v147, v146
	v_cvt_pk_bf16_f32 v157, v146, v146
	v_or_b32_e32 v146, v142, v48
	v_mov_b32_e32 v147, v143
	v_lshlrev_b64 v[146:147], 8, v[146:147]
	v_or_b32_e32 v146, v146, v144
	v_lshl_add_u64 v[154:155], s[36:37], 0, v[146:147]
	global_store_short_d16_hi v[154:155], v157, off
	v_mul_f32_e32 v154, 0xbfb8aa3b, v145
	v_exp_f32_e32 v154, v154
	v_lshl_add_u64 v[146:147], s[38:39], 0, v[146:147]
	v_mul_f32_e32 v154, v154, v156
	v_cvt_pk_bf16_f32 v154, v154, v154
	global_store_short_d16_hi v[146:147], v154, off
	v_sub_f32_e32 v146, v141, v145
	v_mul_f32_e32 v146, 0x3fb8aa3b, v146
	v_exp_f32_e32 v146, v146
	s_nop 0
	v_mul_f32_e32 v146, v146, v156
	v_cvt_pk_bf16_f32 v154, v146, v146
	v_lshrrev_b32_e32 v221, 16, v154
	ds_read_u16 v147, v79 offset:24576
	v_cndmask_b32_e64 v146, v211, v192, s[4:5]
	v_add_f32_e32 v145, v146, v145
	ds_read_u16 v146, v79 offset:8192
	s_waitcnt lgkmcnt(1)
	v_lshlrev_b32_e32 v156, 16, v147
	v_mul_f32_e32 v147, 0x3fb8aa3b, v145
	v_exp_f32_e32 v147, v147
	s_waitcnt lgkmcnt(0)
	v_lshlrev_b32_e32 v146, 16, v146
	v_mul_f32_e32 v146, 0x3db504f3, v146
	v_mul_f32_e32 v146, v147, v146
	v_cvt_pk_bf16_f32 v157, v146, v146
	v_or_b32_e32 v146, v142, v50
	v_mov_b32_e32 v147, v143
	v_lshlrev_b64 v[146:147], 8, v[146:147]
	v_or_b32_e32 v146, v146, v144
	v_lshl_add_u64 v[154:155], s[36:37], 0, v[146:147]
	global_store_short_d16_hi v[154:155], v157, off
	v_mul_f32_e32 v154, 0xbfb8aa3b, v145
	v_exp_f32_e32 v154, v154
	v_lshl_add_u64 v[146:147], s[38:39], 0, v[146:147]
	v_mul_f32_e32 v154, v154, v156
	v_cvt_pk_bf16_f32 v154, v154, v154
	global_store_short_d16_hi v[146:147], v154, off
	v_sub_f32_e32 v146, v141, v145
	v_mul_f32_e32 v146, 0x3fb8aa3b, v146
	v_exp_f32_e32 v146, v146
	s_nop 0
	v_mul_f32_e32 v146, v146, v156
	v_cvt_pk_bf16_f32 v154, v146, v146
	v_and_or_b32 v221, v154, s98, v221
	ds_read_u16 v147, v81 offset:24576
	v_cndmask_b32_e64 v146, v236, v193, s[4:5]
	v_add_f32_e32 v145, v146, v145
	ds_read_u16 v146, v81 offset:8192
	s_waitcnt lgkmcnt(1)
	v_lshlrev_b32_e32 v156, 16, v147
	v_mul_f32_e32 v147, 0x3fb8aa3b, v145
	v_exp_f32_e32 v147, v147
	s_waitcnt lgkmcnt(0)
	v_lshlrev_b32_e32 v146, 16, v146
	v_mul_f32_e32 v146, 0x3db504f3, v146
	v_mul_f32_e32 v146, v147, v146
	v_cvt_pk_bf16_f32 v157, v146, v146
	v_or_b32_e32 v146, v142, v52
	v_mov_b32_e32 v147, v143
	v_lshlrev_b64 v[146:147], 8, v[146:147]
	v_or_b32_e32 v146, v146, v144
	v_lshl_add_u64 v[154:155], s[36:37], 0, v[146:147]
	global_store_short_d16_hi v[154:155], v157, off
	v_mul_f32_e32 v154, 0xbfb8aa3b, v145
	v_exp_f32_e32 v154, v154
	v_lshl_add_u64 v[146:147], s[38:39], 0, v[146:147]
	v_mul_f32_e32 v154, v154, v156
	v_cvt_pk_bf16_f32 v154, v154, v154
	global_store_short_d16_hi v[146:147], v154, off
	v_sub_f32_e32 v146, v141, v145
	v_mul_f32_e32 v146, 0x3fb8aa3b, v146
	v_exp_f32_e32 v146, v146
	s_nop 0
	v_mul_f32_e32 v146, v146, v156
	v_cvt_pk_bf16_f32 v154, v146, v146
	v_lshrrev_b32_e32 v222, 16, v154
	ds_read_u16 v147, v83 offset:24576
	v_cndmask_b32_e64 v146, v234, v194, s[4:5]
	v_add_f32_e32 v145, v146, v145
	ds_read_u16 v146, v83 offset:8192
	s_waitcnt lgkmcnt(1)
	v_lshlrev_b32_e32 v156, 16, v147
	v_mul_f32_e32 v147, 0x3fb8aa3b, v145
	v_exp_f32_e32 v147, v147
	s_waitcnt lgkmcnt(0)
	v_lshlrev_b32_e32 v146, 16, v146
	v_mul_f32_e32 v146, 0x3db504f3, v146
	v_mul_f32_e32 v146, v147, v146
	v_cvt_pk_bf16_f32 v157, v146, v146
	v_or_b32_e32 v146, v142, v54
	v_mov_b32_e32 v147, v143
	v_lshlrev_b64 v[146:147], 8, v[146:147]
	v_or_b32_e32 v146, v146, v144
	v_lshl_add_u64 v[154:155], s[36:37], 0, v[146:147]
	global_store_short_d16_hi v[154:155], v157, off
	v_mul_f32_e32 v154, 0xbfb8aa3b, v145
	v_exp_f32_e32 v154, v154
	v_lshl_add_u64 v[146:147], s[38:39], 0, v[146:147]
	v_mul_f32_e32 v154, v154, v156
	v_cvt_pk_bf16_f32 v154, v154, v154
	global_store_short_d16_hi v[146:147], v154, off
	v_sub_f32_e32 v146, v141, v145
	v_mul_f32_e32 v146, 0x3fb8aa3b, v146
	v_exp_f32_e32 v146, v146
	s_nop 0
	v_mul_f32_e32 v146, v146, v156
	v_cvt_pk_bf16_f32 v154, v146, v146
	v_and_or_b32 v222, v154, s98, v222
	ds_read_u16 v147, v85 offset:24576
	v_cndmask_b32_e64 v146, v213, v195, s[4:5]
	v_add_f32_e32 v145, v146, v145
	ds_read_u16 v146, v85 offset:8192
	s_waitcnt lgkmcnt(1)
	v_lshlrev_b32_e32 v156, 16, v147
	v_mul_f32_e32 v147, 0x3fb8aa3b, v145
	v_exp_f32_e32 v147, v147
	s_waitcnt lgkmcnt(0)
	v_lshlrev_b32_e32 v146, 16, v146
	v_mul_f32_e32 v146, 0x3db504f3, v146
	v_mul_f32_e32 v146, v147, v146
	v_cvt_pk_bf16_f32 v157, v146, v146
	v_or_b32_e32 v146, v142, v56
	v_mov_b32_e32 v147, v143
	v_lshlrev_b64 v[146:147], 8, v[146:147]
	v_or_b32_e32 v146, v146, v144
	v_lshl_add_u64 v[154:155], s[36:37], 0, v[146:147]
	global_store_short_d16_hi v[154:155], v157, off
	v_mul_f32_e32 v154, 0xbfb8aa3b, v145
	v_exp_f32_e32 v154, v154
	v_lshl_add_u64 v[146:147], s[38:39], 0, v[146:147]
	v_mul_f32_e32 v154, v154, v156
	v_cvt_pk_bf16_f32 v154, v154, v154
	global_store_short_d16_hi v[146:147], v154, off
	v_sub_f32_e32 v146, v141, v145
	v_mul_f32_e32 v146, 0x3fb8aa3b, v146
	v_exp_f32_e32 v146, v146
	s_nop 0
	v_mul_f32_e32 v146, v146, v156
	v_cvt_pk_bf16_f32 v154, v146, v146
	v_lshrrev_b32_e32 v223, 16, v154
	ds_read_u16 v147, v87 offset:24576
	v_cndmask_b32_e64 v146, v208, v196, s[4:5]
	v_add_f32_e32 v145, v146, v145
	ds_read_u16 v146, v87 offset:8192
	s_waitcnt lgkmcnt(1)
	v_lshlrev_b32_e32 v156, 16, v147
	v_mul_f32_e32 v147, 0x3fb8aa3b, v145
	v_exp_f32_e32 v147, v147
	s_waitcnt lgkmcnt(0)
	v_lshlrev_b32_e32 v146, 16, v146
	v_mul_f32_e32 v146, 0x3db504f3, v146
	v_mul_f32_e32 v146, v147, v146
	v_cvt_pk_bf16_f32 v157, v146, v146
	v_or_b32_e32 v146, v142, v58
	v_mov_b32_e32 v147, v143
	v_lshlrev_b64 v[146:147], 8, v[146:147]
	v_or_b32_e32 v146, v146, v144
	v_lshl_add_u64 v[154:155], s[36:37], 0, v[146:147]
	global_store_short_d16_hi v[154:155], v157, off
	v_mul_f32_e32 v154, 0xbfb8aa3b, v145
	v_exp_f32_e32 v154, v154
	v_lshl_add_u64 v[146:147], s[38:39], 0, v[146:147]
	v_mul_f32_e32 v154, v154, v156
	v_cvt_pk_bf16_f32 v154, v154, v154
	global_store_short_d16_hi v[146:147], v154, off
	v_sub_f32_e32 v146, v141, v145
	v_mul_f32_e32 v146, 0x3fb8aa3b, v146
	v_exp_f32_e32 v146, v146
	s_nop 0
	v_mul_f32_e32 v146, v146, v156
	v_cvt_pk_bf16_f32 v154, v146, v146
	v_lshlrev_b32_e32 v146, 1, v58
	v_mov_b32_e32 v147, v3
	v_lshl_add_u64 v[146:147], v[6:7], 0, v[146:147]
	v_and_or_b32 v223, v154, s98, v223
	v_alignbit_b32 v226, v223, v223, 16
	v_alignbit_b32 v218, v220, v220, 16
	v_cndmask_b32_e64 v220, v226, v220, s[4:5]
	v_cndmask_b32_e64 v223, v218, v223, s[4:5]
	v_alignbit_b32 v226, v222, v222, 16
	v_alignbit_b32 v218, v221, v221, 16
	v_cndmask_b32_e64 v221, v226, v221, s[4:5]
	v_cndmask_b32_e64 v222, v218, v222, s[4:5]
	v_lshl_add_u64 v[218:219], v[146:147], 0, v[224:225]
	global_store_dwordx4 v[218:219], v[220:223], off
	s_nop 1
	ds_read_u16 v147, v89 offset:24576
	v_cndmask_b32_e64 v146, v216, v197, s[4:5]
	v_add_f32_e32 v145, v146, v145
	ds_read_u16 v146, v89 offset:8192
	s_waitcnt lgkmcnt(1)
	v_lshlrev_b32_e32 v156, 16, v147
	v_mul_f32_e32 v147, 0x3fb8aa3b, v145
	v_exp_f32_e32 v147, v147
	s_waitcnt lgkmcnt(0)
	v_lshlrev_b32_e32 v146, 16, v146
	v_mul_f32_e32 v146, 0x3db504f3, v146
	v_mul_f32_e32 v146, v147, v146
	v_cvt_pk_bf16_f32 v157, v146, v146
	v_or_b32_e32 v146, v142, v60
	v_mov_b32_e32 v147, v143
	v_lshlrev_b64 v[146:147], 8, v[146:147]
	v_or_b32_e32 v146, v146, v144
	v_lshl_add_u64 v[154:155], s[36:37], 0, v[146:147]
	global_store_short_d16_hi v[154:155], v157, off
	v_mul_f32_e32 v154, 0xbfb8aa3b, v145
	v_exp_f32_e32 v154, v154
	v_lshl_add_u64 v[146:147], s[38:39], 0, v[146:147]
	v_mul_f32_e32 v154, v154, v156
	v_cvt_pk_bf16_f32 v154, v154, v154
	global_store_short_d16_hi v[146:147], v154, off
	v_sub_f32_e32 v146, v141, v145
	v_mul_f32_e32 v146, 0x3fb8aa3b, v146
	v_exp_f32_e32 v146, v146
	s_nop 0
	v_mul_f32_e32 v146, v146, v156
	v_cvt_pk_bf16_f32 v154, v146, v146
	v_lshrrev_b32_e32 v220, 16, v154
	ds_read_u16 v147, v91 offset:24576
	v_cndmask_b32_e64 v146, v214, v198, s[4:5]
	v_add_f32_e32 v145, v146, v145
	ds_read_u16 v146, v91 offset:8192
	s_waitcnt lgkmcnt(1)
	v_lshlrev_b32_e32 v156, 16, v147
	v_mul_f32_e32 v147, 0x3fb8aa3b, v145
	v_exp_f32_e32 v147, v147
	s_waitcnt lgkmcnt(0)
	v_lshlrev_b32_e32 v146, 16, v146
	v_mul_f32_e32 v146, 0x3db504f3, v146
	v_mul_f32_e32 v146, v147, v146
	v_cvt_pk_bf16_f32 v157, v146, v146
	v_or_b32_e32 v146, v142, v62
	v_mov_b32_e32 v147, v143
	v_lshlrev_b64 v[146:147], 8, v[146:147]
	v_or_b32_e32 v146, v146, v144
	v_lshl_add_u64 v[154:155], s[36:37], 0, v[146:147]
	global_store_short_d16_hi v[154:155], v157, off
	v_mul_f32_e32 v154, 0xbfb8aa3b, v145
	v_exp_f32_e32 v154, v154
	v_lshl_add_u64 v[146:147], s[38:39], 0, v[146:147]
	v_mul_f32_e32 v154, v154, v156
	v_cvt_pk_bf16_f32 v154, v154, v154
	global_store_short_d16_hi v[146:147], v154, off
	v_sub_f32_e32 v146, v141, v145
	v_mul_f32_e32 v146, 0x3fb8aa3b, v146
	v_exp_f32_e32 v146, v146
	s_nop 0
	v_mul_f32_e32 v146, v146, v156
	v_cvt_pk_bf16_f32 v154, v146, v146
	v_and_or_b32 v220, v154, s98, v220
	ds_read_u16 v147, v93 offset:24576
	v_cndmask_b32_e64 v146, v209, v199, s[4:5]
	v_add_f32_e32 v145, v146, v145
	ds_read_u16 v146, v93 offset:8192
	s_waitcnt lgkmcnt(1)
	v_lshlrev_b32_e32 v156, 16, v147
	v_mul_f32_e32 v147, 0x3fb8aa3b, v145
	v_exp_f32_e32 v147, v147
	s_waitcnt lgkmcnt(0)
	v_lshlrev_b32_e32 v146, 16, v146
	v_mul_f32_e32 v146, 0x3db504f3, v146
	v_mul_f32_e32 v146, v147, v146
	v_cvt_pk_bf16_f32 v157, v146, v146
	v_or_b32_e32 v146, v142, v64
	v_mov_b32_e32 v147, v143
	v_lshlrev_b64 v[146:147], 8, v[146:147]
	v_or_b32_e32 v146, v146, v144
	v_lshl_add_u64 v[154:155], s[36:37], 0, v[146:147]
	global_store_short_d16_hi v[154:155], v157, off
	v_mul_f32_e32 v154, 0xbfb8aa3b, v145
	v_exp_f32_e32 v154, v154
	v_lshl_add_u64 v[146:147], s[38:39], 0, v[146:147]
	v_mul_f32_e32 v154, v154, v156
	v_cvt_pk_bf16_f32 v154, v154, v154
	global_store_short_d16_hi v[146:147], v154, off
	v_sub_f32_e32 v146, v141, v145
	v_mul_f32_e32 v146, 0x3fb8aa3b, v146
	v_exp_f32_e32 v146, v146
	s_nop 0
	v_mul_f32_e32 v146, v146, v156
	v_cvt_pk_bf16_f32 v154, v146, v146
	v_lshrrev_b32_e32 v221, 16, v154
	ds_read_u16 v147, v95 offset:24576
	v_cndmask_b32_e64 v146, v206, v200, s[4:5]
	v_add_f32_e32 v145, v146, v145
	ds_read_u16 v146, v95 offset:8192
	s_waitcnt lgkmcnt(1)
	v_lshlrev_b32_e32 v156, 16, v147
	v_mul_f32_e32 v147, 0x3fb8aa3b, v145
	v_exp_f32_e32 v147, v147
	s_waitcnt lgkmcnt(0)
	v_lshlrev_b32_e32 v146, 16, v146
	v_mul_f32_e32 v146, 0x3db504f3, v146
	v_mul_f32_e32 v146, v147, v146
	v_cvt_pk_bf16_f32 v157, v146, v146
	v_or_b32_e32 v146, v142, v66
	v_mov_b32_e32 v147, v143
	v_lshlrev_b64 v[146:147], 8, v[146:147]
	v_or_b32_e32 v146, v146, v144
	v_lshl_add_u64 v[154:155], s[36:37], 0, v[146:147]
	global_store_short_d16_hi v[154:155], v157, off
	v_mul_f32_e32 v154, 0xbfb8aa3b, v145
	v_exp_f32_e32 v154, v154
	v_lshl_add_u64 v[146:147], s[38:39], 0, v[146:147]
	v_mul_f32_e32 v154, v154, v156
	v_cvt_pk_bf16_f32 v154, v154, v154
	global_store_short_d16_hi v[146:147], v154, off
	v_sub_f32_e32 v146, v141, v145
	v_mul_f32_e32 v146, 0x3fb8aa3b, v146
	v_exp_f32_e32 v146, v146
	s_nop 0
	v_mul_f32_e32 v146, v146, v156
	v_cvt_pk_bf16_f32 v154, v146, v146
	v_and_or_b32 v221, v154, s98, v221
	ds_read_u16 v147, v97 offset:24576
	v_cndmask_b32_e64 v146, v212, v201, s[4:5]
	v_add_f32_e32 v145, v146, v145
	ds_read_u16 v146, v97 offset:8192
	s_waitcnt lgkmcnt(1)
	v_lshlrev_b32_e32 v156, 16, v147
	v_mul_f32_e32 v147, 0x3fb8aa3b, v145
	v_exp_f32_e32 v147, v147
	s_waitcnt lgkmcnt(0)
	v_lshlrev_b32_e32 v146, 16, v146
	v_mul_f32_e32 v146, 0x3db504f3, v146
	v_mul_f32_e32 v146, v147, v146
	v_cvt_pk_bf16_f32 v157, v146, v146
	v_or_b32_e32 v146, v142, v68
	v_mov_b32_e32 v147, v143
	v_lshlrev_b64 v[146:147], 8, v[146:147]
	v_or_b32_e32 v146, v146, v144
	v_lshl_add_u64 v[154:155], s[36:37], 0, v[146:147]
	global_store_short_d16_hi v[154:155], v157, off
	v_mul_f32_e32 v154, 0xbfb8aa3b, v145
	v_exp_f32_e32 v154, v154
	v_lshl_add_u64 v[146:147], s[38:39], 0, v[146:147]
	v_mul_f32_e32 v154, v154, v156
	v_cvt_pk_bf16_f32 v154, v154, v154
	global_store_short_d16_hi v[146:147], v154, off
	v_sub_f32_e32 v146, v141, v145
	v_mul_f32_e32 v146, 0x3fb8aa3b, v146
	v_exp_f32_e32 v146, v146
	s_nop 0
	v_mul_f32_e32 v146, v146, v156
	v_cvt_pk_bf16_f32 v154, v146, v146
	v_lshrrev_b32_e32 v222, 16, v154
	ds_read_u16 v147, v99 offset:24576
	v_cndmask_b32_e64 v146, v210, v202, s[4:5]
	v_add_f32_e32 v145, v146, v145
	ds_read_u16 v146, v99 offset:8192
	s_waitcnt lgkmcnt(1)
	v_lshlrev_b32_e32 v156, 16, v147
	v_mul_f32_e32 v147, 0x3fb8aa3b, v145
	v_exp_f32_e32 v147, v147
	s_waitcnt lgkmcnt(0)
	v_lshlrev_b32_e32 v146, 16, v146
	v_mul_f32_e32 v146, 0x3db504f3, v146
	v_mul_f32_e32 v146, v147, v146
	v_cvt_pk_bf16_f32 v157, v146, v146
	v_or_b32_e32 v146, v142, v70
	v_mov_b32_e32 v147, v143
	v_lshlrev_b64 v[146:147], 8, v[146:147]
	v_or_b32_e32 v146, v146, v144
	v_lshl_add_u64 v[154:155], s[36:37], 0, v[146:147]
	global_store_short_d16_hi v[154:155], v157, off
	v_mul_f32_e32 v154, 0xbfb8aa3b, v145
	v_exp_f32_e32 v154, v154
	v_lshl_add_u64 v[146:147], s[38:39], 0, v[146:147]
	v_mul_f32_e32 v154, v154, v156
	v_cvt_pk_bf16_f32 v154, v154, v154
	global_store_short_d16_hi v[146:147], v154, off
	v_sub_f32_e32 v146, v141, v145
	v_mul_f32_e32 v146, 0x3fb8aa3b, v146
	v_exp_f32_e32 v146, v146
	s_nop 0
	v_mul_f32_e32 v146, v146, v156
	v_cvt_pk_bf16_f32 v154, v146, v146
	v_and_or_b32 v222, v154, s98, v222
	ds_read_u16 v147, v101 offset:24576
	v_cndmask_b32_e64 v146, v207, v203, s[4:5]
	v_add_f32_e32 v145, v146, v145
	ds_read_u16 v146, v101 offset:8192
	s_waitcnt lgkmcnt(1)
	v_lshlrev_b32_e32 v156, 16, v147
	v_mul_f32_e32 v147, 0x3fb8aa3b, v145
	v_exp_f32_e32 v147, v147
	s_waitcnt lgkmcnt(0)
	v_lshlrev_b32_e32 v146, 16, v146
	v_mul_f32_e32 v146, 0x3db504f3, v146
	v_mul_f32_e32 v146, v147, v146
	v_cvt_pk_bf16_f32 v157, v146, v146
	v_or_b32_e32 v146, v142, v72
	v_mov_b32_e32 v147, v143
	v_lshlrev_b64 v[146:147], 8, v[146:147]
	v_or_b32_e32 v146, v146, v144
	v_lshl_add_u64 v[154:155], s[36:37], 0, v[146:147]
	global_store_short_d16_hi v[154:155], v157, off
	v_mul_f32_e32 v154, 0xbfb8aa3b, v145
	v_exp_f32_e32 v154, v154
	v_lshl_add_u64 v[146:147], s[38:39], 0, v[146:147]
	v_mul_f32_e32 v154, v154, v156
	v_cvt_pk_bf16_f32 v154, v154, v154
	global_store_short_d16_hi v[146:147], v154, off
	v_sub_f32_e32 v146, v141, v145
	v_mul_f32_e32 v146, 0x3fb8aa3b, v146
	v_exp_f32_e32 v146, v146
	s_nop 0
	v_mul_f32_e32 v146, v146, v156
	v_cvt_pk_bf16_f32 v154, v146, v146
	v_lshrrev_b32_e32 v223, 16, v154
	ds_read_u16 v147, v103 offset:24576
	v_cndmask_b32_e64 v146, v205, v204, s[4:5]
	v_add_f32_e32 v145, v146, v145
	ds_read_u16 v146, v103 offset:8192
	s_waitcnt lgkmcnt(1)
	v_lshlrev_b32_e32 v156, 16, v147
	v_mul_f32_e32 v147, 0x3fb8aa3b, v145
	v_exp_f32_e32 v147, v147
	s_waitcnt lgkmcnt(0)
	v_lshlrev_b32_e32 v146, 16, v146
	v_mul_f32_e32 v146, 0x3db504f3, v146
	v_mul_f32_e32 v146, v147, v146
	v_cvt_pk_bf16_f32 v157, v146, v146
	v_or_b32_e32 v146, v142, v74
	v_mov_b32_e32 v147, v143
	v_lshlrev_b64 v[146:147], 8, v[146:147]
	v_or_b32_e32 v146, v146, v144
	v_lshl_add_u64 v[154:155], s[36:37], 0, v[146:147]
	global_store_short_d16_hi v[154:155], v157, off
	v_mul_f32_e32 v154, 0xbfb8aa3b, v145
	v_exp_f32_e32 v154, v154
	v_lshl_add_u64 v[146:147], s[38:39], 0, v[146:147]
	v_mul_f32_e32 v154, v154, v156
	v_cvt_pk_bf16_f32 v154, v154, v154
	global_store_short_d16_hi v[146:147], v154, off
	v_sub_f32_e32 v146, v141, v145
	v_mul_f32_e32 v146, 0x3fb8aa3b, v146
	v_exp_f32_e32 v146, v146
	s_nop 0
	v_mul_f32_e32 v146, v146, v156
	v_cvt_pk_bf16_f32 v154, v146, v146
	v_lshlrev_b32_e32 v146, 1, v74
	v_mov_b32_e32 v147, v3
	v_lshl_add_u64 v[146:147], v[6:7], 0, v[146:147]
	v_and_or_b32 v223, v154, s98, v223
	v_alignbit_b32 v226, v223, v223, 16
	v_alignbit_b32 v218, v220, v220, 16
	v_cndmask_b32_e64 v220, v226, v220, s[4:5]
	v_cndmask_b32_e64 v223, v218, v223, s[4:5]
	v_alignbit_b32 v226, v222, v222, 16
	v_alignbit_b32 v218, v221, v221, 16
	v_cndmask_b32_e64 v221, v226, v221, s[4:5]
	v_cndmask_b32_e64 v222, v218, v222, s[4:5]
	v_lshl_add_u64 v[218:219], v[146:147], 0, v[224:225]
	global_store_dwordx4 v[218:219], v[220:223], off
	s_nop 1
	ds_read_u16 v147, v105 offset:24576
	v_cndmask_b32_e64 v146, v204, v205, s[4:5]
	v_add_f32_e32 v145, v146, v145
	ds_read_u16 v146, v105 offset:8192
	s_waitcnt lgkmcnt(1)
	v_lshlrev_b32_e32 v156, 16, v147
	v_mul_f32_e32 v147, 0x3fb8aa3b, v145
	v_exp_f32_e32 v147, v147
	s_waitcnt lgkmcnt(0)
	v_lshlrev_b32_e32 v146, 16, v146
	v_mul_f32_e32 v146, 0x3db504f3, v146
	v_mul_f32_e32 v146, v147, v146
	v_cvt_pk_bf16_f32 v157, v146, v146
	v_or_b32_e32 v146, v142, v76
	v_mov_b32_e32 v147, v143
	v_lshlrev_b64 v[146:147], 8, v[146:147]
	v_or_b32_e32 v146, v146, v144
	v_lshl_add_u64 v[154:155], s[36:37], 0, v[146:147]
	global_store_short_d16_hi v[154:155], v157, off
	v_mul_f32_e32 v154, 0xbfb8aa3b, v145
	v_exp_f32_e32 v154, v154
	v_lshl_add_u64 v[146:147], s[38:39], 0, v[146:147]
	v_mul_f32_e32 v154, v154, v156
	v_cvt_pk_bf16_f32 v154, v154, v154
	global_store_short_d16_hi v[146:147], v154, off
	v_sub_f32_e32 v146, v141, v145
	v_mul_f32_e32 v146, 0x3fb8aa3b, v146
	v_exp_f32_e32 v146, v146
	s_nop 0
	v_mul_f32_e32 v146, v146, v156
	v_cvt_pk_bf16_f32 v154, v146, v146
	v_lshrrev_b32_e32 v220, 16, v154
	ds_read_u16 v147, v107 offset:24576
	v_cndmask_b32_e64 v146, v203, v207, s[4:5]
	v_add_f32_e32 v145, v146, v145
	ds_read_u16 v146, v107 offset:8192
	s_waitcnt lgkmcnt(1)
	v_lshlrev_b32_e32 v156, 16, v147
	v_mul_f32_e32 v147, 0x3fb8aa3b, v145
	v_exp_f32_e32 v147, v147
	s_waitcnt lgkmcnt(0)
	v_lshlrev_b32_e32 v146, 16, v146
	v_mul_f32_e32 v146, 0x3db504f3, v146
	v_mul_f32_e32 v146, v147, v146
	v_cvt_pk_bf16_f32 v157, v146, v146
	v_or_b32_e32 v146, v142, v78
	v_mov_b32_e32 v147, v143
	v_lshlrev_b64 v[146:147], 8, v[146:147]
	v_or_b32_e32 v146, v146, v144
	v_lshl_add_u64 v[154:155], s[36:37], 0, v[146:147]
	global_store_short_d16_hi v[154:155], v157, off
	v_mul_f32_e32 v154, 0xbfb8aa3b, v145
	v_exp_f32_e32 v154, v154
	v_lshl_add_u64 v[146:147], s[38:39], 0, v[146:147]
	v_mul_f32_e32 v154, v154, v156
	v_cvt_pk_bf16_f32 v154, v154, v154
	global_store_short_d16_hi v[146:147], v154, off
	v_sub_f32_e32 v146, v141, v145
	v_mul_f32_e32 v146, 0x3fb8aa3b, v146
	v_exp_f32_e32 v146, v146
	s_nop 0
	v_mul_f32_e32 v146, v146, v156
	v_cvt_pk_bf16_f32 v154, v146, v146
	v_and_or_b32 v220, v154, s98, v220
	ds_read_u16 v147, v109 offset:24576
	v_cndmask_b32_e64 v146, v202, v210, s[4:5]
	v_add_f32_e32 v145, v146, v145
	ds_read_u16 v146, v109 offset:8192
	s_waitcnt lgkmcnt(1)
	v_lshlrev_b32_e32 v156, 16, v147
	v_mul_f32_e32 v147, 0x3fb8aa3b, v145
	v_exp_f32_e32 v147, v147
	s_waitcnt lgkmcnt(0)
	v_lshlrev_b32_e32 v146, 16, v146
	v_mul_f32_e32 v146, 0x3db504f3, v146
	v_mul_f32_e32 v146, v147, v146
	v_cvt_pk_bf16_f32 v157, v146, v146
	v_or_b32_e32 v146, v142, v80
	v_mov_b32_e32 v147, v143
	v_lshlrev_b64 v[146:147], 8, v[146:147]
	v_or_b32_e32 v146, v146, v144
	v_lshl_add_u64 v[154:155], s[36:37], 0, v[146:147]
	global_store_short_d16_hi v[154:155], v157, off
	v_mul_f32_e32 v154, 0xbfb8aa3b, v145
	v_exp_f32_e32 v154, v154
	v_lshl_add_u64 v[146:147], s[38:39], 0, v[146:147]
	v_mul_f32_e32 v154, v154, v156
	v_cvt_pk_bf16_f32 v154, v154, v154
	global_store_short_d16_hi v[146:147], v154, off
	v_sub_f32_e32 v146, v141, v145
	v_mul_f32_e32 v146, 0x3fb8aa3b, v146
	v_exp_f32_e32 v146, v146
	s_nop 0
	v_mul_f32_e32 v146, v146, v156
	v_cvt_pk_bf16_f32 v154, v146, v146
	v_lshrrev_b32_e32 v221, 16, v154
	ds_read_u16 v147, v111 offset:24576
	v_cndmask_b32_e64 v146, v201, v212, s[4:5]
	v_add_f32_e32 v145, v146, v145
	ds_read_u16 v146, v111 offset:8192
	s_waitcnt lgkmcnt(1)
	v_lshlrev_b32_e32 v156, 16, v147
	v_mul_f32_e32 v147, 0x3fb8aa3b, v145
	v_exp_f32_e32 v147, v147
	s_waitcnt lgkmcnt(0)
	v_lshlrev_b32_e32 v146, 16, v146
	v_mul_f32_e32 v146, 0x3db504f3, v146
	v_mul_f32_e32 v146, v147, v146
	v_cvt_pk_bf16_f32 v157, v146, v146
	v_or_b32_e32 v146, v142, v82
	v_mov_b32_e32 v147, v143
	v_lshlrev_b64 v[146:147], 8, v[146:147]
	v_or_b32_e32 v146, v146, v144
	v_lshl_add_u64 v[154:155], s[36:37], 0, v[146:147]
	global_store_short_d16_hi v[154:155], v157, off
	v_mul_f32_e32 v154, 0xbfb8aa3b, v145
	v_exp_f32_e32 v154, v154
	v_lshl_add_u64 v[146:147], s[38:39], 0, v[146:147]
	v_mul_f32_e32 v154, v154, v156
	v_cvt_pk_bf16_f32 v154, v154, v154
	global_store_short_d16_hi v[146:147], v154, off
	v_sub_f32_e32 v146, v141, v145
	v_mul_f32_e32 v146, 0x3fb8aa3b, v146
	v_exp_f32_e32 v146, v146
	s_nop 0
	v_mul_f32_e32 v146, v146, v156
	v_cvt_pk_bf16_f32 v154, v146, v146
	v_and_or_b32 v221, v154, s98, v221
	ds_read_u16 v147, v113 offset:24576
	v_cndmask_b32_e64 v146, v200, v206, s[4:5]
	v_add_f32_e32 v145, v146, v145
	ds_read_u16 v146, v113 offset:8192
	s_waitcnt lgkmcnt(1)
	v_lshlrev_b32_e32 v156, 16, v147
	v_mul_f32_e32 v147, 0x3fb8aa3b, v145
	v_exp_f32_e32 v147, v147
	s_waitcnt lgkmcnt(0)
	v_lshlrev_b32_e32 v146, 16, v146
	v_mul_f32_e32 v146, 0x3db504f3, v146
	v_mul_f32_e32 v146, v147, v146
	v_cvt_pk_bf16_f32 v157, v146, v146
	v_or_b32_e32 v146, v142, v84
	v_mov_b32_e32 v147, v143
	v_lshlrev_b64 v[146:147], 8, v[146:147]
	v_or_b32_e32 v146, v146, v144
	v_lshl_add_u64 v[154:155], s[36:37], 0, v[146:147]
	global_store_short_d16_hi v[154:155], v157, off
	v_mul_f32_e32 v154, 0xbfb8aa3b, v145
	v_exp_f32_e32 v154, v154
	v_lshl_add_u64 v[146:147], s[38:39], 0, v[146:147]
	v_mul_f32_e32 v154, v154, v156
	v_cvt_pk_bf16_f32 v154, v154, v154
	global_store_short_d16_hi v[146:147], v154, off
	v_sub_f32_e32 v146, v141, v145
	v_mul_f32_e32 v146, 0x3fb8aa3b, v146
	v_exp_f32_e32 v146, v146
	s_nop 0
	v_mul_f32_e32 v146, v146, v156
	v_cvt_pk_bf16_f32 v154, v146, v146
	v_lshrrev_b32_e32 v222, 16, v154
	ds_read_u16 v147, v115 offset:24576
	v_cndmask_b32_e64 v146, v199, v209, s[4:5]
	v_add_f32_e32 v145, v146, v145
	ds_read_u16 v146, v115 offset:8192
	s_waitcnt lgkmcnt(1)
	v_lshlrev_b32_e32 v156, 16, v147
	v_mul_f32_e32 v147, 0x3fb8aa3b, v145
	v_exp_f32_e32 v147, v147
	s_waitcnt lgkmcnt(0)
	v_lshlrev_b32_e32 v146, 16, v146
	v_mul_f32_e32 v146, 0x3db504f3, v146
	v_mul_f32_e32 v146, v147, v146
	v_cvt_pk_bf16_f32 v157, v146, v146
	v_or_b32_e32 v146, v142, v86
	v_mov_b32_e32 v147, v143
	v_lshlrev_b64 v[146:147], 8, v[146:147]
	v_or_b32_e32 v146, v146, v144
	v_lshl_add_u64 v[154:155], s[36:37], 0, v[146:147]
	global_store_short_d16_hi v[154:155], v157, off
	v_mul_f32_e32 v154, 0xbfb8aa3b, v145
	v_exp_f32_e32 v154, v154
	v_lshl_add_u64 v[146:147], s[38:39], 0, v[146:147]
	v_mul_f32_e32 v154, v154, v156
	v_cvt_pk_bf16_f32 v154, v154, v154
	global_store_short_d16_hi v[146:147], v154, off
	v_sub_f32_e32 v146, v141, v145
	v_mul_f32_e32 v146, 0x3fb8aa3b, v146
	v_exp_f32_e32 v146, v146
	s_nop 0
	v_mul_f32_e32 v146, v146, v156
	v_cvt_pk_bf16_f32 v154, v146, v146
	v_and_or_b32 v222, v154, s98, v222
	ds_read_u16 v147, v117 offset:24576
	v_cndmask_b32_e64 v146, v198, v214, s[4:5]
	v_add_f32_e32 v145, v146, v145
	ds_read_u16 v146, v117 offset:8192
	s_waitcnt lgkmcnt(1)
	v_lshlrev_b32_e32 v156, 16, v147
	v_mul_f32_e32 v147, 0x3fb8aa3b, v145
	v_exp_f32_e32 v147, v147
	s_waitcnt lgkmcnt(0)
	v_lshlrev_b32_e32 v146, 16, v146
	v_mul_f32_e32 v146, 0x3db504f3, v146
	v_mul_f32_e32 v146, v147, v146
	v_cvt_pk_bf16_f32 v157, v146, v146
	v_or_b32_e32 v146, v142, v88
	v_mov_b32_e32 v147, v143
	v_lshlrev_b64 v[146:147], 8, v[146:147]
	v_or_b32_e32 v146, v146, v144
	v_lshl_add_u64 v[154:155], s[36:37], 0, v[146:147]
	global_store_short_d16_hi v[154:155], v157, off
	v_mul_f32_e32 v154, 0xbfb8aa3b, v145
	v_exp_f32_e32 v154, v154
	v_lshl_add_u64 v[146:147], s[38:39], 0, v[146:147]
	v_mul_f32_e32 v154, v154, v156
	v_cvt_pk_bf16_f32 v154, v154, v154
	global_store_short_d16_hi v[146:147], v154, off
	v_sub_f32_e32 v146, v141, v145
	v_mul_f32_e32 v146, 0x3fb8aa3b, v146
	v_exp_f32_e32 v146, v146
	s_nop 0
	v_mul_f32_e32 v146, v146, v156
	v_cvt_pk_bf16_f32 v154, v146, v146
	v_lshrrev_b32_e32 v223, 16, v154
	ds_read_u16 v147, v119 offset:24576
	v_cndmask_b32_e64 v146, v197, v216, s[4:5]
	v_add_f32_e32 v145, v146, v145
	ds_read_u16 v146, v119 offset:8192
	s_waitcnt lgkmcnt(1)
	v_lshlrev_b32_e32 v156, 16, v147
	v_mul_f32_e32 v147, 0x3fb8aa3b, v145
	v_exp_f32_e32 v147, v147
	s_waitcnt lgkmcnt(0)
	v_lshlrev_b32_e32 v146, 16, v146
	v_mul_f32_e32 v146, 0x3db504f3, v146
	v_mul_f32_e32 v146, v147, v146
	v_cvt_pk_bf16_f32 v157, v146, v146
	v_or_b32_e32 v146, v142, v90
	v_mov_b32_e32 v147, v143
	v_lshlrev_b64 v[146:147], 8, v[146:147]
	v_or_b32_e32 v146, v146, v144
	v_lshl_add_u64 v[154:155], s[36:37], 0, v[146:147]
	global_store_short_d16_hi v[154:155], v157, off
	v_mul_f32_e32 v154, 0xbfb8aa3b, v145
	v_exp_f32_e32 v154, v154
	v_lshl_add_u64 v[146:147], s[38:39], 0, v[146:147]
	v_mul_f32_e32 v154, v154, v156
	v_cvt_pk_bf16_f32 v154, v154, v154
	global_store_short_d16_hi v[146:147], v154, off
	v_sub_f32_e32 v146, v141, v145
	v_mul_f32_e32 v146, 0x3fb8aa3b, v146
	v_exp_f32_e32 v146, v146
	s_nop 0
	v_mul_f32_e32 v146, v146, v156
	v_cvt_pk_bf16_f32 v154, v146, v146
	v_lshlrev_b32_e32 v146, 1, v90
	v_mov_b32_e32 v147, v3
	v_lshl_add_u64 v[146:147], v[6:7], 0, v[146:147]
	v_and_or_b32 v223, v154, s98, v223
	v_alignbit_b32 v226, v223, v223, 16
	v_alignbit_b32 v218, v220, v220, 16
	v_cndmask_b32_e64 v220, v226, v220, s[4:5]
	v_cndmask_b32_e64 v223, v218, v223, s[4:5]
	v_alignbit_b32 v226, v222, v222, 16
	v_alignbit_b32 v218, v221, v221, 16
	v_cndmask_b32_e64 v221, v226, v221, s[4:5]
	v_cndmask_b32_e64 v222, v218, v222, s[4:5]
	v_lshl_add_u64 v[218:219], v[146:147], 0, v[224:225]
	global_store_dwordx4 v[218:219], v[220:223], off
	s_nop 1
	ds_read_u16 v147, v121 offset:24576
	v_cndmask_b32_e64 v146, v196, v208, s[4:5]
	v_add_f32_e32 v145, v146, v145
	ds_read_u16 v146, v121 offset:8192
	s_waitcnt lgkmcnt(1)
	v_lshlrev_b32_e32 v156, 16, v147
	v_mul_f32_e32 v147, 0x3fb8aa3b, v145
	v_exp_f32_e32 v147, v147
	s_waitcnt lgkmcnt(0)
	v_lshlrev_b32_e32 v146, 16, v146
	v_mul_f32_e32 v146, 0x3db504f3, v146
	v_mul_f32_e32 v146, v147, v146
	v_cvt_pk_bf16_f32 v157, v146, v146
	v_or_b32_e32 v146, v142, v92
	v_mov_b32_e32 v147, v143
	v_lshlrev_b64 v[146:147], 8, v[146:147]
	v_or_b32_e32 v146, v146, v144
	v_lshl_add_u64 v[154:155], s[36:37], 0, v[146:147]
	global_store_short_d16_hi v[154:155], v157, off
	v_mul_f32_e32 v154, 0xbfb8aa3b, v145
	v_exp_f32_e32 v154, v154
	v_lshl_add_u64 v[146:147], s[38:39], 0, v[146:147]
	v_mul_f32_e32 v154, v154, v156
	v_cvt_pk_bf16_f32 v154, v154, v154
	global_store_short_d16_hi v[146:147], v154, off
	v_sub_f32_e32 v146, v141, v145
	v_mul_f32_e32 v146, 0x3fb8aa3b, v146
	v_exp_f32_e32 v146, v146
	s_nop 0
	v_mul_f32_e32 v146, v146, v156
	v_cvt_pk_bf16_f32 v154, v146, v146
	v_lshrrev_b32_e32 v220, 16, v154
	ds_read_u16 v147, v123 offset:24576
	v_cndmask_b32_e64 v146, v195, v213, s[4:5]
	v_add_f32_e32 v145, v146, v145
	ds_read_u16 v146, v123 offset:8192
	s_waitcnt lgkmcnt(1)
	v_lshlrev_b32_e32 v156, 16, v147
	v_mul_f32_e32 v147, 0x3fb8aa3b, v145
	v_exp_f32_e32 v147, v147
	s_waitcnt lgkmcnt(0)
	v_lshlrev_b32_e32 v146, 16, v146
	v_mul_f32_e32 v146, 0x3db504f3, v146
	v_mul_f32_e32 v146, v147, v146
	v_cvt_pk_bf16_f32 v157, v146, v146
	v_or_b32_e32 v146, v142, v94
	v_mov_b32_e32 v147, v143
	v_lshlrev_b64 v[146:147], 8, v[146:147]
	v_or_b32_e32 v146, v146, v144
	v_lshl_add_u64 v[154:155], s[36:37], 0, v[146:147]
	global_store_short_d16_hi v[154:155], v157, off
	v_mul_f32_e32 v154, 0xbfb8aa3b, v145
	v_exp_f32_e32 v154, v154
	v_lshl_add_u64 v[146:147], s[38:39], 0, v[146:147]
	v_mul_f32_e32 v154, v154, v156
	v_cvt_pk_bf16_f32 v154, v154, v154
	global_store_short_d16_hi v[146:147], v154, off
	v_sub_f32_e32 v146, v141, v145
	v_mul_f32_e32 v146, 0x3fb8aa3b, v146
	v_exp_f32_e32 v146, v146
	s_nop 0
	v_mul_f32_e32 v146, v146, v156
	v_cvt_pk_bf16_f32 v154, v146, v146
	v_and_or_b32 v220, v154, s98, v220
	ds_read_u16 v147, v125 offset:24576
	v_cndmask_b32_e64 v146, v194, v234, s[4:5]
	v_add_f32_e32 v145, v146, v145
	ds_read_u16 v146, v125 offset:8192
	s_waitcnt lgkmcnt(1)
	v_lshlrev_b32_e32 v156, 16, v147
	v_mul_f32_e32 v147, 0x3fb8aa3b, v145
	v_exp_f32_e32 v147, v147
	s_waitcnt lgkmcnt(0)
	v_lshlrev_b32_e32 v146, 16, v146
	v_mul_f32_e32 v146, 0x3db504f3, v146
	v_mul_f32_e32 v146, v147, v146
	v_cvt_pk_bf16_f32 v157, v146, v146
	v_or_b32_e32 v146, v142, v96
	v_mov_b32_e32 v147, v143
	v_lshlrev_b64 v[146:147], 8, v[146:147]
	v_or_b32_e32 v146, v146, v144
	v_lshl_add_u64 v[154:155], s[36:37], 0, v[146:147]
	global_store_short_d16_hi v[154:155], v157, off
	v_mul_f32_e32 v154, 0xbfb8aa3b, v145
	v_exp_f32_e32 v154, v154
	v_lshl_add_u64 v[146:147], s[38:39], 0, v[146:147]
	v_mul_f32_e32 v154, v154, v156
	v_cvt_pk_bf16_f32 v154, v154, v154
	global_store_short_d16_hi v[146:147], v154, off
	v_sub_f32_e32 v146, v141, v145
	v_mul_f32_e32 v146, 0x3fb8aa3b, v146
	v_exp_f32_e32 v146, v146
	s_nop 0
	v_mul_f32_e32 v146, v146, v156
	v_cvt_pk_bf16_f32 v154, v146, v146
	v_lshrrev_b32_e32 v221, 16, v154
	ds_read_u16 v147, v127 offset:24576
	v_cndmask_b32_e64 v146, v193, v236, s[4:5]
	v_add_f32_e32 v145, v146, v145
	ds_read_u16 v146, v127 offset:8192
	s_waitcnt lgkmcnt(1)
	v_lshlrev_b32_e32 v156, 16, v147
	v_mul_f32_e32 v147, 0x3fb8aa3b, v145
	v_exp_f32_e32 v147, v147
	s_waitcnt lgkmcnt(0)
	v_lshlrev_b32_e32 v146, 16, v146
	v_mul_f32_e32 v146, 0x3db504f3, v146
	v_mul_f32_e32 v146, v147, v146
	v_cvt_pk_bf16_f32 v157, v146, v146
	v_or_b32_e32 v146, v142, v98
	v_mov_b32_e32 v147, v143
	v_lshlrev_b64 v[146:147], 8, v[146:147]
	v_or_b32_e32 v146, v146, v144
	v_lshl_add_u64 v[154:155], s[36:37], 0, v[146:147]
	global_store_short_d16_hi v[154:155], v157, off
	v_mul_f32_e32 v154, 0xbfb8aa3b, v145
	v_exp_f32_e32 v154, v154
	v_lshl_add_u64 v[146:147], s[38:39], 0, v[146:147]
	v_mul_f32_e32 v154, v154, v156
	v_cvt_pk_bf16_f32 v154, v154, v154
	global_store_short_d16_hi v[146:147], v154, off
	v_sub_f32_e32 v146, v141, v145
	v_mul_f32_e32 v146, 0x3fb8aa3b, v146
	v_exp_f32_e32 v146, v146
	s_nop 0
	v_mul_f32_e32 v146, v146, v156
	v_cvt_pk_bf16_f32 v154, v146, v146
	v_and_or_b32 v221, v154, s98, v221
	ds_read_u16 v147, v129 offset:24576
	v_cndmask_b32_e64 v146, v192, v211, s[4:5]
	v_add_f32_e32 v145, v146, v145
	ds_read_u16 v146, v129 offset:8192
	s_waitcnt lgkmcnt(1)
	v_lshlrev_b32_e32 v156, 16, v147
	v_mul_f32_e32 v147, 0x3fb8aa3b, v145
	v_exp_f32_e32 v147, v147
	s_waitcnt lgkmcnt(0)
	v_lshlrev_b32_e32 v146, 16, v146
	v_mul_f32_e32 v146, 0x3db504f3, v146
	v_mul_f32_e32 v146, v147, v146
	v_cvt_pk_bf16_f32 v157, v146, v146
	v_or_b32_e32 v146, v142, v100
	v_mov_b32_e32 v147, v143
	v_lshlrev_b64 v[146:147], 8, v[146:147]
	v_or_b32_e32 v146, v146, v144
	v_lshl_add_u64 v[154:155], s[36:37], 0, v[146:147]
	global_store_short_d16_hi v[154:155], v157, off
	v_mul_f32_e32 v154, 0xbfb8aa3b, v145
	v_exp_f32_e32 v154, v154
	v_lshl_add_u64 v[146:147], s[38:39], 0, v[146:147]
	v_mul_f32_e32 v154, v154, v156
	v_cvt_pk_bf16_f32 v154, v154, v154
	global_store_short_d16_hi v[146:147], v154, off
	v_sub_f32_e32 v146, v141, v145
	v_mul_f32_e32 v146, 0x3fb8aa3b, v146
	v_exp_f32_e32 v146, v146
	s_nop 0
	v_mul_f32_e32 v146, v146, v156
	v_cvt_pk_bf16_f32 v154, v146, v146
	v_lshrrev_b32_e32 v222, 16, v154
	ds_read_u16 v147, v131 offset:24576
	v_cndmask_b32_e64 v146, v191, v217, s[4:5]
	v_add_f32_e32 v145, v146, v145
	ds_read_u16 v146, v131 offset:8192
	s_waitcnt lgkmcnt(1)
	v_lshlrev_b32_e32 v156, 16, v147
	v_mul_f32_e32 v147, 0x3fb8aa3b, v145
	v_exp_f32_e32 v147, v147
	s_waitcnt lgkmcnt(0)
	v_lshlrev_b32_e32 v146, 16, v146
	v_mul_f32_e32 v146, 0x3db504f3, v146
	v_mul_f32_e32 v146, v147, v146
	v_cvt_pk_bf16_f32 v157, v146, v146
	v_or_b32_e32 v146, v142, v102
	v_mov_b32_e32 v147, v143
	v_lshlrev_b64 v[146:147], 8, v[146:147]
	v_or_b32_e32 v146, v146, v144
	v_lshl_add_u64 v[154:155], s[36:37], 0, v[146:147]
	global_store_short_d16_hi v[154:155], v157, off
	v_mul_f32_e32 v154, 0xbfb8aa3b, v145
	v_exp_f32_e32 v154, v154
	v_lshl_add_u64 v[146:147], s[38:39], 0, v[146:147]
	v_mul_f32_e32 v154, v154, v156
	v_cvt_pk_bf16_f32 v154, v154, v154
	global_store_short_d16_hi v[146:147], v154, off
	v_sub_f32_e32 v146, v141, v145
	v_mul_f32_e32 v146, 0x3fb8aa3b, v146
	v_exp_f32_e32 v146, v146
	s_nop 0
	v_mul_f32_e32 v146, v146, v156
	v_cvt_pk_bf16_f32 v154, v146, v146
	v_and_or_b32 v222, v154, s98, v222
	ds_read_u16 v147, v133 offset:24576
	v_cndmask_b32_e64 v146, v190, v238, s[4:5]
	v_add_f32_e32 v145, v146, v145
	ds_read_u16 v146, v133 offset:8192
	s_waitcnt lgkmcnt(1)
	v_lshlrev_b32_e32 v156, 16, v147
	v_mul_f32_e32 v147, 0x3fb8aa3b, v145
	v_exp_f32_e32 v147, v147
	s_waitcnt lgkmcnt(0)
	v_lshlrev_b32_e32 v146, 16, v146
	v_mul_f32_e32 v146, 0x3db504f3, v146
	v_mul_f32_e32 v146, v147, v146
	v_cvt_pk_bf16_f32 v157, v146, v146
	v_or_b32_e32 v146, v142, v104
	v_mov_b32_e32 v147, v143
	v_lshlrev_b64 v[146:147], 8, v[146:147]
	v_or_b32_e32 v146, v146, v144
	v_lshl_add_u64 v[154:155], s[36:37], 0, v[146:147]
	global_store_short_d16_hi v[154:155], v157, off
	v_mul_f32_e32 v154, 0xbfb8aa3b, v145
	v_exp_f32_e32 v154, v154
	v_lshl_add_u64 v[146:147], s[38:39], 0, v[146:147]
	v_mul_f32_e32 v154, v154, v156
	v_cvt_pk_bf16_f32 v154, v154, v154
	global_store_short_d16_hi v[146:147], v154, off
	v_sub_f32_e32 v146, v141, v145
	v_mul_f32_e32 v146, 0x3fb8aa3b, v146
	v_exp_f32_e32 v146, v146
	s_nop 0
	v_mul_f32_e32 v146, v146, v156
	v_cvt_pk_bf16_f32 v154, v146, v146
	v_lshrrev_b32_e32 v223, 16, v154
	ds_read_u16 v147, v135 offset:24576
	v_cndmask_b32_e64 v146, v189, v240, s[4:5]
	v_add_f32_e32 v145, v146, v145
	ds_read_u16 v146, v135 offset:8192
	s_waitcnt lgkmcnt(1)
	v_lshlrev_b32_e32 v156, 16, v147
	v_mul_f32_e32 v147, 0x3fb8aa3b, v145
	v_exp_f32_e32 v147, v147
	s_waitcnt lgkmcnt(0)
	v_lshlrev_b32_e32 v146, 16, v146
	v_mul_f32_e32 v146, 0x3db504f3, v146
	v_mul_f32_e32 v146, v147, v146
	v_cvt_pk_bf16_f32 v157, v146, v146
	v_or_b32_e32 v146, v142, v106
	v_mov_b32_e32 v147, v143
	v_lshlrev_b64 v[146:147], 8, v[146:147]
	v_or_b32_e32 v146, v146, v144
	v_lshl_add_u64 v[154:155], s[36:37], 0, v[146:147]
	global_store_short_d16_hi v[154:155], v157, off
	v_mul_f32_e32 v154, 0xbfb8aa3b, v145
	v_exp_f32_e32 v154, v154
	v_lshl_add_u64 v[146:147], s[38:39], 0, v[146:147]
	v_mul_f32_e32 v154, v154, v156
	v_cvt_pk_bf16_f32 v154, v154, v154
	global_store_short_d16_hi v[146:147], v154, off
	v_sub_f32_e32 v146, v141, v145
	v_mul_f32_e32 v146, 0x3fb8aa3b, v146
	v_exp_f32_e32 v146, v146
	s_nop 0
	v_mul_f32_e32 v146, v146, v156
	v_cvt_pk_bf16_f32 v154, v146, v146
	v_lshlrev_b32_e32 v146, 1, v106
	v_mov_b32_e32 v147, v3
	v_lshl_add_u64 v[146:147], v[6:7], 0, v[146:147]
	v_and_or_b32 v223, v154, s98, v223
	v_alignbit_b32 v226, v223, v223, 16
	v_alignbit_b32 v218, v220, v220, 16
	v_cndmask_b32_e64 v220, v226, v220, s[4:5]
	v_cndmask_b32_e64 v223, v218, v223, s[4:5]
	v_alignbit_b32 v226, v222, v222, 16
	v_alignbit_b32 v218, v221, v221, 16
	v_cndmask_b32_e64 v221, v226, v221, s[4:5]
	v_cndmask_b32_e64 v222, v218, v222, s[4:5]
	v_lshl_add_u64 v[218:219], v[146:147], 0, v[224:225]
	global_store_dwordx4 v[218:219], v[220:223], off
	s_nop 1
	ds_read_u16 v147, v137 offset:24576
	v_cndmask_b32_e64 v146, v188, v215, s[4:5]
	v_add_f32_e32 v145, v146, v145
	ds_read_u16 v146, v137 offset:8192
	s_waitcnt lgkmcnt(1)
	v_lshlrev_b32_e32 v156, 16, v147
	v_mul_f32_e32 v147, 0x3fb8aa3b, v145
	v_exp_f32_e32 v147, v147
	s_waitcnt lgkmcnt(0)
	v_lshlrev_b32_e32 v146, 16, v146
	v_mul_f32_e32 v146, 0x3db504f3, v146
	v_mul_f32_e32 v146, v147, v146
	v_cvt_pk_bf16_f32 v157, v146, v146
	v_or_b32_e32 v146, v142, v108
	v_mov_b32_e32 v147, v143
	v_lshlrev_b64 v[146:147], 8, v[146:147]
	v_or_b32_e32 v146, v146, v144
	v_lshl_add_u64 v[154:155], s[36:37], 0, v[146:147]
	global_store_short_d16_hi v[154:155], v157, off
	v_mul_f32_e32 v154, 0xbfb8aa3b, v145
	v_exp_f32_e32 v154, v154
	v_lshl_add_u64 v[146:147], s[38:39], 0, v[146:147]
	v_mul_f32_e32 v154, v154, v156
	v_cvt_pk_bf16_f32 v154, v154, v154
	global_store_short_d16_hi v[146:147], v154, off
	v_sub_f32_e32 v146, v141, v145
	v_mul_f32_e32 v146, 0x3fb8aa3b, v146
	v_exp_f32_e32 v146, v146
	s_nop 0
	v_mul_f32_e32 v146, v146, v156
	v_cvt_pk_bf16_f32 v154, v146, v146
	v_lshrrev_b32_e32 v220, 16, v154
	ds_read_u16 v147, v139 offset:24576
	v_cndmask_b32_e64 v146, v187, v237, s[4:5]
	v_add_f32_e32 v145, v146, v145
	ds_read_u16 v146, v139 offset:8192
	s_waitcnt lgkmcnt(1)
	v_lshlrev_b32_e32 v156, 16, v147
	v_mul_f32_e32 v147, 0x3fb8aa3b, v145
	v_exp_f32_e32 v147, v147
	s_waitcnt lgkmcnt(0)
	v_lshlrev_b32_e32 v146, 16, v146
	v_mul_f32_e32 v146, 0x3db504f3, v146
	v_mul_f32_e32 v146, v147, v146
	v_cvt_pk_bf16_f32 v157, v146, v146
	v_or_b32_e32 v146, v142, v110
	v_mov_b32_e32 v147, v143
	v_lshlrev_b64 v[146:147], 8, v[146:147]
	v_or_b32_e32 v146, v146, v144
	v_lshl_add_u64 v[154:155], s[36:37], 0, v[146:147]
	global_store_short_d16_hi v[154:155], v157, off
	v_mul_f32_e32 v154, 0xbfb8aa3b, v145
	v_exp_f32_e32 v154, v154
	v_lshl_add_u64 v[146:147], s[38:39], 0, v[146:147]
	v_mul_f32_e32 v154, v154, v156
	v_cvt_pk_bf16_f32 v154, v154, v154
	global_store_short_d16_hi v[146:147], v154, off
	v_sub_f32_e32 v146, v141, v145
	v_mul_f32_e32 v146, 0x3fb8aa3b, v146
	v_exp_f32_e32 v146, v146
	s_nop 0
	v_mul_f32_e32 v146, v146, v156
	v_cvt_pk_bf16_f32 v154, v146, v146
	v_and_or_b32 v220, v154, s98, v220
	ds_read_u16 v147, v148 offset:24576
	v_cndmask_b32_e64 v146, v186, v242, s[4:5]
	v_add_f32_e32 v145, v146, v145
	ds_read_u16 v146, v148 offset:8192
	s_waitcnt lgkmcnt(1)
	v_lshlrev_b32_e32 v156, 16, v147
	v_mul_f32_e32 v147, 0x3fb8aa3b, v145
	v_exp_f32_e32 v147, v147
	s_waitcnt lgkmcnt(0)
	v_lshlrev_b32_e32 v146, 16, v146
	v_mul_f32_e32 v146, 0x3db504f3, v146
	v_mul_f32_e32 v146, v147, v146
	v_cvt_pk_bf16_f32 v157, v146, v146
	v_or_b32_e32 v146, v142, v112
	v_mov_b32_e32 v147, v143
	v_lshlrev_b64 v[146:147], 8, v[146:147]
	v_or_b32_e32 v146, v146, v144
	v_lshl_add_u64 v[154:155], s[36:37], 0, v[146:147]
	global_store_short_d16_hi v[154:155], v157, off
	v_mul_f32_e32 v154, 0xbfb8aa3b, v145
	v_exp_f32_e32 v154, v154
	v_lshl_add_u64 v[146:147], s[38:39], 0, v[146:147]
	v_mul_f32_e32 v154, v154, v156
	v_cvt_pk_bf16_f32 v154, v154, v154
	global_store_short_d16_hi v[146:147], v154, off
	v_sub_f32_e32 v146, v141, v145
	v_mul_f32_e32 v146, 0x3fb8aa3b, v146
	v_exp_f32_e32 v146, v146
	s_nop 0
	v_mul_f32_e32 v146, v146, v156
	v_cvt_pk_bf16_f32 v154, v146, v146
	v_lshrrev_b32_e32 v221, 16, v154
	ds_read_u16 v147, v149 offset:24576
	v_cndmask_b32_e64 v146, v185, v244, s[4:5]
	v_add_f32_e32 v145, v146, v145
	ds_read_u16 v146, v149 offset:8192
	s_waitcnt lgkmcnt(1)
	v_lshlrev_b32_e32 v156, 16, v147
	v_mul_f32_e32 v147, 0x3fb8aa3b, v145
	v_exp_f32_e32 v147, v147
	s_waitcnt lgkmcnt(0)
	v_lshlrev_b32_e32 v146, 16, v146
	v_mul_f32_e32 v146, 0x3db504f3, v146
	v_mul_f32_e32 v146, v147, v146
	v_cvt_pk_bf16_f32 v157, v146, v146
	v_or_b32_e32 v146, v142, v114
	v_mov_b32_e32 v147, v143
	v_lshlrev_b64 v[146:147], 8, v[146:147]
	v_or_b32_e32 v146, v146, v144
	v_lshl_add_u64 v[154:155], s[36:37], 0, v[146:147]
	global_store_short_d16_hi v[154:155], v157, off
	v_mul_f32_e32 v154, 0xbfb8aa3b, v145
	v_exp_f32_e32 v154, v154
	v_lshl_add_u64 v[146:147], s[38:39], 0, v[146:147]
	v_mul_f32_e32 v154, v154, v156
	v_cvt_pk_bf16_f32 v154, v154, v154
	global_store_short_d16_hi v[146:147], v154, off
	v_sub_f32_e32 v146, v141, v145
	v_mul_f32_e32 v146, 0x3fb8aa3b, v146
	v_exp_f32_e32 v146, v146
	s_nop 0
	v_mul_f32_e32 v146, v146, v156
	v_cvt_pk_bf16_f32 v154, v146, v146
	v_and_or_b32 v221, v154, s98, v221
	ds_read_u16 v147, v150 offset:24576
	v_cndmask_b32_e64 v146, v184, v235, s[4:5]
	v_add_f32_e32 v145, v146, v145
	ds_read_u16 v146, v150 offset:8192
	s_waitcnt lgkmcnt(1)
	v_lshlrev_b32_e32 v156, 16, v147
	v_mul_f32_e32 v147, 0x3fb8aa3b, v145
	v_exp_f32_e32 v147, v147
	s_waitcnt lgkmcnt(0)
	v_lshlrev_b32_e32 v146, 16, v146
	v_mul_f32_e32 v146, 0x3db504f3, v146
	v_mul_f32_e32 v146, v147, v146
	v_cvt_pk_bf16_f32 v157, v146, v146
	v_or_b32_e32 v146, v142, v116
	v_mov_b32_e32 v147, v143
	v_lshlrev_b64 v[146:147], 8, v[146:147]
	v_or_b32_e32 v146, v146, v144
	v_lshl_add_u64 v[154:155], s[36:37], 0, v[146:147]
	global_store_short_d16_hi v[154:155], v157, off
	v_mul_f32_e32 v154, 0xbfb8aa3b, v145
	v_exp_f32_e32 v154, v154
	v_lshl_add_u64 v[146:147], s[38:39], 0, v[146:147]
	v_mul_f32_e32 v154, v154, v156
	v_cvt_pk_bf16_f32 v154, v154, v154
	global_store_short_d16_hi v[146:147], v154, off
	v_sub_f32_e32 v146, v141, v145
	v_mul_f32_e32 v146, 0x3fb8aa3b, v146
	v_exp_f32_e32 v146, v146
	s_nop 0
	v_mul_f32_e32 v146, v146, v156
	v_cvt_pk_bf16_f32 v154, v146, v146
	v_lshrrev_b32_e32 v222, 16, v154
	ds_read_u16 v147, v151 offset:24576
	v_cndmask_b32_e64 v146, v183, v241, s[4:5]
	v_add_f32_e32 v145, v146, v145
	ds_read_u16 v146, v151 offset:8192
	s_waitcnt lgkmcnt(1)
	v_lshlrev_b32_e32 v156, 16, v147
	v_mul_f32_e32 v147, 0x3fb8aa3b, v145
	v_exp_f32_e32 v147, v147
	s_waitcnt lgkmcnt(0)
	v_lshlrev_b32_e32 v146, 16, v146
	v_mul_f32_e32 v146, 0x3db504f3, v146
	v_mul_f32_e32 v146, v147, v146
	v_cvt_pk_bf16_f32 v157, v146, v146
	v_or_b32_e32 v146, v142, v118
	v_mov_b32_e32 v147, v143
	v_lshlrev_b64 v[146:147], 8, v[146:147]
	v_or_b32_e32 v146, v146, v144
	v_lshl_add_u64 v[154:155], s[36:37], 0, v[146:147]
	global_store_short_d16_hi v[154:155], v157, off
	v_mul_f32_e32 v154, 0xbfb8aa3b, v145
	v_exp_f32_e32 v154, v154
	v_lshl_add_u64 v[146:147], s[38:39], 0, v[146:147]
	v_mul_f32_e32 v154, v154, v156
	v_cvt_pk_bf16_f32 v154, v154, v154
	global_store_short_d16_hi v[146:147], v154, off
	v_sub_f32_e32 v146, v141, v145
	v_mul_f32_e32 v146, 0x3fb8aa3b, v146
	v_exp_f32_e32 v146, v146
	s_nop 0
	v_mul_f32_e32 v146, v146, v156
	v_cvt_pk_bf16_f32 v154, v146, v146
	v_and_or_b32 v222, v154, s98, v222
	ds_read_u16 v147, v152 offset:24576
	v_cndmask_b32_e64 v146, v182, v246, s[4:5]
	v_add_f32_e32 v145, v146, v145
	ds_read_u16 v146, v152 offset:8192
	s_waitcnt lgkmcnt(1)
	v_lshlrev_b32_e32 v156, 16, v147
	v_mul_f32_e32 v147, 0x3fb8aa3b, v145
	v_exp_f32_e32 v147, v147
	s_waitcnt lgkmcnt(0)
	v_lshlrev_b32_e32 v146, 16, v146
	v_mul_f32_e32 v146, 0x3db504f3, v146
	v_mul_f32_e32 v146, v147, v146
	v_cvt_pk_bf16_f32 v157, v146, v146
	v_or_b32_e32 v146, v142, v120
	v_mov_b32_e32 v147, v143
	v_lshlrev_b64 v[146:147], 8, v[146:147]
	v_or_b32_e32 v146, v146, v144
	v_lshl_add_u64 v[154:155], s[36:37], 0, v[146:147]
	global_store_short_d16_hi v[154:155], v157, off
	v_mul_f32_e32 v154, 0xbfb8aa3b, v145
	v_exp_f32_e32 v154, v154
	v_lshl_add_u64 v[146:147], s[38:39], 0, v[146:147]
	v_mul_f32_e32 v154, v154, v156
	v_cvt_pk_bf16_f32 v154, v154, v154
	global_store_short_d16_hi v[146:147], v154, off
	v_sub_f32_e32 v146, v141, v145
	v_mul_f32_e32 v146, 0x3fb8aa3b, v146
	v_exp_f32_e32 v146, v146
	s_nop 0
	v_mul_f32_e32 v146, v146, v156
	v_cvt_pk_bf16_f32 v154, v146, v146
	v_lshrrev_b32_e32 v223, 16, v154
	ds_read_u16 v147, v153 offset:24576
	v_cndmask_b32_e64 v146, v181, v247, s[4:5]
	v_add_f32_e32 v145, v146, v145
	ds_read_u16 v146, v153 offset:8192
	s_waitcnt lgkmcnt(1)
	v_lshlrev_b32_e32 v156, 16, v147
	v_mul_f32_e32 v147, 0x3fb8aa3b, v145
	v_exp_f32_e32 v147, v147
	s_waitcnt lgkmcnt(0)
	v_lshlrev_b32_e32 v146, 16, v146
	v_mul_f32_e32 v146, 0x3db504f3, v146
	v_mul_f32_e32 v146, v147, v146
	v_cvt_pk_bf16_f32 v157, v146, v146
	v_or_b32_e32 v146, v142, v122
	v_mov_b32_e32 v147, v143
	v_lshlrev_b64 v[146:147], 8, v[146:147]
	v_or_b32_e32 v146, v146, v144
	v_lshl_add_u64 v[154:155], s[36:37], 0, v[146:147]
	global_store_short_d16_hi v[154:155], v157, off
	v_mul_f32_e32 v154, 0xbfb8aa3b, v145
	v_exp_f32_e32 v154, v154
	v_lshl_add_u64 v[146:147], s[38:39], 0, v[146:147]
	v_mul_f32_e32 v154, v154, v156
	v_cvt_pk_bf16_f32 v154, v154, v154
	global_store_short_d16_hi v[146:147], v154, off
	v_sub_f32_e32 v146, v141, v145
	v_mul_f32_e32 v146, 0x3fb8aa3b, v146
	v_exp_f32_e32 v146, v146
	s_nop 0
	v_mul_f32_e32 v146, v146, v156
	v_cvt_pk_bf16_f32 v154, v146, v146
	v_lshlrev_b32_e32 v146, 1, v122
	v_mov_b32_e32 v147, v3
	v_lshl_add_u64 v[146:147], v[6:7], 0, v[146:147]
	v_and_or_b32 v223, v154, s98, v223
	v_alignbit_b32 v226, v223, v223, 16
	v_alignbit_b32 v218, v220, v220, 16
	v_cndmask_b32_e64 v220, v226, v220, s[4:5]
	v_cndmask_b32_e64 v223, v218, v223, s[4:5]
	v_alignbit_b32 v226, v222, v222, 16
	v_alignbit_b32 v218, v221, v221, 16
	v_cndmask_b32_e64 v221, v226, v221, s[4:5]
	v_cndmask_b32_e64 v222, v218, v222, s[4:5]
	v_lshl_add_u64 v[218:219], v[146:147], 0, v[224:225]
	global_store_dwordx4 v[218:219], v[220:223], off
	s_nop 1
	ds_read_u16 v147, v162 offset:24576
	v_cndmask_b32_e64 v146, v180, v239, s[4:5]
	v_add_f32_e32 v145, v146, v145
	ds_read_u16 v146, v162 offset:8192
	s_waitcnt lgkmcnt(1)
	v_lshlrev_b32_e32 v156, 16, v147
	v_mul_f32_e32 v147, 0x3fb8aa3b, v145
	v_exp_f32_e32 v147, v147
	s_waitcnt lgkmcnt(0)
	v_lshlrev_b32_e32 v146, 16, v146
	v_mul_f32_e32 v146, 0x3db504f3, v146
	v_mul_f32_e32 v146, v147, v146
	v_cvt_pk_bf16_f32 v157, v146, v146
	v_or_b32_e32 v146, v142, v124
	v_mov_b32_e32 v147, v143
	v_lshlrev_b64 v[146:147], 8, v[146:147]
	v_or_b32_e32 v146, v146, v144
	v_lshl_add_u64 v[154:155], s[36:37], 0, v[146:147]
	global_store_short_d16_hi v[154:155], v157, off
	v_mul_f32_e32 v154, 0xbfb8aa3b, v145
	v_exp_f32_e32 v154, v154
	v_lshl_add_u64 v[146:147], s[38:39], 0, v[146:147]
	v_mul_f32_e32 v154, v154, v156
	v_cvt_pk_bf16_f32 v154, v154, v154
	global_store_short_d16_hi v[146:147], v154, off
	v_sub_f32_e32 v146, v141, v145
	v_mul_f32_e32 v146, 0x3fb8aa3b, v146
	v_exp_f32_e32 v146, v146
	s_nop 0
	v_mul_f32_e32 v146, v146, v156
	v_cvt_pk_bf16_f32 v154, v146, v146
	v_lshrrev_b32_e32 v220, 16, v154
	ds_read_u16 v147, v163 offset:24576
	v_cndmask_b32_e64 v146, v179, v245, s[4:5]
	v_add_f32_e32 v145, v146, v145
	ds_read_u16 v146, v163 offset:8192
	s_waitcnt lgkmcnt(1)
	v_lshlrev_b32_e32 v156, 16, v147
	v_mul_f32_e32 v147, 0x3fb8aa3b, v145
	v_exp_f32_e32 v147, v147
	s_waitcnt lgkmcnt(0)
	v_lshlrev_b32_e32 v146, 16, v146
	v_mul_f32_e32 v146, 0x3db504f3, v146
	v_mul_f32_e32 v146, v147, v146
	v_cvt_pk_bf16_f32 v157, v146, v146
	v_or_b32_e32 v146, v142, v126
	v_mov_b32_e32 v147, v143
	v_lshlrev_b64 v[146:147], 8, v[146:147]
	v_or_b32_e32 v146, v146, v144
	v_lshl_add_u64 v[154:155], s[36:37], 0, v[146:147]
	global_store_short_d16_hi v[154:155], v157, off
	v_mul_f32_e32 v154, 0xbfb8aa3b, v145
	v_exp_f32_e32 v154, v154
	v_lshl_add_u64 v[146:147], s[38:39], 0, v[146:147]
	v_mul_f32_e32 v154, v154, v156
	v_cvt_pk_bf16_f32 v154, v154, v154
	global_store_short_d16_hi v[146:147], v154, off
	v_sub_f32_e32 v146, v141, v145
	v_mul_f32_e32 v146, 0x3fb8aa3b, v146
	v_exp_f32_e32 v146, v146
	s_nop 0
	v_mul_f32_e32 v146, v146, v156
	v_cvt_pk_bf16_f32 v154, v146, v146
	v_and_or_b32 v220, v154, s98, v220
	ds_read_u16 v147, v164 offset:24576
	v_cndmask_b32_e64 v146, v178, v249, s[4:5]
	v_add_f32_e32 v145, v146, v145
	ds_read_u16 v146, v164 offset:8192
	s_waitcnt lgkmcnt(1)
	v_lshlrev_b32_e32 v156, 16, v147
	v_mul_f32_e32 v147, 0x3fb8aa3b, v145
	v_exp_f32_e32 v147, v147
	s_waitcnt lgkmcnt(0)
	v_lshlrev_b32_e32 v146, 16, v146
	v_mul_f32_e32 v146, 0x3db504f3, v146
	v_mul_f32_e32 v146, v147, v146
	v_cvt_pk_bf16_f32 v157, v146, v146
	v_or_b32_e32 v146, v142, v128
	v_mov_b32_e32 v147, v143
	v_lshlrev_b64 v[146:147], 8, v[146:147]
	v_or_b32_e32 v146, v146, v144
	v_lshl_add_u64 v[154:155], s[36:37], 0, v[146:147]
	global_store_short_d16_hi v[154:155], v157, off
	v_mul_f32_e32 v154, 0xbfb8aa3b, v145
	v_exp_f32_e32 v154, v154
	v_lshl_add_u64 v[146:147], s[38:39], 0, v[146:147]
	v_mul_f32_e32 v154, v154, v156
	v_cvt_pk_bf16_f32 v154, v154, v154
	global_store_short_d16_hi v[146:147], v154, off
	v_sub_f32_e32 v146, v141, v145
	v_mul_f32_e32 v146, 0x3fb8aa3b, v146
	v_exp_f32_e32 v146, v146
	s_nop 0
	v_mul_f32_e32 v146, v146, v156
	v_cvt_pk_bf16_f32 v154, v146, v146
	v_lshrrev_b32_e32 v221, 16, v154
	ds_read_u16 v147, v165 offset:24576
	v_cndmask_b32_e64 v146, v177, v250, s[4:5]
	v_add_f32_e32 v145, v146, v145
	ds_read_u16 v146, v165 offset:8192
	s_waitcnt lgkmcnt(1)
	v_lshlrev_b32_e32 v156, 16, v147
	v_mul_f32_e32 v147, 0x3fb8aa3b, v145
	v_exp_f32_e32 v147, v147
	s_waitcnt lgkmcnt(0)
	v_lshlrev_b32_e32 v146, 16, v146
	v_mul_f32_e32 v146, 0x3db504f3, v146
	v_mul_f32_e32 v146, v147, v146
	v_cvt_pk_bf16_f32 v157, v146, v146
	v_or_b32_e32 v146, v142, v130
	v_mov_b32_e32 v147, v143
	v_lshlrev_b64 v[146:147], 8, v[146:147]
	v_or_b32_e32 v146, v146, v144
	v_lshl_add_u64 v[154:155], s[36:37], 0, v[146:147]
	global_store_short_d16_hi v[154:155], v157, off
	v_mul_f32_e32 v154, 0xbfb8aa3b, v145
	v_exp_f32_e32 v154, v154
	v_lshl_add_u64 v[146:147], s[38:39], 0, v[146:147]
	v_mul_f32_e32 v154, v154, v156
	v_cvt_pk_bf16_f32 v154, v154, v154
	global_store_short_d16_hi v[146:147], v154, off
	v_sub_f32_e32 v146, v141, v145
	v_mul_f32_e32 v146, 0x3fb8aa3b, v146
	v_exp_f32_e32 v146, v146
	s_nop 0
	v_mul_f32_e32 v146, v146, v156
	v_cvt_pk_bf16_f32 v154, v146, v146
	v_and_or_b32 v221, v154, s98, v221
	ds_read_u16 v147, v166 offset:24576
	v_cndmask_b32_e64 v146, v176, v243, s[4:5]
	v_add_f32_e32 v145, v146, v145
	ds_read_u16 v146, v166 offset:8192
	s_waitcnt lgkmcnt(1)
	v_lshlrev_b32_e32 v156, 16, v147
	v_mul_f32_e32 v147, 0x3fb8aa3b, v145
	v_exp_f32_e32 v147, v147
	s_waitcnt lgkmcnt(0)
	v_lshlrev_b32_e32 v146, 16, v146
	v_mul_f32_e32 v146, 0x3db504f3, v146
	v_mul_f32_e32 v146, v147, v146
	v_cvt_pk_bf16_f32 v157, v146, v146
	v_or_b32_e32 v146, v142, v132
	v_mov_b32_e32 v147, v143
	v_lshlrev_b64 v[146:147], 8, v[146:147]
	v_or_b32_e32 v146, v146, v144
	v_lshl_add_u64 v[154:155], s[36:37], 0, v[146:147]
	global_store_short_d16_hi v[154:155], v157, off
	v_mul_f32_e32 v154, 0xbfb8aa3b, v145
	v_exp_f32_e32 v154, v154
	v_lshl_add_u64 v[146:147], s[38:39], 0, v[146:147]
	v_mul_f32_e32 v154, v154, v156
	v_cvt_pk_bf16_f32 v154, v154, v154
	global_store_short_d16_hi v[146:147], v154, off
	v_sub_f32_e32 v146, v141, v145
	v_mul_f32_e32 v146, 0x3fb8aa3b, v146
	v_exp_f32_e32 v146, v146
	s_nop 0
	v_mul_f32_e32 v146, v146, v156
	v_cvt_pk_bf16_f32 v154, v146, v146
	v_lshrrev_b32_e32 v222, 16, v154
	ds_read_u16 v147, v167 offset:24576
	v_cndmask_b32_e64 v146, v175, v248, s[4:5]
	v_add_f32_e32 v145, v146, v145
	ds_read_u16 v146, v167 offset:8192
	s_waitcnt lgkmcnt(1)
	v_lshlrev_b32_e32 v156, 16, v147
	v_mul_f32_e32 v147, 0x3fb8aa3b, v145
	v_exp_f32_e32 v147, v147
	s_waitcnt lgkmcnt(0)
	v_lshlrev_b32_e32 v146, 16, v146
	v_mul_f32_e32 v146, 0x3db504f3, v146
	v_mul_f32_e32 v146, v147, v146
	v_cvt_pk_bf16_f32 v157, v146, v146
	v_or_b32_e32 v146, v142, v134
	v_mov_b32_e32 v147, v143
	v_lshlrev_b64 v[146:147], 8, v[146:147]
	v_or_b32_e32 v146, v146, v144
	v_lshl_add_u64 v[154:155], s[36:37], 0, v[146:147]
	global_store_short_d16_hi v[154:155], v157, off
	v_mul_f32_e32 v154, 0xbfb8aa3b, v145
	v_exp_f32_e32 v154, v154
	v_lshl_add_u64 v[146:147], s[38:39], 0, v[146:147]
	v_mul_f32_e32 v154, v154, v156
	v_cvt_pk_bf16_f32 v154, v154, v154
	global_store_short_d16_hi v[146:147], v154, off
	v_sub_f32_e32 v146, v141, v145
	v_mul_f32_e32 v146, 0x3fb8aa3b, v146
	v_exp_f32_e32 v146, v146
	s_nop 0
	v_mul_f32_e32 v146, v146, v156
	v_cvt_pk_bf16_f32 v154, v146, v146
	v_and_or_b32 v222, v154, s98, v222
	ds_read_u16 v147, v168 offset:24576
	v_cndmask_b32_e64 v146, v174, v251, s[4:5]
	v_add_f32_e32 v145, v146, v145
	ds_read_u16 v146, v168 offset:8192
	s_waitcnt lgkmcnt(1)
	v_lshlrev_b32_e32 v156, 16, v147
	v_mul_f32_e32 v147, 0x3fb8aa3b, v145
	v_exp_f32_e32 v147, v147
	s_waitcnt lgkmcnt(0)
	v_lshlrev_b32_e32 v146, 16, v146
	v_mul_f32_e32 v146, 0x3db504f3, v146
	v_mul_f32_e32 v146, v147, v146
	v_cvt_pk_bf16_f32 v157, v146, v146
	v_or_b32_e32 v146, v142, v136
	v_mov_b32_e32 v147, v143
	v_lshlrev_b64 v[146:147], 8, v[146:147]
	v_or_b32_e32 v146, v146, v144
	v_lshl_add_u64 v[154:155], s[36:37], 0, v[146:147]
	global_store_short_d16_hi v[154:155], v157, off
	v_mul_f32_e32 v154, 0xbfb8aa3b, v145
	v_exp_f32_e32 v154, v154
	v_lshl_add_u64 v[146:147], s[38:39], 0, v[146:147]
	v_or_b32_e32 v142, v142, v138
	v_lshlrev_b64 v[142:143], 8, v[142:143]
	v_mul_f32_e32 v154, v154, v156
	v_bfe_u32 v155, v154, 16, 1
	v_add3_u32 v154, v154, v155, s73
	global_store_short_d16_hi v[146:147], v154, off
	v_sub_f32_e32 v146, v141, v145
	v_mul_f32_e32 v146, 0x3fb8aa3b, v146
	v_exp_f32_e32 v146, v146
	v_or_b32_e32 v142, v142, v144
	v_mul_f32_e32 v146, v146, v156
	v_cvt_pk_bf16_f32 v154, v146, v146
	v_lshrrev_b32_e32 v223, 16, v154
	v_cndmask_b32_e64 v146, v173, v252, s[4:5]
	v_add_f32_e32 v146, v146, v145
	ds_read_u16 v145, v169 offset:8192
	v_mul_f32_e32 v154, 0x3fb8aa3b, v146
	v_exp_f32_e32 v154, v154
	ds_read_u16 v147, v169 offset:24576
	s_waitcnt lgkmcnt(1)
	v_lshlrev_b32_e32 v145, 16, v145
	v_mul_f32_e32 v145, 0x3db504f3, v145
	v_mul_f32_e32 v145, v154, v145
	v_cvt_pk_bf16_f32 v154, v145, v145
	v_lshl_add_u64 v[144:145], s[36:37], 0, v[142:143]
	global_store_short_d16_hi v[144:145], v154, off
	v_mul_f32_e32 v144, 0xbfb8aa3b, v146
	v_exp_f32_e32 v144, v144
	s_waitcnt lgkmcnt(0)
	v_lshlrev_b32_e32 v147, 16, v147
	v_lshl_add_u64 v[142:143], s[38:39], 0, v[142:143]
	v_mul_f32_e32 v144, v144, v147
	v_bfe_u32 v145, v144, 16, 1
	v_add3_u32 v144, v144, v145, s73
	global_store_short_d16_hi v[142:143], v144, off
	v_sub_f32_e32 v142, v141, v146
	v_mul_f32_e32 v142, 0x3fb8aa3b, v142
	v_exp_f32_e32 v142, v142
	s_nop 0
	v_mul_f32_e32 v142, v142, v147
	v_cvt_pk_bf16_f32 v144, v142, v142
	v_lshlrev_b32_e32 v142, 1, v138
	v_mov_b32_e32 v143, v3
	v_lshl_add_u64 v[6:7], v[6:7], 0, v[142:143]
	v_and_or_b32 v223, v144, s98, v223
	v_alignbit_b32 v226, v223, v223, 16
	v_alignbit_b32 v218, v220, v220, 16
	v_cndmask_b32_e64 v220, v226, v220, s[4:5]
	v_cndmask_b32_e64 v223, v218, v223, s[4:5]
	v_alignbit_b32 v226, v222, v222, 16
	v_alignbit_b32 v218, v221, v221, 16
	v_cndmask_b32_e64 v221, v226, v221, s[4:5]
	v_cndmask_b32_e64 v222, v218, v222, s[4:5]
	v_lshl_add_u64 v[218:219], v[6:7], 0, v[224:225]
	global_store_dwordx4 v[218:219], v[220:223], off
	s_nop 1
	v_and_b32_e32 v227, 0xff, v0
	v_lshrrev_b32_e32 v228, 8, v0
	v_lshlrev_b32_e32 v227, 2, v227
	v_lshl_add_u32 v227, v228, 16, v227
	ds_read_b32 v218, v227 offset:40960
	ds_read_b32 v219, v227 offset:41984
	ds_read_b32 v220, v227 offset:43008
	ds_read_b32 v221, v227 offset:44032
	ds_read_b32 v222, v227 offset:45056
	ds_read_b32 v223, v227 offset:46080
	ds_read_b32 v224, v227 offset:47104
	ds_read_b32 v225, v227 offset:48128
	ds_read_b32 v226, v227 offset:49152
	s_waitcnt lgkmcnt(0)
	v_mul_f32_e32 v6, 0x3fb8aa3b, v141
	v_exp_f32_e32 v6, v6
	global_store_dword v[4:5], v6, off
	s_andn2_b64 exec, exec, s[12:13]
	s_cbranch_execnz .LBB0_759
